# counted lgkmcnt ladder in all six GEMM K-loops: each MFMA waits only for the ds_reads it consumes (was lgkmcnt(0) before each 16-MFMA block)
# speedup vs baseline: 1.0181x; 1.0117x over previous
.LBB0_134:
	s_add_u32 s28, s66, 0xfffc0080
	s_addc_u32 s29, s67, -1
	s_add_i32 s88, 0, 0x10000
	v_add_u32_e32 v152, s88, v191
	ds_read_b128 v[128:131], v152
	ds_read_b128 v[132:135], v152 offset:1024
	ds_read_b128 v[148:151], v152 offset:2048
	ds_read_b128 v[152:155], v152 offset:3072
	s_cmp_eq_u32 vcc_lo, 12
	s_cselect_b32 s71, s5, s29
	s_cselect_b32 s70, s7, s28
	s_cselect_b32 s69, s17, s91
	s_cselect_b32 s68, s19, s85
	v_lshl_add_u64 v[172:173], s[66:67], 0, v[144:145]
	s_add_i32 m0, s73, 0xc000
	ds_read_b128 v[156:159], v192
	ds_read_b128 v[160:163], v192 offset:1024
	ds_read_b128 v[164:167], v192 offset:2048
	ds_read_b128 v[168:171], v192 offset:3072
	ds_read_b128 v[194:197], v192 offset:4096
	ds_read_b128 v[198:201], v192 offset:5120
	ds_read_b128 v[202:205], v192 offset:6144
	ds_read_b128 v[206:209], v192 offset:7168
	global_load_lds_dwordx4 v[172:173], off
	v_lshl_add_u64 v[172:173], s[66:67], 0, v[146:147]
	s_add_i32 m0, s73, 0xe000
	s_nop 0
	global_load_lds_dwordx4 v[172:173], off
	s_waitcnt lgkmcnt(8)
	s_barrier
	s_setprio 1
	s_waitcnt lgkmcnt(7)
	v_mfma_f32_16x16x32_bf16 v[124:127], v[128:131], v[156:159], v[124:127]
	v_mfma_f32_16x16x32_bf16 v[120:123], v[148:151], v[156:159], v[120:123]
	s_waitcnt lgkmcnt(5)
	v_mfma_f32_16x16x32_bf16 v[108:111], v[128:131], v[164:167], v[108:111]
	v_mfma_f32_16x16x32_bf16 v[104:107], v[148:151], v[164:167], v[104:107]
	s_waitcnt lgkmcnt(3)
	v_mfma_f32_16x16x32_bf16 v[92:95], v[128:131], v[194:197], v[92:95]
	v_mfma_f32_16x16x32_bf16 v[88:91], v[148:151], v[194:197], v[88:91]
	s_waitcnt lgkmcnt(1)
	v_mfma_f32_16x16x32_bf16 v[76:79], v[128:131], v[202:205], v[76:79]
	v_mfma_f32_16x16x32_bf16 v[72:75], v[148:151], v[202:205], v[72:75]
	v_mfma_f32_16x16x32_bf16 v[124:127], v[132:135], v[160:163], v[124:127]
	v_mfma_f32_16x16x32_bf16 v[120:123], v[152:155], v[160:163], v[120:123]
	v_mfma_f32_16x16x32_bf16 v[108:111], v[132:135], v[168:171], v[108:111]
	v_mfma_f32_16x16x32_bf16 v[104:107], v[152:155], v[168:171], v[104:107]
	v_mfma_f32_16x16x32_bf16 v[92:95], v[132:135], v[198:201], v[92:95]
	v_mfma_f32_16x16x32_bf16 v[88:91], v[152:155], v[198:201], v[88:91]
	s_waitcnt lgkmcnt(0)
	v_mfma_f32_16x16x32_bf16 v[76:79], v[132:135], v[206:209], v[76:79]
	v_mfma_f32_16x16x32_bf16 v[72:75], v[152:155], v[206:209], v[72:75]
	s_setprio 0
	s_barrier
	s_add_i32 s89, 0, 0x14000
	v_add_u32_e32 v172, s89, v191
	s_add_i32 s28, s88, s72
	ds_read_b128 v[210:213], v172
	ds_read_b128 v[214:217], v172 offset:1024
	ds_read_b128 v[232:235], v172 offset:2048
	ds_read_b128 v[236:239], v172 offset:3072
	v_lshl_add_u64 v[172:173], s[68:69], 0, v[138:139]
	s_mov_b32 m0, s28
	v_lshl_add_u64 v[188:189], s[68:69], 0, v[142:143]
	global_load_lds_dwordx4 v[172:173], off
	s_add_i32 m0, s28, 0x2000
	s_nop 0
	global_load_lds_dwordx4 v[188:189], off
	s_barrier
	s_setprio 1
	s_waitcnt lgkmcnt(3)
	v_mfma_f32_16x16x32_bf16 v[116:119], v[210:213], v[156:159], v[116:119]
	s_waitcnt lgkmcnt(1)
	v_mfma_f32_16x16x32_bf16 v[112:115], v[232:235], v[156:159], v[112:115]
	v_mfma_f32_16x16x32_bf16 v[100:103], v[210:213], v[164:167], v[100:103]
	v_mfma_f32_16x16x32_bf16 v[96:99], v[232:235], v[164:167], v[96:99]
	v_mfma_f32_16x16x32_bf16 v[84:87], v[210:213], v[194:197], v[84:87]
	v_mfma_f32_16x16x32_bf16 v[80:83], v[232:235], v[194:197], v[80:83]
	v_mfma_f32_16x16x32_bf16 v[68:71], v[210:213], v[202:205], v[68:71]
	v_mfma_f32_16x16x32_bf16 v[64:67], v[232:235], v[202:205], v[64:67]
	v_mfma_f32_16x16x32_bf16 v[116:119], v[214:217], v[160:163], v[116:119]
	s_waitcnt lgkmcnt(0)
	v_mfma_f32_16x16x32_bf16 v[112:115], v[236:239], v[160:163], v[112:115]
	v_mfma_f32_16x16x32_bf16 v[100:103], v[214:217], v[168:171], v[100:103]
	v_mfma_f32_16x16x32_bf16 v[96:99], v[236:239], v[168:171], v[96:99]
	v_mfma_f32_16x16x32_bf16 v[84:87], v[214:217], v[198:201], v[84:87]
	v_mfma_f32_16x16x32_bf16 v[80:83], v[236:239], v[198:201], v[80:83]
	v_mfma_f32_16x16x32_bf16 v[68:71], v[214:217], v[206:209], v[68:71]
	v_mfma_f32_16x16x32_bf16 v[64:67], v[236:239], v[206:209], v[64:67]
	s_setprio 0
	s_mov_b32 m0, s73
	v_lshl_add_u64 v[240:241], s[70:71], 0, v[136:137]
	s_barrier
	ds_read_b128 v[156:159], v192 offset:16384
	ds_read_b128 v[160:163], v192 offset:17408
	ds_read_b128 v[164:167], v192 offset:18432
	ds_read_b128 v[168:171], v192 offset:19456
	ds_read_b128 v[194:197], v192 offset:20480
	ds_read_b128 v[198:201], v192 offset:21504
	ds_read_b128 v[202:205], v192 offset:22528
	ds_read_b128 v[206:209], v192 offset:23552
	global_load_lds_dwordx4 v[240:241], off
	v_lshl_add_u64 v[242:243], s[70:71], 0, v[140:141]
	s_mov_b32 m0, s74
	s_nop 0
	global_load_lds_dwordx4 v[242:243], off
	s_barrier
	s_setprio 1
	s_waitcnt lgkmcnt(7)
	v_mfma_f32_16x16x32_bf16 v[60:63], v[128:131], v[156:159], v[60:63]
	v_mfma_f32_16x16x32_bf16 v[56:59], v[148:151], v[156:159], v[56:59]
	s_waitcnt lgkmcnt(5)
	v_mfma_f32_16x16x32_bf16 v[44:47], v[128:131], v[164:167], v[44:47]
	v_mfma_f32_16x16x32_bf16 v[40:43], v[148:151], v[164:167], v[40:43]
	s_waitcnt lgkmcnt(3)
	v_mfma_f32_16x16x32_bf16 v[28:31], v[128:131], v[194:197], v[28:31]
	v_mfma_f32_16x16x32_bf16 v[24:27], v[148:151], v[194:197], v[24:27]
	s_waitcnt lgkmcnt(1)
	v_mfma_f32_16x16x32_bf16 v[12:15], v[128:131], v[202:205], v[12:15]
	v_mfma_f32_16x16x32_bf16 v[8:11], v[148:151], v[202:205], v[8:11]
	v_mfma_f32_16x16x32_bf16 v[60:63], v[132:135], v[160:163], v[60:63]
	v_mfma_f32_16x16x32_bf16 v[56:59], v[152:155], v[160:163], v[56:59]
	v_mfma_f32_16x16x32_bf16 v[44:47], v[132:135], v[168:171], v[44:47]
	v_mfma_f32_16x16x32_bf16 v[40:43], v[152:155], v[168:171], v[40:43]
	v_mfma_f32_16x16x32_bf16 v[28:31], v[132:135], v[198:201], v[28:31]
	v_mfma_f32_16x16x32_bf16 v[24:27], v[152:155], v[198:201], v[24:27]
	s_waitcnt lgkmcnt(0)
	v_mfma_f32_16x16x32_bf16 v[12:15], v[132:135], v[206:209], v[12:15]
	v_mfma_f32_16x16x32_bf16 v[8:11], v[152:155], v[206:209], v[8:11]
	s_setprio 0
	s_barrier
	s_add_u32 s28, s68, 0x40000
	s_addc_u32 s29, s69, 0
	s_add_i32 s88, s89, s72
	v_lshl_add_u64 v[128:129], s[28:29], 0, v[138:139]
	s_mov_b32 m0, s88
	s_nop 0
	global_load_lds_dwordx4 v[128:129], off
	v_lshl_add_u64 v[128:129], s[28:29], 0, v[142:143]
	s_add_i32 m0, s88, 0x2000
	s_nop 0
	global_load_lds_dwordx4 v[128:129], off
	s_waitcnt vmcnt(6)
	s_barrier
	s_setprio 1
	v_mfma_f32_16x16x32_bf16 v[52:55], v[210:213], v[156:159], v[52:55]
	v_mfma_f32_16x16x32_bf16 v[48:51], v[232:235], v[156:159], v[48:51]
	v_mfma_f32_16x16x32_bf16 v[36:39], v[210:213], v[164:167], v[36:39]
	v_mfma_f32_16x16x32_bf16 v[32:35], v[232:235], v[164:167], v[32:35]
	v_mfma_f32_16x16x32_bf16 v[20:23], v[210:213], v[194:197], v[20:23]
	v_mfma_f32_16x16x32_bf16 v[16:19], v[232:235], v[194:197], v[16:19]
	v_mfma_f32_16x16x32_bf16 v[4:7], v[210:213], v[202:205], v[4:7]
	v_mfma_f32_16x16x32_bf16 v[0:3], v[232:235], v[202:205], v[0:3]
	v_mfma_f32_16x16x32_bf16 v[52:55], v[214:217], v[160:163], v[52:55]
	v_mfma_f32_16x16x32_bf16 v[48:51], v[236:239], v[160:163], v[48:51]
	v_mfma_f32_16x16x32_bf16 v[36:39], v[214:217], v[168:171], v[36:39]
	v_mfma_f32_16x16x32_bf16 v[32:35], v[236:239], v[168:171], v[32:35]
	v_mfma_f32_16x16x32_bf16 v[20:23], v[214:217], v[198:201], v[20:23]
	v_mfma_f32_16x16x32_bf16 v[16:19], v[236:239], v[198:201], v[16:19]
	v_mfma_f32_16x16x32_bf16 v[4:7], v[214:217], v[206:209], v[4:7]
	v_mfma_f32_16x16x32_bf16 v[0:3], v[236:239], v[206:209], v[0:3]
	s_setprio 0
	s_add_i32 s88, 0, 0x18000
	v_add_u32_e32 v152, s88, v191
	s_barrier
	ds_read_b128 v[128:131], v152
	ds_read_b128 v[132:135], v152 offset:1024
	ds_read_b128 v[148:151], v152 offset:2048
	ds_read_b128 v[152:155], v152 offset:3072
	s_add_u32 s28, s70, 0x40000
	s_addc_u32 s29, s71, 0
	s_mov_b32 m0, s75
	v_lshl_add_u64 v[210:211], s[28:29], 0, v[136:137]
	ds_read_b128 v[156:159], v192 offset:32768
	ds_read_b128 v[160:163], v192 offset:33792
	ds_read_b128 v[164:167], v192 offset:34816
	ds_read_b128 v[168:171], v192 offset:35840
	ds_read_b128 v[194:197], v192 offset:36864
	ds_read_b128 v[198:201], v192 offset:37888
	ds_read_b128 v[202:205], v192 offset:38912
	ds_read_b128 v[206:209], v192 offset:39936
	global_load_lds_dwordx4 v[210:211], off
	v_lshl_add_u64 v[210:211], s[28:29], 0, v[140:141]
	s_mov_b32 m0, s76
	s_nop 0
	global_load_lds_dwordx4 v[210:211], off
	s_waitcnt lgkmcnt(8)
	s_barrier
	s_setprio 1
	s_waitcnt lgkmcnt(7)
	v_mfma_f32_16x16x32_bf16 v[124:127], v[128:131], v[156:159], v[124:127]
	v_mfma_f32_16x16x32_bf16 v[120:123], v[148:151], v[156:159], v[120:123]
	s_waitcnt lgkmcnt(5)
	v_mfma_f32_16x16x32_bf16 v[108:111], v[128:131], v[164:167], v[108:111]
	v_mfma_f32_16x16x32_bf16 v[104:107], v[148:151], v[164:167], v[104:107]
	s_waitcnt lgkmcnt(3)
	v_mfma_f32_16x16x32_bf16 v[92:95], v[128:131], v[194:197], v[92:95]
	v_mfma_f32_16x16x32_bf16 v[88:91], v[148:151], v[194:197], v[88:91]
	s_waitcnt lgkmcnt(1)
	v_mfma_f32_16x16x32_bf16 v[76:79], v[128:131], v[202:205], v[76:79]
	v_mfma_f32_16x16x32_bf16 v[72:75], v[148:151], v[202:205], v[72:75]
	v_mfma_f32_16x16x32_bf16 v[124:127], v[132:135], v[160:163], v[124:127]
	v_mfma_f32_16x16x32_bf16 v[120:123], v[152:155], v[160:163], v[120:123]
	v_mfma_f32_16x16x32_bf16 v[108:111], v[132:135], v[168:171], v[108:111]
	v_mfma_f32_16x16x32_bf16 v[104:107], v[152:155], v[168:171], v[104:107]
	v_mfma_f32_16x16x32_bf16 v[92:95], v[132:135], v[198:201], v[92:95]
	v_mfma_f32_16x16x32_bf16 v[88:91], v[152:155], v[198:201], v[88:91]
	s_waitcnt lgkmcnt(0)
	v_mfma_f32_16x16x32_bf16 v[76:79], v[132:135], v[206:209], v[76:79]
	v_mfma_f32_16x16x32_bf16 v[72:75], v[152:155], v[206:209], v[72:75]
	s_setprio 0
	s_barrier
	s_add_i32 s70, 0, 0x1c000
	s_add_i32 s28, s88, s72
	v_add_u32_e32 v174, s70, v191
	v_lshl_add_u64 v[172:173], v[172:173], 0, s[40:41]
	s_mov_b32 m0, s28
	ds_read_b128 v[210:213], v174
	ds_read_b128 v[214:217], v174 offset:1024
	ds_read_b128 v[232:235], v174 offset:2048
	ds_read_b128 v[236:239], v174 offset:3072
	global_load_lds_dwordx4 v[172:173], off
	v_lshl_add_u64 v[172:173], v[188:189], 0, s[40:41]
	s_add_i32 m0, s28, 0x2000
	s_nop 0
	global_load_lds_dwordx4 v[172:173], off
	s_barrier
	s_setprio 1
	s_waitcnt lgkmcnt(3)
	v_mfma_f32_16x16x32_bf16 v[116:119], v[210:213], v[156:159], v[116:119]
	s_waitcnt lgkmcnt(1)
	v_mfma_f32_16x16x32_bf16 v[112:115], v[232:235], v[156:159], v[112:115]
	v_mfma_f32_16x16x32_bf16 v[100:103], v[210:213], v[164:167], v[100:103]
	v_mfma_f32_16x16x32_bf16 v[96:99], v[232:235], v[164:167], v[96:99]
	v_mfma_f32_16x16x32_bf16 v[84:87], v[210:213], v[194:197], v[84:87]
	v_mfma_f32_16x16x32_bf16 v[80:83], v[232:235], v[194:197], v[80:83]
	v_mfma_f32_16x16x32_bf16 v[68:71], v[210:213], v[202:205], v[68:71]
	v_mfma_f32_16x16x32_bf16 v[64:67], v[232:235], v[202:205], v[64:67]
	v_mfma_f32_16x16x32_bf16 v[116:119], v[214:217], v[160:163], v[116:119]
	s_waitcnt lgkmcnt(0)
	v_mfma_f32_16x16x32_bf16 v[112:115], v[236:239], v[160:163], v[112:115]
	v_mfma_f32_16x16x32_bf16 v[100:103], v[214:217], v[168:171], v[100:103]
	v_mfma_f32_16x16x32_bf16 v[96:99], v[236:239], v[168:171], v[96:99]
	v_mfma_f32_16x16x32_bf16 v[84:87], v[214:217], v[198:201], v[84:87]
	v_mfma_f32_16x16x32_bf16 v[80:83], v[236:239], v[198:201], v[80:83]
	v_mfma_f32_16x16x32_bf16 v[68:71], v[214:217], v[206:209], v[68:71]
	v_mfma_f32_16x16x32_bf16 v[64:67], v[236:239], v[206:209], v[64:67]
	s_setprio 0
	s_mov_b32 m0, s79
	v_lshl_add_u64 v[172:173], v[240:241], 0, s[40:41]
	s_barrier
	ds_read_b128 v[156:159], v192 offset:49152
	ds_read_b128 v[160:163], v192 offset:50176
	ds_read_b128 v[164:167], v192 offset:51200
	ds_read_b128 v[168:171], v192 offset:52224
	ds_read_b128 v[194:197], v192 offset:53248
	ds_read_b128 v[198:201], v192 offset:54272
	ds_read_b128 v[202:205], v192 offset:55296
	ds_read_b128 v[206:209], v192 offset:56320
	global_load_lds_dwordx4 v[172:173], off
	v_lshl_add_u64 v[172:173], v[242:243], 0, s[40:41]
	s_mov_b32 m0, s80
	s_nop 0
	global_load_lds_dwordx4 v[172:173], off
	s_barrier
	s_setprio 1
	s_waitcnt lgkmcnt(7)
	v_mfma_f32_16x16x32_bf16 v[60:63], v[128:131], v[156:159], v[60:63]
	v_mfma_f32_16x16x32_bf16 v[56:59], v[148:151], v[156:159], v[56:59]
	s_waitcnt lgkmcnt(5)
	v_mfma_f32_16x16x32_bf16 v[44:47], v[128:131], v[164:167], v[44:47]
	v_mfma_f32_16x16x32_bf16 v[40:43], v[148:151], v[164:167], v[40:43]
	s_waitcnt lgkmcnt(3)
	v_mfma_f32_16x16x32_bf16 v[28:31], v[128:131], v[194:197], v[28:31]
	v_mfma_f32_16x16x32_bf16 v[24:27], v[148:151], v[194:197], v[24:27]
	s_waitcnt lgkmcnt(1)
	v_mfma_f32_16x16x32_bf16 v[12:15], v[128:131], v[202:205], v[12:15]
	v_mfma_f32_16x16x32_bf16 v[8:11], v[148:151], v[202:205], v[8:11]
	v_mfma_f32_16x16x32_bf16 v[60:63], v[132:135], v[160:163], v[60:63]
	v_mfma_f32_16x16x32_bf16 v[56:59], v[152:155], v[160:163], v[56:59]
	v_mfma_f32_16x16x32_bf16 v[44:47], v[132:135], v[168:171], v[44:47]
	v_mfma_f32_16x16x32_bf16 v[40:43], v[152:155], v[168:171], v[40:43]
	v_mfma_f32_16x16x32_bf16 v[28:31], v[132:135], v[198:201], v[28:31]
	v_mfma_f32_16x16x32_bf16 v[24:27], v[152:155], v[198:201], v[24:27]
	s_waitcnt lgkmcnt(0)
	v_mfma_f32_16x16x32_bf16 v[12:15], v[132:135], v[206:209], v[12:15]
	v_mfma_f32_16x16x32_bf16 v[8:11], v[152:155], v[206:209], v[8:11]
	s_setprio 0
	s_barrier
	s_add_u32 s28, s68, 0x40080
	s_addc_u32 s29, s69, 0
	s_add_i32 s68, s70, s72
	v_lshl_add_u64 v[128:129], s[28:29], 0, v[138:139]
	s_mov_b32 m0, s68
	s_nop 0
	global_load_lds_dwordx4 v[128:129], off
	v_lshl_add_u64 v[128:129], s[28:29], 0, v[142:143]
	s_add_i32 m0, s68, 0x2000
	s_nop 0
	global_load_lds_dwordx4 v[128:129], off
	s_waitcnt vmcnt(6)
	s_barrier
	s_setprio 1
	v_mfma_f32_16x16x32_bf16 v[52:55], v[210:213], v[156:159], v[52:55]
	v_mfma_f32_16x16x32_bf16 v[48:51], v[232:235], v[156:159], v[48:51]
	v_mfma_f32_16x16x32_bf16 v[36:39], v[210:213], v[164:167], v[36:39]
	v_mfma_f32_16x16x32_bf16 v[32:35], v[232:235], v[164:167], v[32:35]
	v_mfma_f32_16x16x32_bf16 v[20:23], v[210:213], v[194:197], v[20:23]
	v_mfma_f32_16x16x32_bf16 v[16:19], v[232:235], v[194:197], v[16:19]
	v_mfma_f32_16x16x32_bf16 v[4:7], v[210:213], v[202:205], v[4:7]
	v_mfma_f32_16x16x32_bf16 v[0:3], v[232:235], v[202:205], v[0:3]
	v_mfma_f32_16x16x32_bf16 v[52:55], v[214:217], v[160:163], v[52:55]
	v_mfma_f32_16x16x32_bf16 v[48:51], v[236:239], v[160:163], v[48:51]
	v_mfma_f32_16x16x32_bf16 v[36:39], v[214:217], v[168:171], v[36:39]
	v_mfma_f32_16x16x32_bf16 v[32:35], v[236:239], v[168:171], v[32:35]
	v_mfma_f32_16x16x32_bf16 v[20:23], v[214:217], v[198:201], v[20:23]
	v_mfma_f32_16x16x32_bf16 v[16:19], v[236:239], v[198:201], v[16:19]
	v_mfma_f32_16x16x32_bf16 v[4:7], v[214:217], v[206:209], v[4:7]
	v_mfma_f32_16x16x32_bf16 v[0:3], v[236:239], v[206:209], v[0:3]
	s_setprio 0
	s_add_i32 vcc_lo, vcc_lo, 2
	s_add_u32 s66, s66, 0x100
	s_addc_u32 s67, s67, 0
	s_add_u32 s85, s85, 0x100
	s_addc_u32 s91, s91, 0
	s_cmp_lt_u32 vcc_lo, 14
	s_barrier
	s_cbranch_scc1 .LBB0_134
	s_lshl_b32 s4, s4, 8
	v_mov_b32_e32 v176, v175
	v_mov_b32_e32 v188, v190
	s_add_i32 s4, s4, s77
	s_cmp_gt_i32 s6, 7
	v_add_u32_e32 v148, s4, v176
	v_lshlrev_b32_e32 v128, 2, v188
	v_ashrrev_i32_e32 v129, 31, v128
	v_ashrrev_i32_e32 v149, 31, v148
	v_lshl_add_u64 v[128:129], v[128:129], 2, s[8:9]
	v_lshlrev_b64 v[130:131], 6, v[148:149]
	v_add_u32_e32 v166, 16, v148
	v_lshl_add_u64 v[130:131], v[128:129], 0, v[130:131]
	v_ashrrev_i32_e32 v167, 31, v166
	global_load_dwordx4 v[160:163], v[130:131], off
	v_lshlrev_b64 v[130:131], 6, v[166:167]
	v_lshl_add_u64 v[130:131], v[128:129], 0, v[130:131]
	global_load_dwordx4 v[168:171], v[130:131], off
	v_add_u32_e32 v164, 32, v148
	v_ashrrev_i32_e32 v165, 31, v164
	v_lshlrev_b64 v[130:131], 6, v[164:165]
	v_add_u32_e32 v158, 48, v148
	v_lshl_add_u64 v[130:131], v[128:129], 0, v[130:131]
	v_ashrrev_i32_e32 v159, 31, v158
	global_load_dwordx4 v[194:197], v[130:131], off
	v_lshlrev_b64 v[130:131], 6, v[158:159]
	v_lshl_add_u64 v[130:131], v[128:129], 0, v[130:131]
	global_load_dwordx4 v[198:201], v[130:131], off
	v_add_u32_e32 v156, 0x80, v148
	v_ashrrev_i32_e32 v157, 31, v156
	v_lshlrev_b64 v[130:131], 6, v[156:157]
	v_add_u32_e32 v154, 0x90, v148
	v_lshl_add_u64 v[130:131], v[128:129], 0, v[130:131]
	v_ashrrev_i32_e32 v155, 31, v154
	global_load_dwordx4 v[202:205], v[130:131], off
	v_lshlrev_b64 v[130:131], 6, v[154:155]
	v_add_u32_e32 v152, 0xa0, v148
	v_lshl_add_u64 v[130:131], v[128:129], 0, v[130:131]
	v_ashrrev_i32_e32 v153, 31, v152
	global_load_dwordx4 v[206:209], v[130:131], off
	v_lshlrev_b64 v[130:131], 6, v[152:153]
	v_add_u32_e32 v150, 0xb0, v148
	v_lshl_add_u64 v[130:131], v[128:129], 0, v[130:131]
	v_ashrrev_i32_e32 v151, 31, v150
	global_load_dwordx4 v[132:135], v[130:131], off
	v_lshlrev_b64 v[130:131], 6, v[150:151]
	v_lshl_add_u64 v[128:129], v[128:129], 0, v[130:131]
	global_load_dwordx4 v[128:131], v[128:129], off
	s_cselect_b64 s[66:67], -1, 0
	s_lshl_b32 s7, s6, 8
	s_add_i32 s7, s81, s7
	s_cmp_lt_i32 s6, 8
	s_mov_b64 s[68:69], -1
	s_waitcnt vmcnt(0)
	v_mov_b32_e32 v172, v161
	v_mov_b32_e32 v173, v162
	v_mov_b32_e32 v161, v163
	v_mov_b32_e32 v162, v169
	v_mov_b32_e32 v163, v170
	v_mov_b32_e32 v169, v171
	v_pk_add_f32 v[160:161], v[172:173], v[160:161]
	v_pk_add_f32 v[162:163], v[162:163], v[168:169]
	v_mov_b32_e32 v169, v160
	v_mov_b32_e32 v168, v162
	v_mov_b32_e32 v160, v163
	v_pk_add_f32 v[160:161], v[168:169], v[160:161]
	ds_bpermute_b32 v163, v219, v161
	ds_bpermute_b32 v162, v219, v160
	s_waitcnt lgkmcnt(0)
	v_pk_add_f32 v[160:161], v[160:161], v[162:163]
	ds_bpermute_b32 v163, v218, v161
	ds_bpermute_b32 v162, v218, v160
	s_waitcnt lgkmcnt(0)
	v_pk_add_f32 v[160:161], v[160:161], v[162:163]
	s_nop 0
	v_pk_fma_f32 v[172:173], v[160:161], s[30:31], v[178:179] op_sel_hi:[1,0,0]
	v_mov_b32_e32 v162, v199
	v_mul_f32_e32 v160, 0x4b800000, v173
	v_cmp_gt_f32_e32 vcc, s86, v173
	v_mov_b32_e32 v163, v200
	v_mov_b32_e32 v199, v201
	v_cndmask_b32_e32 v160, v173, v160, vcc
	v_rsq_f32_e32 v160, v160
	v_pk_add_f32 v[162:163], v[162:163], v[198:199]
	v_cmp_gt_f32_e64 s[4:5], s86, v172
	v_mov_b32_e32 v168, v162
	v_mul_f32_e32 v161, 0x45800000, v160
	v_cndmask_b32_e32 v174, v160, v161, vcc
	v_mov_b32_e32 v160, v195
	v_mov_b32_e32 v161, v196
	v_mov_b32_e32 v195, v197
	v_pk_add_f32 v[160:161], v[160:161], v[194:195]
	s_nop 0
	v_mov_b32_e32 v169, v160
	v_mov_b32_e32 v160, v163
	v_pk_add_f32 v[160:161], v[168:169], v[160:161]
	ds_bpermute_b32 v163, v219, v161
	ds_bpermute_b32 v162, v219, v160
	s_waitcnt lgkmcnt(0)
	v_pk_add_f32 v[168:169], v[160:161], v[162:163]
	v_mov_b32_e32 v160, v203
	v_mov_b32_e32 v161, v204
	v_mov_b32_e32 v203, v205
	v_mov_b32_e32 v162, v207
	v_mov_b32_e32 v163, v208
	v_mov_b32_e32 v207, v209
	v_pk_add_f32 v[160:161], v[160:161], v[202:203]
	v_pk_add_f32 v[162:163], v[162:163], v[206:207]
	v_mov_b32_e32 v195, v160
	v_mov_b32_e32 v194, v162
	v_mov_b32_e32 v160, v163
	v_pk_add_f32 v[160:161], v[194:195], v[160:161]
	v_mov_b32_e32 v194, v133
	v_mov_b32_e32 v195, v134
	v_mov_b32_e32 v133, v135
	v_mov_b32_e32 v134, v129
	v_mov_b32_e32 v135, v130
	v_mov_b32_e32 v129, v131
	v_pk_add_f32 v[132:133], v[194:195], v[132:133]
	v_pk_add_f32 v[128:129], v[134:135], v[128:129]
	v_mov_b32_e32 v131, v132
	v_mov_b32_e32 v130, v128
	v_mov_b32_e32 v132, v129
	v_pk_add_f32 v[128:129], v[130:131], v[132:133]
	ds_bpermute_b32 v163, v219, v161
	ds_bpermute_b32 v162, v219, v160
	ds_bpermute_b32 v131, v219, v129
	ds_bpermute_b32 v130, v219, v128
	ds_bpermute_b32 v171, v218, v169
	ds_bpermute_b32 v170, v218, v168
	s_waitcnt lgkmcnt(4)
	v_pk_add_f32 v[160:161], v[160:161], v[162:163]
	ds_bpermute_b32 v163, v218, v161
	s_waitcnt lgkmcnt(3)
	v_pk_add_f32 v[132:133], v[128:129], v[130:131]
	ds_bpermute_b32 v162, v218, v160
	ds_bpermute_b32 v135, v218, v133
	ds_bpermute_b32 v134, v218, v132
	v_lshlrev_b32_e32 v128, 3, v188
	v_add_u32_e32 v130, s7, v128
	v_lshlrev_b64 v[188:189], 11, v[148:149]
	v_ashrrev_i32_e32 v131, 31, v130
	s_cbranch_scc1 .LBB0_137
	v_mul_f32_e32 v196, v120, v174
	v_mul_f32_e32 v197, v121, v174
	v_mul_f32_e32 v198, v122, v174
	v_mul_f32_e32 v199, v123, v174
	v_mul_f32_e32 v129, v124, v174
	v_mul_f32_e32 v149, v125, v174
	v_mul_f32_e32 v173, v126, v174
	v_mul_f32_e32 v193, v127, v174
	v_cvt_pk_bf16_f32 v194, v129, v149
	v_cvt_pk_bf16_f32 v195, v173, v193
	v_cvt_pk_bf16_f32 v196, v196, v197
	v_cvt_pk_bf16_f32 v197, v198, v199
	v_lshl_add_u64 v[198:199], s[12:13], 0, v[188:189]
	v_lshl_add_u64 v[198:199], v[130:131], 1, v[198:199]
	global_store_dwordx4 v[198:199], v[194:197], off
	s_mov_b64 s[68:69], 0
	v_mul_f32_e32 v129, v116, v174
	v_mul_f32_e32 v196, v112, v174
	v_mul_f32_e32 v197, v113, v174
	v_mul_f32_e32 v149, v117, v174
	v_mul_f32_e32 v173, v118, v174
	v_mul_f32_e32 v193, v119, v174
	v_mul_f32_e32 v200, v114, v174
	v_mul_f32_e32 v201, v115, v174
	v_cvt_pk_bf16_f32 v194, v129, v149
	v_cvt_pk_bf16_f32 v195, v173, v193
	v_cvt_pk_bf16_f32 v196, v196, v197
	v_cvt_pk_bf16_f32 v197, v200, v201
	global_store_dwordx4 v[198:199], v[194:197], off offset:256

.LBB0_413:
	s_add_i32 vcc_lo, s62, 2
	s_add_u32 s4, s18, 0x100
	s_addc_u32 s5, s19, 0
	s_add_i32 s28, 0, 0x10000
	v_add_u32_e32 v140, s28, v164
	ds_read_b128 v[128:131], v140
	ds_read_b128 v[132:135], v140 offset:1024
	ds_read_b128 v[136:139], v140 offset:2048
	ds_read_b128 v[140:143], v140 offset:3072
	s_cmp_eq_u32 s13, s62
	s_cselect_b32 s62, s6, s85
	s_cselect_b32 s65, s17, s5
	s_cselect_b32 s64, s16, s4
	s_cselect_b32 s63, s7, s91
	v_lshl_add_u64 v[174:175], s[18:19], 0, v[150:151]
	s_add_i32 m0, s69, 0xc000
	ds_read_b128 v[154:157], v165
	ds_read_b128 v[158:161], v165 offset:1024
	ds_read_b128 v[166:169], v165 offset:2048
	ds_read_b128 v[170:173], v165 offset:3072
	ds_read_b128 v[188:191], v165 offset:4096
	ds_read_b128 v[192:195], v165 offset:5120
	ds_read_b128 v[196:199], v165 offset:6144
	ds_read_b128 v[200:203], v165 offset:7168
	global_load_lds_dwordx4 v[174:175], off
	v_lshl_add_u64 v[174:175], s[18:19], 0, v[152:153]
	s_add_i32 m0, s69, 0xe000
	s_nop 0
	global_load_lds_dwordx4 v[174:175], off
	s_waitcnt lgkmcnt(8)
	s_barrier
	s_setprio 1
	s_waitcnt lgkmcnt(7)
	v_mfma_f32_16x16x32_bf16 v[124:127], v[128:131], v[154:157], v[124:127]
	v_mfma_f32_16x16x32_bf16 v[120:123], v[136:139], v[154:157], v[120:123]
	s_waitcnt lgkmcnt(5)
	v_mfma_f32_16x16x32_bf16 v[108:111], v[128:131], v[166:169], v[108:111]
	v_mfma_f32_16x16x32_bf16 v[104:107], v[136:139], v[166:169], v[104:107]
	s_waitcnt lgkmcnt(3)
	v_mfma_f32_16x16x32_bf16 v[92:95], v[128:131], v[188:191], v[92:95]
	v_mfma_f32_16x16x32_bf16 v[88:91], v[136:139], v[188:191], v[88:91]
	s_waitcnt lgkmcnt(1)
	v_mfma_f32_16x16x32_bf16 v[76:79], v[128:131], v[196:199], v[76:79]
	v_mfma_f32_16x16x32_bf16 v[72:75], v[136:139], v[196:199], v[72:75]
	v_mfma_f32_16x16x32_bf16 v[124:127], v[132:135], v[158:161], v[124:127]
	v_mfma_f32_16x16x32_bf16 v[120:123], v[140:143], v[158:161], v[120:123]
	v_mfma_f32_16x16x32_bf16 v[108:111], v[132:135], v[170:173], v[108:111]
	v_mfma_f32_16x16x32_bf16 v[104:107], v[140:143], v[170:173], v[104:107]
	v_mfma_f32_16x16x32_bf16 v[92:95], v[132:135], v[192:195], v[92:95]
	v_mfma_f32_16x16x32_bf16 v[88:91], v[140:143], v[192:195], v[88:91]
	s_waitcnt lgkmcnt(0)
	v_mfma_f32_16x16x32_bf16 v[76:79], v[132:135], v[200:203], v[76:79]
	v_mfma_f32_16x16x32_bf16 v[72:75], v[140:143], v[200:203], v[72:75]
	s_setprio 0
	s_barrier
	s_add_i32 s29, 0, 0x14000
	v_add_u32_e32 v174, s29, v164
	s_add_i32 s18, s28, s68
	ds_read_b128 v[204:207], v174
	ds_read_b128 v[208:211], v174 offset:1024
	ds_read_b128 v[212:215], v174 offset:2048
	ds_read_b128 v[232:235], v174 offset:3072
	v_lshl_add_u64 v[174:175], s[62:63], 0, v[176:177]
	s_mov_b32 m0, s18
	v_lshl_add_u64 v[216:217], s[62:63], 0, v[148:149]
	global_load_lds_dwordx4 v[174:175], off
	s_add_i32 m0, s18, 0x2000
	s_nop 0
	global_load_lds_dwordx4 v[216:217], off
	s_barrier
	s_setprio 1
	s_waitcnt lgkmcnt(3)
	v_mfma_f32_16x16x32_bf16 v[116:119], v[204:207], v[154:157], v[116:119]
	s_waitcnt lgkmcnt(1)
	v_mfma_f32_16x16x32_bf16 v[112:115], v[212:215], v[154:157], v[112:115]
	v_mfma_f32_16x16x32_bf16 v[100:103], v[204:207], v[166:169], v[100:103]
	v_mfma_f32_16x16x32_bf16 v[96:99], v[212:215], v[166:169], v[96:99]
	v_mfma_f32_16x16x32_bf16 v[84:87], v[204:207], v[188:191], v[84:87]
	v_mfma_f32_16x16x32_bf16 v[80:83], v[212:215], v[188:191], v[80:83]
	v_mfma_f32_16x16x32_bf16 v[68:71], v[204:207], v[196:199], v[68:71]
	v_mfma_f32_16x16x32_bf16 v[64:67], v[212:215], v[196:199], v[64:67]
	v_mfma_f32_16x16x32_bf16 v[116:119], v[208:211], v[158:161], v[116:119]
	s_waitcnt lgkmcnt(0)
	v_mfma_f32_16x16x32_bf16 v[112:115], v[232:235], v[158:161], v[112:115]
	v_mfma_f32_16x16x32_bf16 v[100:103], v[208:211], v[170:173], v[100:103]
	v_mfma_f32_16x16x32_bf16 v[96:99], v[232:235], v[170:173], v[96:99]
	v_mfma_f32_16x16x32_bf16 v[84:87], v[208:211], v[192:195], v[84:87]
	v_mfma_f32_16x16x32_bf16 v[80:83], v[232:235], v[192:195], v[80:83]
	v_mfma_f32_16x16x32_bf16 v[68:71], v[208:211], v[200:203], v[68:71]
	v_mfma_f32_16x16x32_bf16 v[64:67], v[232:235], v[200:203], v[64:67]
	s_setprio 0
	s_mov_b32 m0, s69
	v_lshl_add_u64 v[236:237], s[64:65], 0, v[144:145]
	s_barrier
	ds_read_b128 v[154:157], v165 offset:16384
	ds_read_b128 v[158:161], v165 offset:17408
	ds_read_b128 v[166:169], v165 offset:18432
	ds_read_b128 v[170:173], v165 offset:19456
	ds_read_b128 v[188:191], v165 offset:20480
	ds_read_b128 v[192:195], v165 offset:21504
	ds_read_b128 v[196:199], v165 offset:22528
	ds_read_b128 v[200:203], v165 offset:23552
	global_load_lds_dwordx4 v[236:237], off
	v_lshl_add_u64 v[238:239], s[64:65], 0, v[146:147]
	s_mov_b32 m0, s70
	s_nop 0
	global_load_lds_dwordx4 v[238:239], off
	s_barrier
	s_setprio 1
	s_waitcnt lgkmcnt(7)
	v_mfma_f32_16x16x32_bf16 v[60:63], v[128:131], v[154:157], v[60:63]
	v_mfma_f32_16x16x32_bf16 v[56:59], v[136:139], v[154:157], v[56:59]
	s_waitcnt lgkmcnt(5)
	v_mfma_f32_16x16x32_bf16 v[44:47], v[128:131], v[166:169], v[44:47]
	v_mfma_f32_16x16x32_bf16 v[40:43], v[136:139], v[166:169], v[40:43]
	s_waitcnt lgkmcnt(3)
	v_mfma_f32_16x16x32_bf16 v[28:31], v[128:131], v[188:191], v[28:31]
	v_mfma_f32_16x16x32_bf16 v[24:27], v[136:139], v[188:191], v[24:27]
	s_waitcnt lgkmcnt(1)
	v_mfma_f32_16x16x32_bf16 v[12:15], v[128:131], v[196:199], v[12:15]
	v_mfma_f32_16x16x32_bf16 v[8:11], v[136:139], v[196:199], v[8:11]
	v_mfma_f32_16x16x32_bf16 v[60:63], v[132:135], v[158:161], v[60:63]
	v_mfma_f32_16x16x32_bf16 v[56:59], v[140:143], v[158:161], v[56:59]
	v_mfma_f32_16x16x32_bf16 v[44:47], v[132:135], v[170:173], v[44:47]
	v_mfma_f32_16x16x32_bf16 v[40:43], v[140:143], v[170:173], v[40:43]
	v_mfma_f32_16x16x32_bf16 v[28:31], v[132:135], v[192:195], v[28:31]
	v_mfma_f32_16x16x32_bf16 v[24:27], v[140:143], v[192:195], v[24:27]
	s_waitcnt lgkmcnt(0)
	v_mfma_f32_16x16x32_bf16 v[12:15], v[132:135], v[200:203], v[12:15]
	v_mfma_f32_16x16x32_bf16 v[8:11], v[140:143], v[200:203], v[8:11]
	s_setprio 0
	s_barrier
	s_add_u32 s18, s62, 0x18000
	s_addc_u32 s19, s63, 0
	s_add_i32 s28, s29, s68
	v_lshl_add_u64 v[128:129], s[18:19], 0, v[176:177]
	s_mov_b32 m0, s28
	s_nop 0
	global_load_lds_dwordx4 v[128:129], off
	v_lshl_add_u64 v[128:129], s[18:19], 0, v[148:149]
	s_add_i32 m0, s28, 0x2000
	s_nop 0
	global_load_lds_dwordx4 v[128:129], off
	s_waitcnt vmcnt(6)
	s_barrier
	s_setprio 1
	v_mfma_f32_16x16x32_bf16 v[52:55], v[204:207], v[154:157], v[52:55]
	v_mfma_f32_16x16x32_bf16 v[48:51], v[212:215], v[154:157], v[48:51]
	v_mfma_f32_16x16x32_bf16 v[36:39], v[204:207], v[166:169], v[36:39]
	v_mfma_f32_16x16x32_bf16 v[32:35], v[212:215], v[166:169], v[32:35]
	v_mfma_f32_16x16x32_bf16 v[20:23], v[204:207], v[188:191], v[20:23]
	v_mfma_f32_16x16x32_bf16 v[16:19], v[212:215], v[188:191], v[16:19]
	v_mfma_f32_16x16x32_bf16 v[4:7], v[204:207], v[196:199], v[4:7]
	v_mfma_f32_16x16x32_bf16 v[0:3], v[212:215], v[196:199], v[0:3]
	v_mfma_f32_16x16x32_bf16 v[52:55], v[208:211], v[158:161], v[52:55]
	v_mfma_f32_16x16x32_bf16 v[48:51], v[232:235], v[158:161], v[48:51]
	v_mfma_f32_16x16x32_bf16 v[36:39], v[208:211], v[170:173], v[36:39]
	v_mfma_f32_16x16x32_bf16 v[32:35], v[232:235], v[170:173], v[32:35]
	v_mfma_f32_16x16x32_bf16 v[20:23], v[208:211], v[192:195], v[20:23]
	v_mfma_f32_16x16x32_bf16 v[16:19], v[232:235], v[192:195], v[16:19]
	v_mfma_f32_16x16x32_bf16 v[4:7], v[208:211], v[200:203], v[4:7]
	v_mfma_f32_16x16x32_bf16 v[0:3], v[232:235], v[200:203], v[0:3]
	s_setprio 0
	s_add_i32 s28, 0, 0x18000
	v_add_u32_e32 v140, s28, v164
	s_barrier
	ds_read_b128 v[128:131], v140
	ds_read_b128 v[132:135], v140 offset:1024
	ds_read_b128 v[136:139], v140 offset:2048
	ds_read_b128 v[140:143], v140 offset:3072
	s_add_u32 s18, s64, 0x18000
	s_addc_u32 s19, s65, 0
	s_mov_b32 m0, s71
	v_lshl_add_u64 v[204:205], s[18:19], 0, v[144:145]
	ds_read_b128 v[154:157], v165 offset:32768
	ds_read_b128 v[158:161], v165 offset:33792
	ds_read_b128 v[166:169], v165 offset:34816
	ds_read_b128 v[170:173], v165 offset:35840
	ds_read_b128 v[188:191], v165 offset:36864
	ds_read_b128 v[192:195], v165 offset:37888
	ds_read_b128 v[196:199], v165 offset:38912
	ds_read_b128 v[200:203], v165 offset:39936
	global_load_lds_dwordx4 v[204:205], off
	v_lshl_add_u64 v[204:205], s[18:19], 0, v[146:147]
	s_mov_b32 m0, s72
	s_nop 0
	global_load_lds_dwordx4 v[204:205], off
	s_waitcnt lgkmcnt(8)
	s_barrier
	s_setprio 1
	s_waitcnt lgkmcnt(7)
	v_mfma_f32_16x16x32_bf16 v[124:127], v[128:131], v[154:157], v[124:127]
	v_mfma_f32_16x16x32_bf16 v[120:123], v[136:139], v[154:157], v[120:123]
	s_waitcnt lgkmcnt(5)
	v_mfma_f32_16x16x32_bf16 v[108:111], v[128:131], v[166:169], v[108:111]
	v_mfma_f32_16x16x32_bf16 v[104:107], v[136:139], v[166:169], v[104:107]
	s_waitcnt lgkmcnt(3)
	v_mfma_f32_16x16x32_bf16 v[92:95], v[128:131], v[188:191], v[92:95]
	v_mfma_f32_16x16x32_bf16 v[88:91], v[136:139], v[188:191], v[88:91]
	s_waitcnt lgkmcnt(1)
	v_mfma_f32_16x16x32_bf16 v[76:79], v[128:131], v[196:199], v[76:79]
	v_mfma_f32_16x16x32_bf16 v[72:75], v[136:139], v[196:199], v[72:75]
	v_mfma_f32_16x16x32_bf16 v[124:127], v[132:135], v[158:161], v[124:127]
	v_mfma_f32_16x16x32_bf16 v[120:123], v[140:143], v[158:161], v[120:123]
	v_mfma_f32_16x16x32_bf16 v[108:111], v[132:135], v[170:173], v[108:111]
	v_mfma_f32_16x16x32_bf16 v[104:107], v[140:143], v[170:173], v[104:107]
	v_mfma_f32_16x16x32_bf16 v[92:95], v[132:135], v[192:195], v[92:95]
	v_mfma_f32_16x16x32_bf16 v[88:91], v[140:143], v[192:195], v[88:91]
	s_waitcnt lgkmcnt(0)
	v_mfma_f32_16x16x32_bf16 v[76:79], v[132:135], v[200:203], v[76:79]
	v_mfma_f32_16x16x32_bf16 v[72:75], v[140:143], v[200:203], v[72:75]
	s_setprio 0
	s_barrier
	s_add_i32 s29, 0, 0x1c000
	s_add_i32 s18, s28, s68
	v_add_u32_e32 v232, s29, v164
	v_lshl_add_u64 v[174:175], v[174:175], 0, s[40:41]
	s_mov_b32 m0, s18
	ds_read_b128 v[204:207], v232
	ds_read_b128 v[208:211], v232 offset:1024
	ds_read_b128 v[212:215], v232 offset:2048
	ds_read_b128 v[232:235], v232 offset:3072
	global_load_lds_dwordx4 v[174:175], off
	v_lshl_add_u64 v[174:175], v[216:217], 0, s[40:41]
	s_add_i32 m0, s18, 0x2000
	s_nop 0
	global_load_lds_dwordx4 v[174:175], off
	s_barrier
	s_setprio 1
	s_waitcnt lgkmcnt(3)
	v_mfma_f32_16x16x32_bf16 v[116:119], v[204:207], v[154:157], v[116:119]
	s_waitcnt lgkmcnt(1)
	v_mfma_f32_16x16x32_bf16 v[112:115], v[212:215], v[154:157], v[112:115]
	v_mfma_f32_16x16x32_bf16 v[100:103], v[204:207], v[166:169], v[100:103]
	v_mfma_f32_16x16x32_bf16 v[96:99], v[212:215], v[166:169], v[96:99]
	v_mfma_f32_16x16x32_bf16 v[84:87], v[204:207], v[188:191], v[84:87]
	v_mfma_f32_16x16x32_bf16 v[80:83], v[212:215], v[188:191], v[80:83]
	v_mfma_f32_16x16x32_bf16 v[68:71], v[204:207], v[196:199], v[68:71]
	v_mfma_f32_16x16x32_bf16 v[64:67], v[212:215], v[196:199], v[64:67]
	v_mfma_f32_16x16x32_bf16 v[116:119], v[208:211], v[158:161], v[116:119]
	s_waitcnt lgkmcnt(0)
	v_mfma_f32_16x16x32_bf16 v[112:115], v[232:235], v[158:161], v[112:115]
	v_mfma_f32_16x16x32_bf16 v[100:103], v[208:211], v[170:173], v[100:103]
	v_mfma_f32_16x16x32_bf16 v[96:99], v[232:235], v[170:173], v[96:99]
	v_mfma_f32_16x16x32_bf16 v[84:87], v[208:211], v[192:195], v[84:87]
	v_mfma_f32_16x16x32_bf16 v[80:83], v[232:235], v[192:195], v[80:83]
	v_mfma_f32_16x16x32_bf16 v[68:71], v[208:211], v[200:203], v[68:71]
	v_mfma_f32_16x16x32_bf16 v[64:67], v[232:235], v[200:203], v[64:67]
	s_setprio 0
	s_mov_b32 m0, s75
	v_lshl_add_u64 v[174:175], v[236:237], 0, s[40:41]
	s_barrier
	ds_read_b128 v[154:157], v165 offset:49152
	ds_read_b128 v[158:161], v165 offset:50176
	ds_read_b128 v[166:169], v165 offset:51200
	ds_read_b128 v[170:173], v165 offset:52224
	ds_read_b128 v[188:191], v165 offset:53248
	ds_read_b128 v[192:195], v165 offset:54272
	ds_read_b128 v[196:199], v165 offset:55296
	ds_read_b128 v[200:203], v165 offset:56320
	global_load_lds_dwordx4 v[174:175], off
	v_lshl_add_u64 v[174:175], v[238:239], 0, s[40:41]
	s_mov_b32 m0, s76
	s_nop 0
	global_load_lds_dwordx4 v[174:175], off
	s_barrier
	s_setprio 1
	s_waitcnt lgkmcnt(7)
	v_mfma_f32_16x16x32_bf16 v[60:63], v[128:131], v[154:157], v[60:63]
	v_mfma_f32_16x16x32_bf16 v[56:59], v[136:139], v[154:157], v[56:59]
	s_waitcnt lgkmcnt(5)
	v_mfma_f32_16x16x32_bf16 v[44:47], v[128:131], v[166:169], v[44:47]
	v_mfma_f32_16x16x32_bf16 v[40:43], v[136:139], v[166:169], v[40:43]
	s_waitcnt lgkmcnt(3)
	v_mfma_f32_16x16x32_bf16 v[28:31], v[128:131], v[188:191], v[28:31]
	v_mfma_f32_16x16x32_bf16 v[24:27], v[136:139], v[188:191], v[24:27]
	s_waitcnt lgkmcnt(1)
	v_mfma_f32_16x16x32_bf16 v[12:15], v[128:131], v[196:199], v[12:15]
	v_mfma_f32_16x16x32_bf16 v[8:11], v[136:139], v[196:199], v[8:11]
	v_mfma_f32_16x16x32_bf16 v[60:63], v[132:135], v[158:161], v[60:63]
	v_mfma_f32_16x16x32_bf16 v[56:59], v[140:143], v[158:161], v[56:59]
	v_mfma_f32_16x16x32_bf16 v[44:47], v[132:135], v[170:173], v[44:47]
	v_mfma_f32_16x16x32_bf16 v[40:43], v[140:143], v[170:173], v[40:43]
	v_mfma_f32_16x16x32_bf16 v[28:31], v[132:135], v[192:195], v[28:31]
	v_mfma_f32_16x16x32_bf16 v[24:27], v[140:143], v[192:195], v[24:27]
	s_waitcnt lgkmcnt(0)
	v_mfma_f32_16x16x32_bf16 v[12:15], v[132:135], v[200:203], v[12:15]
	v_mfma_f32_16x16x32_bf16 v[8:11], v[140:143], v[200:203], v[8:11]
	s_setprio 0
	s_barrier
	s_add_u32 s18, s62, 0x18080
	s_addc_u32 s19, s63, 0
	s_add_i32 s28, s29, s68
	v_lshl_add_u64 v[128:129], s[18:19], 0, v[176:177]
	s_mov_b32 m0, s28
	s_nop 0
	global_load_lds_dwordx4 v[128:129], off
	v_lshl_add_u64 v[128:129], s[18:19], 0, v[148:149]
	s_add_i32 m0, s28, 0x2000
	s_nop 0
	global_load_lds_dwordx4 v[128:129], off
	s_waitcnt vmcnt(6)
	s_barrier
	s_setprio 1
	v_mfma_f32_16x16x32_bf16 v[52:55], v[204:207], v[154:157], v[52:55]
	v_mfma_f32_16x16x32_bf16 v[48:51], v[212:215], v[154:157], v[48:51]
	v_mfma_f32_16x16x32_bf16 v[36:39], v[204:207], v[166:169], v[36:39]
	v_mfma_f32_16x16x32_bf16 v[32:35], v[212:215], v[166:169], v[32:35]
	v_mfma_f32_16x16x32_bf16 v[20:23], v[204:207], v[188:191], v[20:23]
	v_mfma_f32_16x16x32_bf16 v[16:19], v[212:215], v[188:191], v[16:19]
	v_mfma_f32_16x16x32_bf16 v[4:7], v[204:207], v[196:199], v[4:7]
	v_mfma_f32_16x16x32_bf16 v[0:3], v[212:215], v[196:199], v[0:3]
	v_mfma_f32_16x16x32_bf16 v[52:55], v[208:211], v[158:161], v[52:55]
	v_mfma_f32_16x16x32_bf16 v[48:51], v[232:235], v[158:161], v[48:51]
	v_mfma_f32_16x16x32_bf16 v[36:39], v[208:211], v[170:173], v[36:39]
	v_mfma_f32_16x16x32_bf16 v[32:35], v[232:235], v[170:173], v[32:35]
	v_mfma_f32_16x16x32_bf16 v[20:23], v[208:211], v[192:195], v[20:23]
	v_mfma_f32_16x16x32_bf16 v[16:19], v[232:235], v[192:195], v[16:19]
	v_mfma_f32_16x16x32_bf16 v[4:7], v[208:211], v[200:203], v[4:7]
	v_mfma_f32_16x16x32_bf16 v[0:3], v[232:235], v[200:203], v[0:3]
	s_setprio 0
	s_add_u32 s85, s85, 0x100
	s_addc_u32 s91, s91, 0
	s_cmp_lt_i32 vcc_lo, s67
	s_mov_b64 s[18:19], s[4:5]
	s_mov_b32 s62, vcc_lo
	s_barrier
	s_cbranch_scc1 .LBB0_413
	s_ashr_i32 s4, s66, 2
	v_mov_b32_e32 v128, v163
	v_mov_b32_e32 v166, v162
	s_cmp_eq_u32 s4, 2
	s_cbranch_scc1 .LBB0_416
	s_mul_i32 s13, s4, 0x2280000
	s_mul_hi_i32 s5, s4, 0x2280000
	s_add_u32 s18, s13, 0x5858000
	s_addc_u32 s19, s5, 0
	s_mov_b32 s62, 1.0
	s_branch .LBB0_417

.LBB0_505:
	s_add_u32 s6, s4, 0xfff80080
	s_addc_u32 s7, s5, -1
	s_add_i32 s28, 0, 0x10000
	v_add_u32_e32 v154, s28, v144
	ds_read_b128 v[138:141], v154
	ds_read_b128 v[146:149], v154 offset:1024
	ds_read_b128 v[150:153], v154 offset:2048
	ds_read_b128 v[154:157], v154 offset:3072
	s_cmp_eq_u32 s72, 28
	s_cselect_b32 s9, s10, s7
	s_cselect_b32 s8, s11, s6
	s_cselect_b32 s7, s63, s71
	s_cselect_b32 s6, s65, s70
	v_lshl_add_u64 v[174:175], s[4:5], 0, v[134:135]
	s_add_i32 m0, s17, 0xc000
	ds_read_b128 v[158:161], v145
	ds_read_b128 v[162:165], v145 offset:1024
	ds_read_b128 v[166:169], v145 offset:2048
	ds_read_b128 v[170:173], v145 offset:3072
	ds_read_b128 v[188:191], v145 offset:4096
	ds_read_b128 v[192:195], v145 offset:5120
	ds_read_b128 v[196:199], v145 offset:6144
	ds_read_b128 v[200:203], v145 offset:7168
	global_load_lds_dwordx4 v[174:175], off
	v_lshl_add_u64 v[174:175], s[4:5], 0, v[136:137]
	s_add_i32 m0, s17, 0xe000
	s_nop 0
	global_load_lds_dwordx4 v[174:175], off
	s_waitcnt lgkmcnt(8)
	s_barrier
	s_setprio 1
	s_waitcnt lgkmcnt(7)
	v_mfma_f32_16x16x32_bf16 v[124:127], v[138:141], v[158:161], v[124:127]
	v_mfma_f32_16x16x32_bf16 v[120:123], v[150:153], v[158:161], v[120:123]
	s_waitcnt lgkmcnt(5)
	v_mfma_f32_16x16x32_bf16 v[116:119], v[138:141], v[166:169], v[116:119]
	v_mfma_f32_16x16x32_bf16 v[108:111], v[150:153], v[166:169], v[108:111]
	s_waitcnt lgkmcnt(3)
	v_mfma_f32_16x16x32_bf16 v[100:103], v[138:141], v[188:191], v[100:103]
	v_mfma_f32_16x16x32_bf16 v[92:95], v[150:153], v[188:191], v[92:95]
	s_waitcnt lgkmcnt(1)
	v_mfma_f32_16x16x32_bf16 v[84:87], v[138:141], v[196:199], v[84:87]
	v_mfma_f32_16x16x32_bf16 v[76:79], v[150:153], v[196:199], v[76:79]
	v_mfma_f32_16x16x32_bf16 v[124:127], v[146:149], v[162:165], v[124:127]
	v_mfma_f32_16x16x32_bf16 v[120:123], v[154:157], v[162:165], v[120:123]
	v_mfma_f32_16x16x32_bf16 v[116:119], v[146:149], v[170:173], v[116:119]
	v_mfma_f32_16x16x32_bf16 v[108:111], v[154:157], v[170:173], v[108:111]
	v_mfma_f32_16x16x32_bf16 v[100:103], v[146:149], v[192:195], v[100:103]
	v_mfma_f32_16x16x32_bf16 v[92:95], v[154:157], v[192:195], v[92:95]
	s_waitcnt lgkmcnt(0)
	v_mfma_f32_16x16x32_bf16 v[84:87], v[146:149], v[200:203], v[84:87]
	v_mfma_f32_16x16x32_bf16 v[76:79], v[154:157], v[200:203], v[76:79]
	s_setprio 0
	s_barrier
	s_add_i32 s29, 0, 0x14000
	v_add_u32_e32 v174, s29, v144
	s_add_i32 s28, s28, s77
	ds_read_b128 v[204:207], v174
	ds_read_b128 v[208:211], v174 offset:1024
	ds_read_b128 v[212:215], v174 offset:2048
	ds_read_b128 v[232:235], v174 offset:3072
	v_lshl_add_u64 v[174:175], s[6:7], 0, v[176:177]
	s_mov_b32 m0, s28
	v_lshl_add_u64 v[216:217], s[6:7], 0, v[132:133]
	global_load_lds_dwordx4 v[174:175], off
	s_add_i32 m0, s28, 0x2000
	s_nop 0
	global_load_lds_dwordx4 v[216:217], off
	s_barrier
	s_setprio 1
	s_waitcnt lgkmcnt(3)
	v_mfma_f32_16x16x32_bf16 v[112:115], v[204:207], v[158:161], v[112:115]
	s_waitcnt lgkmcnt(1)
	v_mfma_f32_16x16x32_bf16 v[104:107], v[212:215], v[158:161], v[104:107]
	v_mfma_f32_16x16x32_bf16 v[96:99], v[204:207], v[166:169], v[96:99]
	v_mfma_f32_16x16x32_bf16 v[88:91], v[212:215], v[166:169], v[88:91]
	v_mfma_f32_16x16x32_bf16 v[80:83], v[204:207], v[188:191], v[80:83]
	v_mfma_f32_16x16x32_bf16 v[72:75], v[212:215], v[188:191], v[72:75]
	v_mfma_f32_16x16x32_bf16 v[68:71], v[204:207], v[196:199], v[68:71]
	v_mfma_f32_16x16x32_bf16 v[64:67], v[212:215], v[196:199], v[64:67]
	v_mfma_f32_16x16x32_bf16 v[112:115], v[208:211], v[162:165], v[112:115]
	s_waitcnt lgkmcnt(0)
	v_mfma_f32_16x16x32_bf16 v[104:107], v[232:235], v[162:165], v[104:107]
	v_mfma_f32_16x16x32_bf16 v[96:99], v[208:211], v[170:173], v[96:99]
	v_mfma_f32_16x16x32_bf16 v[88:91], v[232:235], v[170:173], v[88:91]
	v_mfma_f32_16x16x32_bf16 v[80:83], v[208:211], v[192:195], v[80:83]
	v_mfma_f32_16x16x32_bf16 v[72:75], v[232:235], v[192:195], v[72:75]
	v_mfma_f32_16x16x32_bf16 v[68:71], v[208:211], v[200:203], v[68:71]
	v_mfma_f32_16x16x32_bf16 v[64:67], v[232:235], v[200:203], v[64:67]
	s_setprio 0
	s_mov_b32 m0, s17
	v_lshl_add_u64 v[236:237], s[8:9], 0, v[128:129]
	s_barrier
	ds_read_b128 v[158:161], v145 offset:16384
	ds_read_b128 v[162:165], v145 offset:17408
	ds_read_b128 v[166:169], v145 offset:18432
	ds_read_b128 v[170:173], v145 offset:19456
	ds_read_b128 v[188:191], v145 offset:20480
	ds_read_b128 v[192:195], v145 offset:21504
	ds_read_b128 v[196:199], v145 offset:22528
	ds_read_b128 v[200:203], v145 offset:23552
	global_load_lds_dwordx4 v[236:237], off
	v_lshl_add_u64 v[238:239], s[8:9], 0, v[130:131]
	s_mov_b32 m0, s19
	s_nop 0
	global_load_lds_dwordx4 v[238:239], off
	s_barrier
	s_setprio 1
	s_waitcnt lgkmcnt(7)
	v_mfma_f32_16x16x32_bf16 v[60:63], v[138:141], v[158:161], v[60:63]
	v_mfma_f32_16x16x32_bf16 v[56:59], v[150:153], v[158:161], v[56:59]
	s_waitcnt lgkmcnt(5)
	v_mfma_f32_16x16x32_bf16 v[52:55], v[138:141], v[166:169], v[52:55]
	v_mfma_f32_16x16x32_bf16 v[44:47], v[150:153], v[166:169], v[44:47]
	s_waitcnt lgkmcnt(3)
	v_mfma_f32_16x16x32_bf16 v[36:39], v[138:141], v[188:191], v[36:39]
	v_mfma_f32_16x16x32_bf16 v[28:31], v[150:153], v[188:191], v[28:31]
	s_waitcnt lgkmcnt(1)
	v_mfma_f32_16x16x32_bf16 v[20:23], v[138:141], v[196:199], v[20:23]
	v_mfma_f32_16x16x32_bf16 v[12:15], v[150:153], v[196:199], v[12:15]
	v_mfma_f32_16x16x32_bf16 v[60:63], v[146:149], v[162:165], v[60:63]
	v_mfma_f32_16x16x32_bf16 v[56:59], v[154:157], v[162:165], v[56:59]
	v_mfma_f32_16x16x32_bf16 v[52:55], v[146:149], v[170:173], v[52:55]
	v_mfma_f32_16x16x32_bf16 v[44:47], v[154:157], v[170:173], v[44:47]
	v_mfma_f32_16x16x32_bf16 v[36:39], v[146:149], v[192:195], v[36:39]
	v_mfma_f32_16x16x32_bf16 v[28:31], v[154:157], v[192:195], v[28:31]
	s_waitcnt lgkmcnt(0)
	v_mfma_f32_16x16x32_bf16 v[20:23], v[146:149], v[200:203], v[20:23]
	v_mfma_f32_16x16x32_bf16 v[12:15], v[154:157], v[200:203], v[12:15]
	s_setprio 0
	s_barrier
	s_add_u32 vcc_lo, s6, 0x80000
	s_addc_u32 vcc_hi, s7, 0
	s_add_i32 s28, s29, s77
	v_lshl_add_u64 v[138:139], vcc, 0, v[176:177]
	s_mov_b32 m0, s28
	s_nop 0
	global_load_lds_dwordx4 v[138:139], off
	v_lshl_add_u64 v[138:139], vcc, 0, v[132:133]
	s_add_i32 m0, s28, 0x2000
	s_nop 0
	global_load_lds_dwordx4 v[138:139], off
	s_waitcnt vmcnt(6)
	s_barrier
	s_setprio 1
	v_mfma_f32_16x16x32_bf16 v[48:51], v[204:207], v[158:161], v[48:51]
	v_mfma_f32_16x16x32_bf16 v[40:43], v[212:215], v[158:161], v[40:43]
	v_mfma_f32_16x16x32_bf16 v[32:35], v[204:207], v[166:169], v[32:35]
	v_mfma_f32_16x16x32_bf16 v[24:27], v[212:215], v[166:169], v[24:27]
	v_mfma_f32_16x16x32_bf16 v[16:19], v[204:207], v[188:191], v[16:19]
	v_mfma_f32_16x16x32_bf16 v[8:11], v[212:215], v[188:191], v[8:11]
	v_mfma_f32_16x16x32_bf16 v[4:7], v[204:207], v[196:199], v[4:7]
	v_mfma_f32_16x16x32_bf16 v[0:3], v[212:215], v[196:199], v[0:3]
	v_mfma_f32_16x16x32_bf16 v[48:51], v[208:211], v[162:165], v[48:51]
	v_mfma_f32_16x16x32_bf16 v[40:43], v[232:235], v[162:165], v[40:43]
	v_mfma_f32_16x16x32_bf16 v[32:35], v[208:211], v[170:173], v[32:35]
	v_mfma_f32_16x16x32_bf16 v[24:27], v[232:235], v[170:173], v[24:27]
	v_mfma_f32_16x16x32_bf16 v[16:19], v[208:211], v[192:195], v[16:19]
	v_mfma_f32_16x16x32_bf16 v[8:11], v[232:235], v[192:195], v[8:11]
	v_mfma_f32_16x16x32_bf16 v[4:7], v[208:211], v[200:203], v[4:7]
	v_mfma_f32_16x16x32_bf16 v[0:3], v[232:235], v[200:203], v[0:3]
	s_setprio 0
	s_add_i32 s28, 0, 0x18000
	v_add_u32_e32 v154, s28, v144
	s_barrier
	ds_read_b128 v[138:141], v154
	ds_read_b128 v[146:149], v154 offset:1024
	ds_read_b128 v[150:153], v154 offset:2048
	ds_read_b128 v[154:157], v154 offset:3072
	s_add_u32 s8, s8, 0x80000
	s_addc_u32 s9, s9, 0
	s_mov_b32 m0, s78
	v_lshl_add_u64 v[204:205], s[8:9], 0, v[128:129]
	ds_read_b128 v[158:161], v145 offset:32768
	ds_read_b128 v[162:165], v145 offset:33792
	ds_read_b128 v[166:169], v145 offset:34816
	ds_read_b128 v[170:173], v145 offset:35840
	ds_read_b128 v[188:191], v145 offset:36864
	ds_read_b128 v[192:195], v145 offset:37888
	ds_read_b128 v[196:199], v145 offset:38912
	ds_read_b128 v[200:203], v145 offset:39936
	global_load_lds_dwordx4 v[204:205], off
	v_lshl_add_u64 v[204:205], s[8:9], 0, v[130:131]
	s_mov_b32 m0, s79
	s_nop 0
	global_load_lds_dwordx4 v[204:205], off
	s_waitcnt lgkmcnt(8)
	s_barrier
	s_setprio 1
	s_waitcnt lgkmcnt(7)
	v_mfma_f32_16x16x32_bf16 v[124:127], v[138:141], v[158:161], v[124:127]
	v_mfma_f32_16x16x32_bf16 v[120:123], v[150:153], v[158:161], v[120:123]
	s_waitcnt lgkmcnt(5)
	v_mfma_f32_16x16x32_bf16 v[116:119], v[138:141], v[166:169], v[116:119]
	v_mfma_f32_16x16x32_bf16 v[108:111], v[150:153], v[166:169], v[108:111]
	s_waitcnt lgkmcnt(3)
	v_mfma_f32_16x16x32_bf16 v[100:103], v[138:141], v[188:191], v[100:103]
	v_mfma_f32_16x16x32_bf16 v[92:95], v[150:153], v[188:191], v[92:95]
	s_waitcnt lgkmcnt(1)
	v_mfma_f32_16x16x32_bf16 v[84:87], v[138:141], v[196:199], v[84:87]
	v_mfma_f32_16x16x32_bf16 v[76:79], v[150:153], v[196:199], v[76:79]
	v_mfma_f32_16x16x32_bf16 v[124:127], v[146:149], v[162:165], v[124:127]
	v_mfma_f32_16x16x32_bf16 v[120:123], v[154:157], v[162:165], v[120:123]
	v_mfma_f32_16x16x32_bf16 v[116:119], v[146:149], v[170:173], v[116:119]
	v_mfma_f32_16x16x32_bf16 v[108:111], v[154:157], v[170:173], v[108:111]
	v_mfma_f32_16x16x32_bf16 v[100:103], v[146:149], v[192:195], v[100:103]
	v_mfma_f32_16x16x32_bf16 v[92:95], v[154:157], v[192:195], v[92:95]
	s_waitcnt lgkmcnt(0)
	v_mfma_f32_16x16x32_bf16 v[84:87], v[146:149], v[200:203], v[84:87]
	v_mfma_f32_16x16x32_bf16 v[76:79], v[154:157], v[200:203], v[76:79]
	s_setprio 0
	s_barrier
	s_add_i32 s8, 0, 0x1c000
	s_add_i32 s9, s28, s77
	v_add_u32_e32 v232, s8, v144
	v_lshl_add_u64 v[174:175], v[174:175], 0, s[40:41]
	s_mov_b32 m0, s9
	ds_read_b128 v[204:207], v232
	ds_read_b128 v[208:211], v232 offset:1024
	ds_read_b128 v[212:215], v232 offset:2048
	ds_read_b128 v[232:235], v232 offset:3072
	global_load_lds_dwordx4 v[174:175], off
	v_lshl_add_u64 v[174:175], v[216:217], 0, s[40:41]
	s_add_i32 m0, s9, 0x2000
	s_nop 0
	global_load_lds_dwordx4 v[174:175], off
	s_barrier
	s_setprio 1
	s_waitcnt lgkmcnt(3)
	v_mfma_f32_16x16x32_bf16 v[112:115], v[204:207], v[158:161], v[112:115]
	s_waitcnt lgkmcnt(1)
	v_mfma_f32_16x16x32_bf16 v[104:107], v[212:215], v[158:161], v[104:107]
	v_mfma_f32_16x16x32_bf16 v[96:99], v[204:207], v[166:169], v[96:99]
	v_mfma_f32_16x16x32_bf16 v[88:91], v[212:215], v[166:169], v[88:91]
	v_mfma_f32_16x16x32_bf16 v[80:83], v[204:207], v[188:191], v[80:83]
	v_mfma_f32_16x16x32_bf16 v[72:75], v[212:215], v[188:191], v[72:75]
	v_mfma_f32_16x16x32_bf16 v[68:71], v[204:207], v[196:199], v[68:71]
	v_mfma_f32_16x16x32_bf16 v[64:67], v[212:215], v[196:199], v[64:67]
	v_mfma_f32_16x16x32_bf16 v[112:115], v[208:211], v[162:165], v[112:115]
	s_waitcnt lgkmcnt(0)
	v_mfma_f32_16x16x32_bf16 v[104:107], v[232:235], v[162:165], v[104:107]
	v_mfma_f32_16x16x32_bf16 v[96:99], v[208:211], v[170:173], v[96:99]
	v_mfma_f32_16x16x32_bf16 v[88:91], v[232:235], v[170:173], v[88:91]
	v_mfma_f32_16x16x32_bf16 v[80:83], v[208:211], v[192:195], v[80:83]
	v_mfma_f32_16x16x32_bf16 v[72:75], v[232:235], v[192:195], v[72:75]
	v_mfma_f32_16x16x32_bf16 v[68:71], v[208:211], v[200:203], v[68:71]
	v_mfma_f32_16x16x32_bf16 v[64:67], v[232:235], v[200:203], v[64:67]
	s_setprio 0
	s_mov_b32 m0, s82
	v_lshl_add_u64 v[174:175], v[236:237], 0, s[40:41]
	s_barrier
	ds_read_b128 v[158:161], v145 offset:49152
	ds_read_b128 v[162:165], v145 offset:50176
	ds_read_b128 v[166:169], v145 offset:51200
	ds_read_b128 v[170:173], v145 offset:52224
	ds_read_b128 v[188:191], v145 offset:53248
	ds_read_b128 v[192:195], v145 offset:54272
	ds_read_b128 v[196:199], v145 offset:55296
	ds_read_b128 v[200:203], v145 offset:56320
	global_load_lds_dwordx4 v[174:175], off
	v_lshl_add_u64 v[174:175], v[238:239], 0, s[40:41]
	s_mov_b32 m0, s83
	s_nop 0
	global_load_lds_dwordx4 v[174:175], off
	s_barrier
	s_setprio 1
	s_waitcnt lgkmcnt(7)
	v_mfma_f32_16x16x32_bf16 v[60:63], v[138:141], v[158:161], v[60:63]
	v_mfma_f32_16x16x32_bf16 v[56:59], v[150:153], v[158:161], v[56:59]
	s_waitcnt lgkmcnt(5)
	v_mfma_f32_16x16x32_bf16 v[52:55], v[138:141], v[166:169], v[52:55]
	v_mfma_f32_16x16x32_bf16 v[44:47], v[150:153], v[166:169], v[44:47]
	s_waitcnt lgkmcnt(3)
	v_mfma_f32_16x16x32_bf16 v[36:39], v[138:141], v[188:191], v[36:39]
	v_mfma_f32_16x16x32_bf16 v[28:31], v[150:153], v[188:191], v[28:31]
	s_waitcnt lgkmcnt(1)
	v_mfma_f32_16x16x32_bf16 v[20:23], v[138:141], v[196:199], v[20:23]
	v_mfma_f32_16x16x32_bf16 v[12:15], v[150:153], v[196:199], v[12:15]
	v_mfma_f32_16x16x32_bf16 v[60:63], v[146:149], v[162:165], v[60:63]
	v_mfma_f32_16x16x32_bf16 v[56:59], v[154:157], v[162:165], v[56:59]
	v_mfma_f32_16x16x32_bf16 v[52:55], v[146:149], v[170:173], v[52:55]
	v_mfma_f32_16x16x32_bf16 v[44:47], v[154:157], v[170:173], v[44:47]
	v_mfma_f32_16x16x32_bf16 v[36:39], v[146:149], v[192:195], v[36:39]
	v_mfma_f32_16x16x32_bf16 v[28:31], v[154:157], v[192:195], v[28:31]
	s_waitcnt lgkmcnt(0)
	v_mfma_f32_16x16x32_bf16 v[20:23], v[146:149], v[200:203], v[20:23]
	v_mfma_f32_16x16x32_bf16 v[12:15], v[154:157], v[200:203], v[12:15]
	s_setprio 0
	s_barrier
	s_add_u32 s6, s6, 0x80080
	s_addc_u32 s7, s7, 0
	s_add_i32 s8, s8, s77
	v_lshl_add_u64 v[138:139], s[6:7], 0, v[176:177]
	s_mov_b32 m0, s8
	s_nop 0
	global_load_lds_dwordx4 v[138:139], off
	v_lshl_add_u64 v[138:139], s[6:7], 0, v[132:133]
	s_add_i32 m0, s8, 0x2000
	s_nop 0
	global_load_lds_dwordx4 v[138:139], off
	s_waitcnt vmcnt(6)
	s_barrier
	s_setprio 1
	v_mfma_f32_16x16x32_bf16 v[48:51], v[204:207], v[158:161], v[48:51]
	v_mfma_f32_16x16x32_bf16 v[40:43], v[212:215], v[158:161], v[40:43]
	v_mfma_f32_16x16x32_bf16 v[32:35], v[204:207], v[166:169], v[32:35]
	v_mfma_f32_16x16x32_bf16 v[24:27], v[212:215], v[166:169], v[24:27]
	v_mfma_f32_16x16x32_bf16 v[16:19], v[204:207], v[188:191], v[16:19]
	v_mfma_f32_16x16x32_bf16 v[8:11], v[212:215], v[188:191], v[8:11]
	v_mfma_f32_16x16x32_bf16 v[4:7], v[204:207], v[196:199], v[4:7]
	v_mfma_f32_16x16x32_bf16 v[0:3], v[212:215], v[196:199], v[0:3]
	v_mfma_f32_16x16x32_bf16 v[48:51], v[208:211], v[162:165], v[48:51]
	v_mfma_f32_16x16x32_bf16 v[40:43], v[232:235], v[162:165], v[40:43]
	v_mfma_f32_16x16x32_bf16 v[32:35], v[208:211], v[170:173], v[32:35]
	v_mfma_f32_16x16x32_bf16 v[24:27], v[232:235], v[170:173], v[24:27]
	v_mfma_f32_16x16x32_bf16 v[16:19], v[208:211], v[192:195], v[16:19]
	v_mfma_f32_16x16x32_bf16 v[8:11], v[232:235], v[192:195], v[8:11]
	v_mfma_f32_16x16x32_bf16 v[4:7], v[208:211], v[200:203], v[4:7]
	v_mfma_f32_16x16x32_bf16 v[0:3], v[232:235], v[200:203], v[0:3]
	s_setprio 0
	s_add_i32 s72, s72, 2
	s_add_u32 s4, s4, 0x100
	s_addc_u32 s5, s5, 0
	s_add_u32 s70, s70, 0x100
	s_addc_u32 s71, s71, 0
	s_cmp_lt_u32 s72, 30
	s_barrier
	s_cbranch_scc1 .LBB0_505
	v_mov_b32_e32 v147, v142
	v_mov_b32_e32 v146, v143
	s_cmp_lt_i32 s16, 12
	s_mov_b64 s[4:5], -1
	s_cbranch_scc1 .LBB0_1052
	s_lshl_b32 s4, s18, 8
	s_add_i32 s4, s4, s80
	v_add_u32_e32 v149, s4, v147
	s_lshl_b32 s4, s16, 8
	s_add_i32 s4, s84, s4
	v_lshl_add_u32 v138, v146, 3, s4
	v_mad_i64_i32 v[140:141], s[4:5], v149, s97, 0
	v_cmp_gt_i32_e32 vcc, s34, v138
	s_and_saveexec_b64 s[10:11], vcc
	s_cbranch_execz .LBB0_541
	v_cmp_lt_i32_e64 s[8:9], 63, v138
	v_cmp_gt_u32_e64 s[4:5], s93, v138
	v_cmp_gt_u32_e64 s[6:7], s96, v138
	s_and_saveexec_b64 s[70:71], s[8:9]
	s_xor_b64 s[70:71], exec, s[70:71]
	s_cbranch_execz .LBB0_510
	v_mul_f32_e32 v139, 0xbfb8aa3b, v124
	v_exp_f32_e32 v139, v139
	s_nop 0
	v_add_f32_e32 v139, 1.0, v139
	v_rcp_f32_e32 v139, v139
	s_nop 0
	v_cndmask_b32_e64 v139, 0, v139, s[6:7]
	v_cndmask_b32_e64 v139, v139, v124, s[4:5]
	s_andn2_saveexec_b64 s[70:71], s[70:71]
	s_cbranch_execz .LBB0_512
	s_branch .LBB0_511

.LBB0_1114:
	s_add_i32 vcc_hi, s66, 2
	s_add_u32 s28, s64, 0x80
	s_addc_u32 s29, s65, 0
	s_add_i32 s88, 0, 0x10000
	v_add_u32_e32 v140, s88, v194
	ds_read_b128 v[128:131], v140
	ds_read_b128 v[132:135], v140 offset:1024
	ds_read_b128 v[136:139], v140 offset:2048
	ds_read_b128 v[140:143], v140 offset:3072
	s_cmp_eq_u32 s85, s66
	s_cselect_b32 s66, s4, s28
	s_cselect_b32 s67, s5, s29
	s_cselect_b32 s69, s7, vcc_lo
	s_cselect_b32 s68, s6, s91
	v_lshl_add_u64 v[174:175], s[64:65], 0, v[158:159]
	s_add_i32 m0, s70, 0xc000
	ds_read_b128 v[144:147], v195
	ds_read_b128 v[148:151], v195 offset:1024
	ds_read_b128 v[162:165], v195 offset:2048
	ds_read_b128 v[166:169], v195 offset:3072
	ds_read_b128 v[170:173], v195 offset:4096
	ds_read_b128 v[188:191], v195 offset:5120
	ds_read_b128 v[196:199], v195 offset:6144
	ds_read_b128 v[200:203], v195 offset:7168
	global_load_lds_dwordx4 v[174:175], off
	v_lshl_add_u64 v[174:175], s[64:65], 0, v[160:161]
	s_add_i32 m0, s70, 0xe000
	s_nop 0
	global_load_lds_dwordx4 v[174:175], off
	s_waitcnt lgkmcnt(8)
	s_barrier
	s_setprio 1
	s_waitcnt lgkmcnt(7)
	v_mfma_f32_16x16x32_bf16 v[124:127], v[128:131], v[144:147], v[124:127]
	v_mfma_f32_16x16x32_bf16 v[120:123], v[136:139], v[144:147], v[120:123]
	s_waitcnt lgkmcnt(5)
	v_mfma_f32_16x16x32_bf16 v[108:111], v[128:131], v[162:165], v[108:111]
	v_mfma_f32_16x16x32_bf16 v[104:107], v[136:139], v[162:165], v[104:107]
	s_waitcnt lgkmcnt(3)
	v_mfma_f32_16x16x32_bf16 v[92:95], v[128:131], v[170:173], v[92:95]
	v_mfma_f32_16x16x32_bf16 v[88:91], v[136:139], v[170:173], v[88:91]
	s_waitcnt lgkmcnt(1)
	v_mfma_f32_16x16x32_bf16 v[76:79], v[128:131], v[196:199], v[76:79]
	v_mfma_f32_16x16x32_bf16 v[72:75], v[136:139], v[196:199], v[72:75]
	v_mfma_f32_16x16x32_bf16 v[124:127], v[132:135], v[148:151], v[124:127]
	v_mfma_f32_16x16x32_bf16 v[120:123], v[140:143], v[148:151], v[120:123]
	v_mfma_f32_16x16x32_bf16 v[108:111], v[132:135], v[166:169], v[108:111]
	v_mfma_f32_16x16x32_bf16 v[104:107], v[140:143], v[166:169], v[104:107]
	v_mfma_f32_16x16x32_bf16 v[92:95], v[132:135], v[188:191], v[92:95]
	v_mfma_f32_16x16x32_bf16 v[88:91], v[140:143], v[188:191], v[88:91]
	s_waitcnt lgkmcnt(0)
	v_mfma_f32_16x16x32_bf16 v[76:79], v[132:135], v[200:203], v[76:79]
	v_mfma_f32_16x16x32_bf16 v[72:75], v[140:143], v[200:203], v[72:75]
	s_setprio 0
	s_barrier
	s_add_i32 s28, 0, 0x14000
	v_add_u32_e32 v174, s28, v194
	s_add_i32 s29, s88, s47
	ds_read_b128 v[204:207], v174
	ds_read_b128 v[208:211], v174 offset:1024
	ds_read_b128 v[212:215], v174 offset:2048
	ds_read_b128 v[232:235], v174 offset:3072
	v_lshl_add_u64 v[174:175], s[68:69], 0, v[176:177]
	s_mov_b32 m0, s29
	v_lshl_add_u64 v[216:217], s[68:69], 0, v[156:157]
	global_load_lds_dwordx4 v[174:175], off
	s_add_i32 m0, s29, 0x2000
	s_nop 0
	global_load_lds_dwordx4 v[216:217], off
	s_barrier
	s_setprio 1
	s_waitcnt lgkmcnt(3)
	v_mfma_f32_16x16x32_bf16 v[116:119], v[204:207], v[144:147], v[116:119]
	s_waitcnt lgkmcnt(1)
	v_mfma_f32_16x16x32_bf16 v[112:115], v[212:215], v[144:147], v[112:115]
	v_mfma_f32_16x16x32_bf16 v[100:103], v[204:207], v[162:165], v[100:103]
	v_mfma_f32_16x16x32_bf16 v[96:99], v[212:215], v[162:165], v[96:99]
	v_mfma_f32_16x16x32_bf16 v[84:87], v[204:207], v[170:173], v[84:87]
	v_mfma_f32_16x16x32_bf16 v[80:83], v[212:215], v[170:173], v[80:83]
	v_mfma_f32_16x16x32_bf16 v[68:71], v[204:207], v[196:199], v[68:71]
	v_mfma_f32_16x16x32_bf16 v[64:67], v[212:215], v[196:199], v[64:67]
	v_mfma_f32_16x16x32_bf16 v[116:119], v[208:211], v[148:151], v[116:119]
	s_waitcnt lgkmcnt(0)
	v_mfma_f32_16x16x32_bf16 v[112:115], v[232:235], v[148:151], v[112:115]
	v_mfma_f32_16x16x32_bf16 v[100:103], v[208:211], v[166:169], v[100:103]
	v_mfma_f32_16x16x32_bf16 v[96:99], v[232:235], v[166:169], v[96:99]
	v_mfma_f32_16x16x32_bf16 v[84:87], v[208:211], v[188:191], v[84:87]
	v_mfma_f32_16x16x32_bf16 v[80:83], v[232:235], v[188:191], v[80:83]
	v_mfma_f32_16x16x32_bf16 v[68:71], v[208:211], v[200:203], v[68:71]
	v_mfma_f32_16x16x32_bf16 v[64:67], v[232:235], v[200:203], v[64:67]
	s_setprio 0
	s_mov_b32 m0, s70
	v_lshl_add_u64 v[236:237], s[66:67], 0, v[152:153]
	s_barrier
	ds_read_b128 v[144:147], v195 offset:16384
	ds_read_b128 v[148:151], v195 offset:17408
	ds_read_b128 v[162:165], v195 offset:18432
	ds_read_b128 v[166:169], v195 offset:19456
	ds_read_b128 v[170:173], v195 offset:20480
	ds_read_b128 v[188:191], v195 offset:21504
	ds_read_b128 v[196:199], v195 offset:22528
	ds_read_b128 v[200:203], v195 offset:23552
	global_load_lds_dwordx4 v[236:237], off
	v_lshl_add_u64 v[238:239], s[66:67], 0, v[154:155]
	s_mov_b32 m0, s71
	s_nop 0
	global_load_lds_dwordx4 v[238:239], off
	s_barrier
	s_setprio 1
	s_waitcnt lgkmcnt(7)
	v_mfma_f32_16x16x32_bf16 v[60:63], v[128:131], v[144:147], v[60:63]
	v_mfma_f32_16x16x32_bf16 v[56:59], v[136:139], v[144:147], v[56:59]
	s_waitcnt lgkmcnt(5)
	v_mfma_f32_16x16x32_bf16 v[44:47], v[128:131], v[162:165], v[44:47]
	v_mfma_f32_16x16x32_bf16 v[40:43], v[136:139], v[162:165], v[40:43]
	s_waitcnt lgkmcnt(3)
	v_mfma_f32_16x16x32_bf16 v[28:31], v[128:131], v[170:173], v[28:31]
	v_mfma_f32_16x16x32_bf16 v[24:27], v[136:139], v[170:173], v[24:27]
	s_waitcnt lgkmcnt(1)
	v_mfma_f32_16x16x32_bf16 v[12:15], v[128:131], v[196:199], v[12:15]
	v_mfma_f32_16x16x32_bf16 v[8:11], v[136:139], v[196:199], v[8:11]
	v_mfma_f32_16x16x32_bf16 v[60:63], v[132:135], v[148:151], v[60:63]
	v_mfma_f32_16x16x32_bf16 v[56:59], v[140:143], v[148:151], v[56:59]
	v_mfma_f32_16x16x32_bf16 v[44:47], v[132:135], v[166:169], v[44:47]
	v_mfma_f32_16x16x32_bf16 v[40:43], v[140:143], v[166:169], v[40:43]
	v_mfma_f32_16x16x32_bf16 v[28:31], v[132:135], v[188:191], v[28:31]
	v_mfma_f32_16x16x32_bf16 v[24:27], v[140:143], v[188:191], v[24:27]
	s_waitcnt lgkmcnt(0)
	v_mfma_f32_16x16x32_bf16 v[12:15], v[132:135], v[200:203], v[12:15]
	v_mfma_f32_16x16x32_bf16 v[8:11], v[140:143], v[200:203], v[8:11]
	s_setprio 0
	s_barrier
	s_add_u32 s68, s68, s58
	s_addc_u32 s69, s69, 0
	s_add_i32 s28, s28, s47
	v_lshl_add_u64 v[240:241], s[68:69], 0, v[176:177]
	s_mov_b32 m0, s28
	v_lshl_add_u64 v[242:243], s[68:69], 0, v[156:157]
	global_load_lds_dwordx4 v[240:241], off
	s_add_i32 m0, s28, 0x2000
	s_nop 0
	global_load_lds_dwordx4 v[242:243], off
	s_waitcnt vmcnt(6)
	s_barrier
	s_setprio 1
	v_mfma_f32_16x16x32_bf16 v[52:55], v[204:207], v[144:147], v[52:55]
	v_mfma_f32_16x16x32_bf16 v[48:51], v[212:215], v[144:147], v[48:51]
	v_mfma_f32_16x16x32_bf16 v[36:39], v[204:207], v[162:165], v[36:39]
	v_mfma_f32_16x16x32_bf16 v[32:35], v[212:215], v[162:165], v[32:35]
	v_mfma_f32_16x16x32_bf16 v[20:23], v[204:207], v[170:173], v[20:23]
	v_mfma_f32_16x16x32_bf16 v[16:19], v[212:215], v[170:173], v[16:19]
	v_mfma_f32_16x16x32_bf16 v[4:7], v[204:207], v[196:199], v[4:7]
	v_mfma_f32_16x16x32_bf16 v[0:3], v[212:215], v[196:199], v[0:3]
	v_mfma_f32_16x16x32_bf16 v[52:55], v[208:211], v[148:151], v[52:55]
	v_mfma_f32_16x16x32_bf16 v[48:51], v[232:235], v[148:151], v[48:51]
	v_mfma_f32_16x16x32_bf16 v[36:39], v[208:211], v[166:169], v[36:39]
	v_mfma_f32_16x16x32_bf16 v[32:35], v[232:235], v[166:169], v[32:35]
	v_mfma_f32_16x16x32_bf16 v[20:23], v[208:211], v[188:191], v[20:23]
	v_mfma_f32_16x16x32_bf16 v[16:19], v[232:235], v[188:191], v[16:19]
	v_mfma_f32_16x16x32_bf16 v[4:7], v[208:211], v[200:203], v[4:7]
	v_mfma_f32_16x16x32_bf16 v[0:3], v[232:235], v[200:203], v[0:3]
	s_setprio 0
	s_add_i32 s28, 0, 0x18000
	v_add_u32_e32 v140, s28, v194
	s_barrier
	ds_read_b128 v[128:131], v140
	ds_read_b128 v[132:135], v140 offset:1024
	ds_read_b128 v[136:139], v140 offset:2048
	ds_read_b128 v[140:143], v140 offset:3072
	s_add_u32 s66, s66, s58
	s_addc_u32 s67, s67, 0
	s_mov_b32 m0, s72
	v_lshl_add_u64 v[204:205], s[66:67], 0, v[152:153]
	ds_read_b128 v[144:147], v195 offset:32768
	ds_read_b128 v[148:151], v195 offset:33792
	ds_read_b128 v[162:165], v195 offset:34816
	ds_read_b128 v[166:169], v195 offset:35840
	ds_read_b128 v[170:173], v195 offset:36864
	ds_read_b128 v[188:191], v195 offset:37888
	ds_read_b128 v[196:199], v195 offset:38912
	ds_read_b128 v[200:203], v195 offset:39936
	global_load_lds_dwordx4 v[204:205], off
	v_lshl_add_u64 v[204:205], s[66:67], 0, v[154:155]
	s_mov_b32 m0, s73
	s_nop 0
	global_load_lds_dwordx4 v[204:205], off
	s_waitcnt lgkmcnt(8)
	s_barrier
	s_setprio 1
	s_waitcnt lgkmcnt(7)
	v_mfma_f32_16x16x32_bf16 v[124:127], v[128:131], v[144:147], v[124:127]
	v_mfma_f32_16x16x32_bf16 v[120:123], v[136:139], v[144:147], v[120:123]
	s_waitcnt lgkmcnt(5)
	v_mfma_f32_16x16x32_bf16 v[108:111], v[128:131], v[162:165], v[108:111]
	v_mfma_f32_16x16x32_bf16 v[104:107], v[136:139], v[162:165], v[104:107]
	s_waitcnt lgkmcnt(3)
	v_mfma_f32_16x16x32_bf16 v[92:95], v[128:131], v[170:173], v[92:95]
	v_mfma_f32_16x16x32_bf16 v[88:91], v[136:139], v[170:173], v[88:91]
	s_waitcnt lgkmcnt(1)
	v_mfma_f32_16x16x32_bf16 v[76:79], v[128:131], v[196:199], v[76:79]
	v_mfma_f32_16x16x32_bf16 v[72:75], v[136:139], v[196:199], v[72:75]
	v_mfma_f32_16x16x32_bf16 v[124:127], v[132:135], v[148:151], v[124:127]
	v_mfma_f32_16x16x32_bf16 v[120:123], v[140:143], v[148:151], v[120:123]
	v_mfma_f32_16x16x32_bf16 v[108:111], v[132:135], v[166:169], v[108:111]
	v_mfma_f32_16x16x32_bf16 v[104:107], v[140:143], v[166:169], v[104:107]
	v_mfma_f32_16x16x32_bf16 v[92:95], v[132:135], v[188:191], v[92:95]
	v_mfma_f32_16x16x32_bf16 v[88:91], v[140:143], v[188:191], v[88:91]
	s_waitcnt lgkmcnt(0)
	v_mfma_f32_16x16x32_bf16 v[76:79], v[132:135], v[200:203], v[76:79]
	v_mfma_f32_16x16x32_bf16 v[72:75], v[140:143], v[200:203], v[72:75]
	s_setprio 0
	s_barrier
	s_add_i32 s29, 0, 0x1c000
	s_add_i32 s28, s28, s47
	v_add_u32_e32 v232, s29, v194
	v_lshl_add_u64 v[174:175], v[174:175], 0, s[40:41]
	s_mov_b32 m0, s28
	ds_read_b128 v[204:207], v232
	ds_read_b128 v[208:211], v232 offset:1024
	ds_read_b128 v[212:215], v232 offset:2048
	ds_read_b128 v[232:235], v232 offset:3072
	global_load_lds_dwordx4 v[174:175], off
	v_lshl_add_u64 v[174:175], v[216:217], 0, s[40:41]
	s_add_i32 m0, s28, 0x2000
	s_nop 0
	global_load_lds_dwordx4 v[174:175], off
	s_barrier
	s_setprio 1
	s_waitcnt lgkmcnt(3)
	v_mfma_f32_16x16x32_bf16 v[116:119], v[204:207], v[144:147], v[116:119]
	s_waitcnt lgkmcnt(1)
	v_mfma_f32_16x16x32_bf16 v[112:115], v[212:215], v[144:147], v[112:115]
	v_mfma_f32_16x16x32_bf16 v[100:103], v[204:207], v[162:165], v[100:103]
	v_mfma_f32_16x16x32_bf16 v[96:99], v[212:215], v[162:165], v[96:99]
	v_mfma_f32_16x16x32_bf16 v[84:87], v[204:207], v[170:173], v[84:87]
	v_mfma_f32_16x16x32_bf16 v[80:83], v[212:215], v[170:173], v[80:83]
	v_mfma_f32_16x16x32_bf16 v[68:71], v[204:207], v[196:199], v[68:71]
	v_mfma_f32_16x16x32_bf16 v[64:67], v[212:215], v[196:199], v[64:67]
	v_mfma_f32_16x16x32_bf16 v[116:119], v[208:211], v[148:151], v[116:119]
	s_waitcnt lgkmcnt(0)
	v_mfma_f32_16x16x32_bf16 v[112:115], v[232:235], v[148:151], v[112:115]
	v_mfma_f32_16x16x32_bf16 v[100:103], v[208:211], v[166:169], v[100:103]
	v_mfma_f32_16x16x32_bf16 v[96:99], v[232:235], v[166:169], v[96:99]
	v_mfma_f32_16x16x32_bf16 v[84:87], v[208:211], v[188:191], v[84:87]
	v_mfma_f32_16x16x32_bf16 v[80:83], v[232:235], v[188:191], v[80:83]
	v_mfma_f32_16x16x32_bf16 v[68:71], v[208:211], v[200:203], v[68:71]
	v_mfma_f32_16x16x32_bf16 v[64:67], v[232:235], v[200:203], v[64:67]
	s_setprio 0
	s_mov_b32 m0, s74
	v_lshl_add_u64 v[174:175], v[236:237], 0, s[40:41]
	s_barrier
	ds_read_b128 v[144:147], v195 offset:49152
	ds_read_b128 v[148:151], v195 offset:50176
	ds_read_b128 v[162:165], v195 offset:51200
	ds_read_b128 v[166:169], v195 offset:52224
	ds_read_b128 v[170:173], v195 offset:53248
	ds_read_b128 v[188:191], v195 offset:54272
	ds_read_b128 v[196:199], v195 offset:55296
	ds_read_b128 v[200:203], v195 offset:56320
	global_load_lds_dwordx4 v[174:175], off
	v_lshl_add_u64 v[174:175], v[238:239], 0, s[40:41]
	s_mov_b32 m0, s75
	s_nop 0
	global_load_lds_dwordx4 v[174:175], off
	s_barrier
	s_setprio 1
	s_waitcnt lgkmcnt(7)
	v_mfma_f32_16x16x32_bf16 v[60:63], v[128:131], v[144:147], v[60:63]
	v_mfma_f32_16x16x32_bf16 v[56:59], v[136:139], v[144:147], v[56:59]
	s_waitcnt lgkmcnt(5)
	v_mfma_f32_16x16x32_bf16 v[44:47], v[128:131], v[162:165], v[44:47]
	v_mfma_f32_16x16x32_bf16 v[40:43], v[136:139], v[162:165], v[40:43]
	s_waitcnt lgkmcnt(3)
	v_mfma_f32_16x16x32_bf16 v[28:31], v[128:131], v[170:173], v[28:31]
	v_mfma_f32_16x16x32_bf16 v[24:27], v[136:139], v[170:173], v[24:27]
	s_waitcnt lgkmcnt(1)
	v_mfma_f32_16x16x32_bf16 v[12:15], v[128:131], v[196:199], v[12:15]
	v_mfma_f32_16x16x32_bf16 v[8:11], v[136:139], v[196:199], v[8:11]
	v_mfma_f32_16x16x32_bf16 v[60:63], v[132:135], v[148:151], v[60:63]
	v_mfma_f32_16x16x32_bf16 v[56:59], v[140:143], v[148:151], v[56:59]
	v_mfma_f32_16x16x32_bf16 v[44:47], v[132:135], v[166:169], v[44:47]
	v_mfma_f32_16x16x32_bf16 v[40:43], v[140:143], v[166:169], v[40:43]
	v_mfma_f32_16x16x32_bf16 v[28:31], v[132:135], v[188:191], v[28:31]
	v_mfma_f32_16x16x32_bf16 v[24:27], v[140:143], v[188:191], v[24:27]
	s_waitcnt lgkmcnt(0)
	v_mfma_f32_16x16x32_bf16 v[12:15], v[132:135], v[200:203], v[12:15]
	v_mfma_f32_16x16x32_bf16 v[8:11], v[140:143], v[200:203], v[8:11]
	s_setprio 0
	s_barrier
	s_add_i32 s28, s29, s47
	v_lshl_add_u64 v[128:129], v[240:241], 0, s[40:41]
	s_mov_b32 m0, s28
	s_nop 0
	global_load_lds_dwordx4 v[128:129], off
	v_lshl_add_u64 v[128:129], v[242:243], 0, s[40:41]
	s_add_i32 m0, s28, 0x2000
	s_nop 0
	global_load_lds_dwordx4 v[128:129], off
	s_waitcnt vmcnt(6)
	s_barrier
	s_setprio 1
	v_mfma_f32_16x16x32_bf16 v[52:55], v[204:207], v[144:147], v[52:55]
	v_mfma_f32_16x16x32_bf16 v[48:51], v[212:215], v[144:147], v[48:51]
	v_mfma_f32_16x16x32_bf16 v[36:39], v[204:207], v[162:165], v[36:39]
	v_mfma_f32_16x16x32_bf16 v[32:35], v[212:215], v[162:165], v[32:35]
	v_mfma_f32_16x16x32_bf16 v[20:23], v[204:207], v[170:173], v[20:23]
	v_mfma_f32_16x16x32_bf16 v[16:19], v[212:215], v[170:173], v[16:19]
	v_mfma_f32_16x16x32_bf16 v[4:7], v[204:207], v[196:199], v[4:7]
	v_mfma_f32_16x16x32_bf16 v[0:3], v[212:215], v[196:199], v[0:3]
	v_mfma_f32_16x16x32_bf16 v[52:55], v[208:211], v[148:151], v[52:55]
	v_mfma_f32_16x16x32_bf16 v[48:51], v[232:235], v[148:151], v[48:51]
	v_mfma_f32_16x16x32_bf16 v[36:39], v[208:211], v[166:169], v[36:39]
	v_mfma_f32_16x16x32_bf16 v[32:35], v[232:235], v[166:169], v[32:35]
	v_mfma_f32_16x16x32_bf16 v[20:23], v[208:211], v[188:191], v[20:23]
	v_mfma_f32_16x16x32_bf16 v[16:19], v[232:235], v[188:191], v[16:19]
	v_mfma_f32_16x16x32_bf16 v[4:7], v[208:211], v[200:203], v[4:7]
	v_mfma_f32_16x16x32_bf16 v[0:3], v[232:235], v[200:203], v[0:3]
	s_setprio 0
	s_add_u32 s64, s64, 0x100
	s_addc_u32 s65, s65, 0
	s_add_u32 s91, s91, 0x100
	s_addc_u32 vcc_lo, vcc_lo, 0
	s_cmp_lt_i32 vcc_hi, s76
	s_mov_b32 s66, vcc_hi
	s_barrier
	s_cbranch_scc1 .LBB0_1114
	s_lshl_b32 s28, s84, 8
	v_mov_b32_e32 v128, v193
	v_mov_b32_e32 v129, v192
	s_add_i32 s28, s28, s78
	s_lshl_b32 s64, s24, 2
	v_add_u32_e32 v166, s28, v129
	s_lshl_b32 s28, s24, 8
	s_or_b32 s28, s28, s79
	v_lshl_add_u32 v162, v128, 3, s28
	v_ashrrev_i32_e32 v163, 31, v162
	v_lshlrev_b64 v[204:205], 1, v[162:163]
	v_ashrrev_i32_e32 v167, 31, v166
	v_lshl_add_u64 v[164:165], s[12:13], 0, v[204:205]
	v_lshlrev_b64 v[206:207], 11, v[166:167]
	v_cmp_eq_u32_e32 vcc, 0, v128
	v_lshl_add_u64 v[128:129], v[164:165], 0, v[206:207]
	global_load_dwordx4 v[196:199], v[128:129], off
	global_load_dwordx4 v[200:203], v[128:129], off offset:256
	v_add_u32_e32 v188, 16, v166
	v_ashrrev_i32_e32 v189, 31, v188
	v_add_u32_e32 v172, 32, v166
	v_lshlrev_b64 v[190:191], 11, v[188:189]
	v_ashrrev_i32_e32 v173, 31, v172
	v_add_u32_e32 v168, 48, v166
	v_lshl_add_u64 v[128:129], v[164:165], 0, v[190:191]
	v_lshlrev_b64 v[174:175], 11, v[172:173]
	v_ashrrev_i32_e32 v169, 31, v168
	global_load_dwordx4 v[148:151], v[128:129], off
	global_load_dwordx4 v[144:147], v[128:129], off offset:256
	v_lshl_add_u64 v[128:129], v[164:165], 0, v[174:175]
	v_lshlrev_b64 v[170:171], 11, v[168:169]
	global_load_dwordx4 v[140:143], v[128:129], off
	global_load_dwordx4 v[136:139], v[128:129], off offset:256
	v_lshl_add_u64 v[128:129], v[164:165], 0, v[170:171]
	global_load_dwordx4 v[132:135], v[128:129], off
	s_nop 0
	global_load_dwordx4 v[128:131], v[128:129], off offset:256
	v_lshl_add_u64 v[206:207], s[12:13], 0, v[206:207]
	v_lshl_add_u64 v[204:205], v[206:207], 0, v[204:205]
	s_ashr_i32 s65, s64, 31
	s_waitcnt vmcnt(0)
	v_lshlrev_b32_e32 v208, 16, v196
	v_and_b32_e32 v209, 0xffff0000, v196
	v_lshlrev_b32_e32 v196, 16, v197
	v_and_b32_e32 v197, 0xffff0000, v197
	v_lshlrev_b32_e32 v210, 16, v198
	v_and_b32_e32 v211, 0xffff0000, v198
	v_lshlrev_b32_e32 v198, 16, v199
	v_and_b32_e32 v199, 0xffff0000, v199
	v_pk_fma_f32 v[126:127], s[62:63], v[126:127], v[196:197]
	v_pk_fma_f32 v[124:125], s[10:11], v[124:125], v[208:209]
	v_pk_fma_f32 v[196:197], s[62:63], v[122:123], v[198:199]
	v_pk_fma_f32 v[198:199], s[10:11], v[120:121], v[210:211]
	v_cvt_pk_bf16_f32 v120, v124, v125
	v_cvt_pk_bf16_f32 v121, v126, v127
	s_nop 0
	v_cvt_pk_bf16_f32 v122, v198, v199
	v_cvt_pk_bf16_f32 v123, v196, v197
	global_store_dwordx4 v[204:205], v[120:123], off
	s_nop 1
	v_pk_mul_f32 v[120:121], v[198:199], v[198:199]
	v_pk_mul_f32 v[122:123], v[196:197], v[196:197]
	v_pk_fma_f32 v[120:121], v[124:125], v[124:125], v[120:121]
	v_pk_fma_f32 v[122:123], v[126:127], v[126:127], v[122:123]
	v_add_f32_e32 v120, v120, v121
	v_add_f32_e32 v121, v122, v123
	v_add_f32_e32 v196, v120, v121
	v_lshlrev_b32_e32 v120, 16, v200
	v_and_b32_e32 v121, 0xffff0000, v200
	v_lshlrev_b32_e32 v122, 16, v201
	v_and_b32_e32 v123, 0xffff0000, v201
	v_lshlrev_b32_e32 v124, 16, v202
	v_and_b32_e32 v125, 0xffff0000, v202
	v_lshlrev_b32_e32 v126, 16, v203
	v_and_b32_e32 v127, 0xffff0000, v203
	v_pk_fma_f32 v[118:119], s[62:63], v[118:119], v[122:123]
	v_pk_fma_f32 v[116:117], s[10:11], v[116:117], v[120:121]
	v_pk_fma_f32 v[120:121], s[62:63], v[114:115], v[126:127]
	v_pk_fma_f32 v[122:123], s[10:11], v[112:113], v[124:125]
	v_cvt_pk_bf16_f32 v112, v116, v117
	v_cvt_pk_bf16_f32 v113, v118, v119
	s_nop 0
	v_cvt_pk_bf16_f32 v114, v122, v123
	v_cvt_pk_bf16_f32 v115, v120, v121
	global_store_dwordx4 v[204:205], v[112:115], off offset:256
	s_nop 1
	v_pk_mul_f32 v[112:113], v[122:123], v[122:123]
	v_pk_mul_f32 v[114:115], v[120:121], v[120:121]
	v_pk_fma_f32 v[112:113], v[116:117], v[116:117], v[112:113]
	v_pk_fma_f32 v[114:115], v[118:119], v[118:119], v[114:115]
	v_add_f32_e32 v112, v112, v113
	v_add_f32_e32 v113, v114, v115
	v_add_f32_e32 v112, v112, v113
	v_add_f32_e32 v112, v196, v112
	ds_bpermute_b32 v113, v219, v112
	s_waitcnt lgkmcnt(0)
	v_add_f32_e32 v112, v112, v113
	ds_bpermute_b32 v113, v218, v112
	s_and_saveexec_b64 s[66:67], vcc
	s_cbranch_execz .LBB0_1117
	v_lshlrev_b64 v[114:115], 6, v[166:167]
	v_lshl_add_u64 v[114:115], s[8:9], 0, v[114:115]
	v_lshl_add_u64 v[114:115], s[64:65], 2, v[114:115]
	s_lshl_b32 s24, s77, 2
	v_lshl_add_u64 v[114:115], v[114:115], 0, s[24:25]
	s_waitcnt lgkmcnt(0)
	v_add_f32_e32 v112, v112, v113
	global_store_dword v[114:115], v112, off

.LBB0_1282:
	s_add_i32 s81, s60, 2
	s_add_u32 s28, s58, 0x80
	s_addc_u32 s29, s59, 0
	s_add_i32 s82, 0, 0x10000
	v_add_u32_e32 v140, s82, v195
	ds_read_b128 v[128:131], v140
	ds_read_b128 v[132:135], v140 offset:1024
	ds_read_b128 v[136:139], v140 offset:2048
	ds_read_b128 v[140:143], v140 offset:3072
	s_cmp_eq_u32 s5, s60
	s_cselect_b32 s60, s56, s28
	s_cselect_b32 s61, s57, s29
	s_cselect_b32 s63, s3, s80
	s_cselect_b32 s62, s2, s21
	v_lshl_add_u64 v[174:175], s[58:59], 0, v[158:159]
	s_add_i32 m0, s66, 0xc000
	ds_read_b128 v[144:147], v196
	ds_read_b128 v[148:151], v196 offset:1024
	ds_read_b128 v[162:165], v196 offset:2048
	ds_read_b128 v[166:169], v196 offset:3072
	ds_read_b128 v[170:173], v196 offset:4096
	ds_read_b128 v[188:191], v196 offset:5120
	ds_read_b128 v[198:201], v196 offset:6144
	ds_read_b128 v[202:205], v196 offset:7168
	global_load_lds_dwordx4 v[174:175], off
	v_lshl_add_u64 v[174:175], s[58:59], 0, v[160:161]
	s_add_i32 m0, s66, 0xe000
	s_nop 0
	global_load_lds_dwordx4 v[174:175], off
	s_waitcnt lgkmcnt(8)
	s_barrier
	s_setprio 1
	s_waitcnt lgkmcnt(7)
	v_mfma_f32_16x16x32_bf16 v[124:127], v[128:131], v[144:147], v[124:127]
	v_mfma_f32_16x16x32_bf16 v[120:123], v[136:139], v[144:147], v[120:123]
	s_waitcnt lgkmcnt(5)
	v_mfma_f32_16x16x32_bf16 v[108:111], v[128:131], v[162:165], v[108:111]
	v_mfma_f32_16x16x32_bf16 v[104:107], v[136:139], v[162:165], v[104:107]
	s_waitcnt lgkmcnt(3)
	v_mfma_f32_16x16x32_bf16 v[92:95], v[128:131], v[170:173], v[92:95]
	v_mfma_f32_16x16x32_bf16 v[88:91], v[136:139], v[170:173], v[88:91]
	s_waitcnt lgkmcnt(1)
	v_mfma_f32_16x16x32_bf16 v[76:79], v[128:131], v[198:201], v[76:79]
	v_mfma_f32_16x16x32_bf16 v[72:75], v[136:139], v[198:201], v[72:75]
	v_mfma_f32_16x16x32_bf16 v[124:127], v[132:135], v[148:151], v[124:127]
	v_mfma_f32_16x16x32_bf16 v[120:123], v[140:143], v[148:151], v[120:123]
	v_mfma_f32_16x16x32_bf16 v[108:111], v[132:135], v[166:169], v[108:111]
	v_mfma_f32_16x16x32_bf16 v[104:107], v[140:143], v[166:169], v[104:107]
	v_mfma_f32_16x16x32_bf16 v[92:95], v[132:135], v[188:191], v[92:95]
	v_mfma_f32_16x16x32_bf16 v[88:91], v[140:143], v[188:191], v[88:91]
	s_waitcnt lgkmcnt(0)
	v_mfma_f32_16x16x32_bf16 v[76:79], v[132:135], v[202:205], v[76:79]
	v_mfma_f32_16x16x32_bf16 v[72:75], v[140:143], v[202:205], v[72:75]
	s_setprio 0
	s_barrier
	s_add_i32 s28, 0, 0x14000
	v_add_u32_e32 v174, s28, v195
	s_add_i32 s29, s82, s65
	ds_read_b128 v[206:209], v174
	ds_read_b128 v[210:213], v174 offset:1024
	ds_read_b128 v[214:217], v174 offset:2048
	ds_read_b128 v[232:235], v174 offset:3072
	v_lshl_add_u64 v[174:175], s[62:63], 0, v[176:177]
	s_mov_b32 m0, s29
	v_lshl_add_u64 v[236:237], s[62:63], 0, v[156:157]
	global_load_lds_dwordx4 v[174:175], off
	s_add_i32 m0, s29, 0x2000
	s_nop 0
	global_load_lds_dwordx4 v[236:237], off
	s_barrier
	s_setprio 1
	s_waitcnt lgkmcnt(3)
	v_mfma_f32_16x16x32_bf16 v[116:119], v[206:209], v[144:147], v[116:119]
	s_waitcnt lgkmcnt(1)
	v_mfma_f32_16x16x32_bf16 v[112:115], v[214:217], v[144:147], v[112:115]
	v_mfma_f32_16x16x32_bf16 v[100:103], v[206:209], v[162:165], v[100:103]
	v_mfma_f32_16x16x32_bf16 v[96:99], v[214:217], v[162:165], v[96:99]
	v_mfma_f32_16x16x32_bf16 v[84:87], v[206:209], v[170:173], v[84:87]
	v_mfma_f32_16x16x32_bf16 v[80:83], v[214:217], v[170:173], v[80:83]
	v_mfma_f32_16x16x32_bf16 v[68:71], v[206:209], v[198:201], v[68:71]
	v_mfma_f32_16x16x32_bf16 v[64:67], v[214:217], v[198:201], v[64:67]
	v_mfma_f32_16x16x32_bf16 v[116:119], v[210:213], v[148:151], v[116:119]
	s_waitcnt lgkmcnt(0)
	v_mfma_f32_16x16x32_bf16 v[112:115], v[232:235], v[148:151], v[112:115]
	v_mfma_f32_16x16x32_bf16 v[100:103], v[210:213], v[166:169], v[100:103]
	v_mfma_f32_16x16x32_bf16 v[96:99], v[232:235], v[166:169], v[96:99]
	v_mfma_f32_16x16x32_bf16 v[84:87], v[210:213], v[188:191], v[84:87]
	v_mfma_f32_16x16x32_bf16 v[80:83], v[232:235], v[188:191], v[80:83]
	v_mfma_f32_16x16x32_bf16 v[68:71], v[210:213], v[202:205], v[68:71]
	v_mfma_f32_16x16x32_bf16 v[64:67], v[232:235], v[202:205], v[64:67]
	s_setprio 0
	s_mov_b32 m0, s66
	v_lshl_add_u64 v[238:239], s[60:61], 0, v[152:153]
	s_barrier
	ds_read_b128 v[144:147], v196 offset:16384
	ds_read_b128 v[148:151], v196 offset:17408
	ds_read_b128 v[162:165], v196 offset:18432
	ds_read_b128 v[166:169], v196 offset:19456
	ds_read_b128 v[170:173], v196 offset:20480
	ds_read_b128 v[188:191], v196 offset:21504
	ds_read_b128 v[198:201], v196 offset:22528
	ds_read_b128 v[202:205], v196 offset:23552
	global_load_lds_dwordx4 v[238:239], off
	v_lshl_add_u64 v[240:241], s[60:61], 0, v[154:155]
	s_mov_b32 m0, s67
	s_nop 0
	global_load_lds_dwordx4 v[240:241], off
	s_barrier
	s_setprio 1
	s_waitcnt lgkmcnt(7)
	v_mfma_f32_16x16x32_bf16 v[60:63], v[128:131], v[144:147], v[60:63]
	v_mfma_f32_16x16x32_bf16 v[56:59], v[136:139], v[144:147], v[56:59]
	s_waitcnt lgkmcnt(5)
	v_mfma_f32_16x16x32_bf16 v[44:47], v[128:131], v[162:165], v[44:47]
	v_mfma_f32_16x16x32_bf16 v[40:43], v[136:139], v[162:165], v[40:43]
	s_waitcnt lgkmcnt(3)
	v_mfma_f32_16x16x32_bf16 v[28:31], v[128:131], v[170:173], v[28:31]
	v_mfma_f32_16x16x32_bf16 v[24:27], v[136:139], v[170:173], v[24:27]
	s_waitcnt lgkmcnt(1)
	v_mfma_f32_16x16x32_bf16 v[12:15], v[128:131], v[198:201], v[12:15]
	v_mfma_f32_16x16x32_bf16 v[8:11], v[136:139], v[198:201], v[8:11]
	v_mfma_f32_16x16x32_bf16 v[60:63], v[132:135], v[148:151], v[60:63]
	v_mfma_f32_16x16x32_bf16 v[56:59], v[140:143], v[148:151], v[56:59]
	v_mfma_f32_16x16x32_bf16 v[44:47], v[132:135], v[166:169], v[44:47]
	v_mfma_f32_16x16x32_bf16 v[40:43], v[140:143], v[166:169], v[40:43]
	v_mfma_f32_16x16x32_bf16 v[28:31], v[132:135], v[188:191], v[28:31]
	v_mfma_f32_16x16x32_bf16 v[24:27], v[140:143], v[188:191], v[24:27]
	s_waitcnt lgkmcnt(0)
	v_mfma_f32_16x16x32_bf16 v[12:15], v[132:135], v[202:205], v[12:15]
	v_mfma_f32_16x16x32_bf16 v[8:11], v[140:143], v[202:205], v[8:11]
	s_setprio 0
	s_barrier
	s_add_u32 s62, s62, s4
	s_addc_u32 s63, s63, 0
	s_add_i32 s28, s28, s65
	v_lshl_add_u64 v[242:243], s[62:63], 0, v[176:177]
	s_mov_b32 m0, s28
	v_lshl_add_u64 v[244:245], s[62:63], 0, v[156:157]
	global_load_lds_dwordx4 v[242:243], off
	s_add_i32 m0, s28, 0x2000
	s_nop 0
	global_load_lds_dwordx4 v[244:245], off
	s_waitcnt vmcnt(6)
	s_barrier
	s_setprio 1
	v_mfma_f32_16x16x32_bf16 v[52:55], v[206:209], v[144:147], v[52:55]
	v_mfma_f32_16x16x32_bf16 v[48:51], v[214:217], v[144:147], v[48:51]
	v_mfma_f32_16x16x32_bf16 v[36:39], v[206:209], v[162:165], v[36:39]
	v_mfma_f32_16x16x32_bf16 v[32:35], v[214:217], v[162:165], v[32:35]
	v_mfma_f32_16x16x32_bf16 v[20:23], v[206:209], v[170:173], v[20:23]
	v_mfma_f32_16x16x32_bf16 v[16:19], v[214:217], v[170:173], v[16:19]
	v_mfma_f32_16x16x32_bf16 v[4:7], v[206:209], v[198:201], v[4:7]
	v_mfma_f32_16x16x32_bf16 v[0:3], v[214:217], v[198:201], v[0:3]
	v_mfma_f32_16x16x32_bf16 v[52:55], v[210:213], v[148:151], v[52:55]
	v_mfma_f32_16x16x32_bf16 v[48:51], v[232:235], v[148:151], v[48:51]
	v_mfma_f32_16x16x32_bf16 v[36:39], v[210:213], v[166:169], v[36:39]
	v_mfma_f32_16x16x32_bf16 v[32:35], v[232:235], v[166:169], v[32:35]
	v_mfma_f32_16x16x32_bf16 v[20:23], v[210:213], v[188:191], v[20:23]
	v_mfma_f32_16x16x32_bf16 v[16:19], v[232:235], v[188:191], v[16:19]
	v_mfma_f32_16x16x32_bf16 v[4:7], v[210:213], v[202:205], v[4:7]
	v_mfma_f32_16x16x32_bf16 v[0:3], v[232:235], v[202:205], v[0:3]
	s_setprio 0
	s_add_i32 s28, 0, 0x18000
	v_add_u32_e32 v140, s28, v195
	s_barrier
	ds_read_b128 v[128:131], v140
	ds_read_b128 v[132:135], v140 offset:1024
	ds_read_b128 v[136:139], v140 offset:2048
	ds_read_b128 v[140:143], v140 offset:3072
	s_add_u32 s60, s60, s4
	s_addc_u32 s61, s61, 0
	s_mov_b32 m0, s68
	v_lshl_add_u64 v[206:207], s[60:61], 0, v[152:153]
	ds_read_b128 v[144:147], v196 offset:32768
	ds_read_b128 v[148:151], v196 offset:33792
	ds_read_b128 v[162:165], v196 offset:34816
	ds_read_b128 v[166:169], v196 offset:35840
	ds_read_b128 v[170:173], v196 offset:36864
	ds_read_b128 v[188:191], v196 offset:37888
	ds_read_b128 v[198:201], v196 offset:38912
	ds_read_b128 v[202:205], v196 offset:39936
	global_load_lds_dwordx4 v[206:207], off
	v_lshl_add_u64 v[206:207], s[60:61], 0, v[154:155]
	s_mov_b32 m0, s69
	s_nop 0
	global_load_lds_dwordx4 v[206:207], off
	s_waitcnt lgkmcnt(8)
	s_barrier
	s_setprio 1
	s_waitcnt lgkmcnt(7)
	v_mfma_f32_16x16x32_bf16 v[124:127], v[128:131], v[144:147], v[124:127]
	v_mfma_f32_16x16x32_bf16 v[120:123], v[136:139], v[144:147], v[120:123]
	s_waitcnt lgkmcnt(5)
	v_mfma_f32_16x16x32_bf16 v[108:111], v[128:131], v[162:165], v[108:111]
	v_mfma_f32_16x16x32_bf16 v[104:107], v[136:139], v[162:165], v[104:107]
	s_waitcnt lgkmcnt(3)
	v_mfma_f32_16x16x32_bf16 v[92:95], v[128:131], v[170:173], v[92:95]
	v_mfma_f32_16x16x32_bf16 v[88:91], v[136:139], v[170:173], v[88:91]
	s_waitcnt lgkmcnt(1)
	v_mfma_f32_16x16x32_bf16 v[76:79], v[128:131], v[198:201], v[76:79]
	v_mfma_f32_16x16x32_bf16 v[72:75], v[136:139], v[198:201], v[72:75]
	v_mfma_f32_16x16x32_bf16 v[124:127], v[132:135], v[148:151], v[124:127]
	v_mfma_f32_16x16x32_bf16 v[120:123], v[140:143], v[148:151], v[120:123]
	v_mfma_f32_16x16x32_bf16 v[108:111], v[132:135], v[166:169], v[108:111]
	v_mfma_f32_16x16x32_bf16 v[104:107], v[140:143], v[166:169], v[104:107]
	v_mfma_f32_16x16x32_bf16 v[92:95], v[132:135], v[188:191], v[92:95]
	v_mfma_f32_16x16x32_bf16 v[88:91], v[140:143], v[188:191], v[88:91]
	s_waitcnt lgkmcnt(0)
	v_mfma_f32_16x16x32_bf16 v[76:79], v[132:135], v[202:205], v[76:79]
	v_mfma_f32_16x16x32_bf16 v[72:75], v[140:143], v[202:205], v[72:75]
	s_setprio 0
	s_barrier
	s_add_i32 s29, 0, 0x1c000
	s_add_i32 s28, s28, s65
	v_add_u32_e32 v197, s29, v195
	v_lshl_add_u64 v[174:175], v[174:175], 0, s[40:41]
	s_mov_b32 m0, s28
	ds_read_b128 v[206:209], v197
	ds_read_b128 v[210:213], v197 offset:1024
	ds_read_b128 v[214:217], v197 offset:2048
	ds_read_b128 v[232:235], v197 offset:3072
	global_load_lds_dwordx4 v[174:175], off
	v_lshl_add_u64 v[174:175], v[236:237], 0, s[40:41]
	s_add_i32 m0, s28, 0x2000
	s_nop 0
	global_load_lds_dwordx4 v[174:175], off
	s_barrier
	s_setprio 1
	s_waitcnt lgkmcnt(3)
	v_mfma_f32_16x16x32_bf16 v[116:119], v[206:209], v[144:147], v[116:119]
	s_waitcnt lgkmcnt(1)
	v_mfma_f32_16x16x32_bf16 v[112:115], v[214:217], v[144:147], v[112:115]
	v_mfma_f32_16x16x32_bf16 v[100:103], v[206:209], v[162:165], v[100:103]
	v_mfma_f32_16x16x32_bf16 v[96:99], v[214:217], v[162:165], v[96:99]
	v_mfma_f32_16x16x32_bf16 v[84:87], v[206:209], v[170:173], v[84:87]
	v_mfma_f32_16x16x32_bf16 v[80:83], v[214:217], v[170:173], v[80:83]
	v_mfma_f32_16x16x32_bf16 v[68:71], v[206:209], v[198:201], v[68:71]
	v_mfma_f32_16x16x32_bf16 v[64:67], v[214:217], v[198:201], v[64:67]
	v_mfma_f32_16x16x32_bf16 v[116:119], v[210:213], v[148:151], v[116:119]
	s_waitcnt lgkmcnt(0)
	v_mfma_f32_16x16x32_bf16 v[112:115], v[232:235], v[148:151], v[112:115]
	v_mfma_f32_16x16x32_bf16 v[100:103], v[210:213], v[166:169], v[100:103]
	v_mfma_f32_16x16x32_bf16 v[96:99], v[232:235], v[166:169], v[96:99]
	v_mfma_f32_16x16x32_bf16 v[84:87], v[210:213], v[188:191], v[84:87]
	v_mfma_f32_16x16x32_bf16 v[80:83], v[232:235], v[188:191], v[80:83]
	v_mfma_f32_16x16x32_bf16 v[68:71], v[210:213], v[202:205], v[68:71]
	v_mfma_f32_16x16x32_bf16 v[64:67], v[232:235], v[202:205], v[64:67]
	s_setprio 0
	s_mov_b32 m0, s71
	v_lshl_add_u64 v[174:175], v[238:239], 0, s[40:41]
	s_barrier
	ds_read_b128 v[144:147], v196 offset:49152
	ds_read_b128 v[148:151], v196 offset:50176
	ds_read_b128 v[162:165], v196 offset:51200
	ds_read_b128 v[166:169], v196 offset:52224
	ds_read_b128 v[170:173], v196 offset:53248
	ds_read_b128 v[188:191], v196 offset:54272
	ds_read_b128 v[198:201], v196 offset:55296
	ds_read_b128 v[202:205], v196 offset:56320
	global_load_lds_dwordx4 v[174:175], off
	v_lshl_add_u64 v[174:175], v[240:241], 0, s[40:41]
	s_mov_b32 m0, s72
	s_nop 0
	global_load_lds_dwordx4 v[174:175], off
	s_barrier
	s_setprio 1
	s_waitcnt lgkmcnt(7)
	v_mfma_f32_16x16x32_bf16 v[60:63], v[128:131], v[144:147], v[60:63]
	v_mfma_f32_16x16x32_bf16 v[56:59], v[136:139], v[144:147], v[56:59]
	s_waitcnt lgkmcnt(5)
	v_mfma_f32_16x16x32_bf16 v[44:47], v[128:131], v[162:165], v[44:47]
	v_mfma_f32_16x16x32_bf16 v[40:43], v[136:139], v[162:165], v[40:43]
	s_waitcnt lgkmcnt(3)
	v_mfma_f32_16x16x32_bf16 v[28:31], v[128:131], v[170:173], v[28:31]
	v_mfma_f32_16x16x32_bf16 v[24:27], v[136:139], v[170:173], v[24:27]
	s_waitcnt lgkmcnt(1)
	v_mfma_f32_16x16x32_bf16 v[12:15], v[128:131], v[198:201], v[12:15]
	v_mfma_f32_16x16x32_bf16 v[8:11], v[136:139], v[198:201], v[8:11]
	v_mfma_f32_16x16x32_bf16 v[60:63], v[132:135], v[148:151], v[60:63]
	v_mfma_f32_16x16x32_bf16 v[56:59], v[140:143], v[148:151], v[56:59]
	v_mfma_f32_16x16x32_bf16 v[44:47], v[132:135], v[166:169], v[44:47]
	v_mfma_f32_16x16x32_bf16 v[40:43], v[140:143], v[166:169], v[40:43]
	v_mfma_f32_16x16x32_bf16 v[28:31], v[132:135], v[188:191], v[28:31]
	v_mfma_f32_16x16x32_bf16 v[24:27], v[140:143], v[188:191], v[24:27]
	s_waitcnt lgkmcnt(0)
	v_mfma_f32_16x16x32_bf16 v[12:15], v[132:135], v[202:205], v[12:15]
	v_mfma_f32_16x16x32_bf16 v[8:11], v[140:143], v[202:205], v[8:11]
	s_setprio 0
	s_barrier
	s_add_i32 s28, s29, s65
	v_lshl_add_u64 v[128:129], v[242:243], 0, s[40:41]
	s_mov_b32 m0, s28
	s_nop 0
	global_load_lds_dwordx4 v[128:129], off
	v_lshl_add_u64 v[128:129], v[244:245], 0, s[40:41]
	s_add_i32 m0, s28, 0x2000
	s_nop 0
	global_load_lds_dwordx4 v[128:129], off
	s_waitcnt vmcnt(6)
	s_barrier
	s_setprio 1
	v_mfma_f32_16x16x32_bf16 v[52:55], v[206:209], v[144:147], v[52:55]
	v_mfma_f32_16x16x32_bf16 v[48:51], v[214:217], v[144:147], v[48:51]
	v_mfma_f32_16x16x32_bf16 v[36:39], v[206:209], v[162:165], v[36:39]
	v_mfma_f32_16x16x32_bf16 v[32:35], v[214:217], v[162:165], v[32:35]
	v_mfma_f32_16x16x32_bf16 v[20:23], v[206:209], v[170:173], v[20:23]
	v_mfma_f32_16x16x32_bf16 v[16:19], v[214:217], v[170:173], v[16:19]
	v_mfma_f32_16x16x32_bf16 v[4:7], v[206:209], v[198:201], v[4:7]
	v_mfma_f32_16x16x32_bf16 v[0:3], v[214:217], v[198:201], v[0:3]
	v_mfma_f32_16x16x32_bf16 v[52:55], v[210:213], v[148:151], v[52:55]
	v_mfma_f32_16x16x32_bf16 v[48:51], v[232:235], v[148:151], v[48:51]
	v_mfma_f32_16x16x32_bf16 v[36:39], v[210:213], v[166:169], v[36:39]
	v_mfma_f32_16x16x32_bf16 v[32:35], v[232:235], v[166:169], v[32:35]
	v_mfma_f32_16x16x32_bf16 v[20:23], v[210:213], v[188:191], v[20:23]
	v_mfma_f32_16x16x32_bf16 v[16:19], v[232:235], v[188:191], v[16:19]
	v_mfma_f32_16x16x32_bf16 v[4:7], v[210:213], v[202:205], v[4:7]
	v_mfma_f32_16x16x32_bf16 v[0:3], v[232:235], v[202:205], v[0:3]
	s_setprio 0
	s_add_u32 s58, s58, 0x100
	s_addc_u32 s59, s59, 0
	s_add_u32 s21, s21, 0x100
	s_addc_u32 s80, s80, 0
	s_cmp_ge_i32 s81, s79
	s_mov_b32 s60, s81
	s_barrier
	s_cbranch_scc0 .LBB0_1282
	s_cmp_gt_i32 s24, -1
	s_mov_b64 s[58:59], -1
	s_cbranch_scc0 .LBB0_1285
	s_lshl_b64 s[58:59], s[24:25], 17
	v_mov_b32_e32 v128, v231
	s_add_u32 s58, s37, s58
	s_addc_u32 s59, s46, s59
	v_ashrrev_i32_e32 v129, 31, v128
	v_lshl_add_u64 v[128:129], v[128:129], 4, s[58:59]
	v_add_co_u32_e32 v134, vcc, s36, v128
	v_cvt_pk_bf16_f32 v130, v124, v125
	v_cvt_pk_bf16_f32 v131, v126, v127
	v_cvt_pk_bf16_f32 v132, v120, v121
	v_cvt_pk_bf16_f32 v133, v122, v123
	s_nop 1
	v_addc_co_u32_e32 v135, vcc, 0, v129, vcc
	s_movk_i32 s5, 0x4000
	global_store_dwordx4 v[128:129], v[130:133], off
	s_mov_b64 s[58:59], 0
	s_nop 0
	v_cvt_pk_bf16_f32 v130, v108, v109
	v_cvt_pk_bf16_f32 v131, v110, v111
	v_cvt_pk_bf16_f32 v132, v104, v105
	v_cvt_pk_bf16_f32 v133, v106, v107
	global_store_dwordx4 v[134:135], v[130:133], off
	v_add_co_u32_e32 v134, vcc, s5, v128
	s_movk_i32 s5, 0x6000
	s_nop 0
	v_addc_co_u32_e32 v135, vcc, 0, v129, vcc
	v_cvt_pk_bf16_f32 v130, v92, v93
	v_cvt_pk_bf16_f32 v131, v94, v95
	v_cvt_pk_bf16_f32 v132, v88, v89
	v_cvt_pk_bf16_f32 v133, v90, v91
	global_store_dwordx4 v[134:135], v[130:133], off
	v_add_co_u32_e32 v134, vcc, s5, v128
	s_nop 0
	v_cvt_pk_bf16_f32 v130, v76, v77
	v_cvt_pk_bf16_f32 v131, v78, v79
	v_cvt_pk_bf16_f32 v132, v72, v73
	v_cvt_pk_bf16_f32 v133, v74, v75
	s_nop 0
	v_addc_co_u32_e32 v135, vcc, 0, v129, vcc
	global_store_dwordx4 v[134:135], v[130:133], off
	v_add_co_u32_e32 v134, vcc, s92, v128
	s_mov_b32 s5, 0xa000
	s_nop 0
	v_addc_co_u32_e32 v135, vcc, 0, v129, vcc
	v_cvt_pk_bf16_f32 v130, v116, v117
	v_cvt_pk_bf16_f32 v131, v118, v119
	v_cvt_pk_bf16_f32 v132, v112, v113
	v_cvt_pk_bf16_f32 v133, v114, v115
	global_store_dwordx4 v[134:135], v[130:133], off
	v_add_co_u32_e32 v134, vcc, s5, v128
	s_mov_b32 s5, 0xc000
	s_nop 0
	v_addc_co_u32_e32 v135, vcc, 0, v129, vcc
	v_cvt_pk_bf16_f32 v130, v100, v101
	v_cvt_pk_bf16_f32 v131, v102, v103
	v_cvt_pk_bf16_f32 v132, v96, v97
	v_cvt_pk_bf16_f32 v133, v98, v99
	global_store_dwordx4 v[134:135], v[130:133], off
	v_add_co_u32_e32 v134, vcc, s5, v128
	s_mov_b32 s5, 0xe000
	s_nop 0
	v_addc_co_u32_e32 v135, vcc, 0, v129, vcc
	v_cvt_pk_bf16_f32 v130, v84, v85
	v_cvt_pk_bf16_f32 v131, v86, v87
	v_cvt_pk_bf16_f32 v132, v80, v81
	v_cvt_pk_bf16_f32 v133, v82, v83
	global_store_dwordx4 v[134:135], v[130:133], off
	v_add_co_u32_e32 v134, vcc, s5, v128
	s_mov_b32 s5, 0x10000
	s_nop 0
	v_addc_co_u32_e32 v135, vcc, 0, v129, vcc
	v_cvt_pk_bf16_f32 v130, v68, v69
	v_cvt_pk_bf16_f32 v131, v70, v71
	v_cvt_pk_bf16_f32 v132, v64, v65
	v_cvt_pk_bf16_f32 v133, v66, v67
	global_store_dwordx4 v[134:135], v[130:133], off
	v_add_co_u32_e32 v134, vcc, s5, v128
	s_mov_b32 s5, 0x12000
	s_nop 0
	v_addc_co_u32_e32 v135, vcc, 0, v129, vcc
	v_cvt_pk_bf16_f32 v130, v60, v61
	v_cvt_pk_bf16_f32 v131, v62, v63
	v_cvt_pk_bf16_f32 v132, v56, v57
	v_cvt_pk_bf16_f32 v133, v58, v59
	global_store_dwordx4 v[134:135], v[130:133], off
	v_add_co_u32_e32 v134, vcc, s5, v128
	s_mov_b32 s5, 0x14000
	s_nop 0
	v_addc_co_u32_e32 v135, vcc, 0, v129, vcc
	v_cvt_pk_bf16_f32 v130, v44, v45
	v_cvt_pk_bf16_f32 v131, v46, v47
	v_cvt_pk_bf16_f32 v132, v40, v41
	v_cvt_pk_bf16_f32 v133, v42, v43
	global_store_dwordx4 v[134:135], v[130:133], off
	v_add_co_u32_e32 v134, vcc, s5, v128
	s_mov_b32 s5, 0x16000
	s_nop 0
	v_addc_co_u32_e32 v135, vcc, 0, v129, vcc
	v_cvt_pk_bf16_f32 v130, v28, v29
	v_cvt_pk_bf16_f32 v131, v30, v31
	v_cvt_pk_bf16_f32 v132, v24, v25
	v_cvt_pk_bf16_f32 v133, v26, v27
	global_store_dwordx4 v[134:135], v[130:133], off
	v_add_co_u32_e32 v134, vcc, s5, v128
	s_mov_b32 s5, 0x18000
	s_nop 0
	v_addc_co_u32_e32 v135, vcc, 0, v129, vcc
	v_cvt_pk_bf16_f32 v130, v12, v13
	v_cvt_pk_bf16_f32 v131, v14, v15
	v_cvt_pk_bf16_f32 v132, v8, v9
	v_cvt_pk_bf16_f32 v133, v10, v11
	global_store_dwordx4 v[134:135], v[130:133], off
	v_add_co_u32_e32 v134, vcc, s5, v128
	s_mov_b32 s5, 0x1a000
	s_nop 0
	v_addc_co_u32_e32 v135, vcc, 0, v129, vcc
	v_cvt_pk_bf16_f32 v130, v52, v53
	v_cvt_pk_bf16_f32 v131, v54, v55
	v_cvt_pk_bf16_f32 v132, v48, v49
	v_cvt_pk_bf16_f32 v133, v50, v51
	global_store_dwordx4 v[134:135], v[130:133], off
	v_add_co_u32_e32 v134, vcc, s5, v128
	s_mov_b32 s5, 0x1c000
	s_nop 0
	v_addc_co_u32_e32 v135, vcc, 0, v129, vcc
	v_cvt_pk_bf16_f32 v130, v36, v37
	v_cvt_pk_bf16_f32 v131, v38, v39
	v_cvt_pk_bf16_f32 v132, v32, v33
	v_cvt_pk_bf16_f32 v133, v34, v35
	global_store_dwordx4 v[134:135], v[130:133], off
	v_add_co_u32_e32 v134, vcc, s5, v128
	s_nop 0
	v_cvt_pk_bf16_f32 v130, v20, v21
	v_cvt_pk_bf16_f32 v131, v22, v23
	v_cvt_pk_bf16_f32 v132, v16, v17
	v_cvt_pk_bf16_f32 v133, v18, v19
	s_nop 0
	v_addc_co_u32_e32 v135, vcc, 0, v129, vcc
	v_add_co_u32_e32 v128, vcc, 0x1e000, v128
	global_store_dwordx4 v[134:135], v[130:133], off
	s_nop 0
	v_addc_co_u32_e32 v129, vcc, 0, v129, vcc
	v_cvt_pk_bf16_f32 v130, v4, v5
	v_cvt_pk_bf16_f32 v131, v6, v7
	v_cvt_pk_bf16_f32 v132, v0, v1
	v_cvt_pk_bf16_f32 v133, v2, v3
	global_store_dwordx4 v[128:129], v[130:133], off

.LBB0_1436:
	s_add_u32 s28, s6, 0xfffc0080
	s_addc_u32 s29, s7, -1
	s_add_i32 s71, 0, 0x10000
	v_add_u32_e32 v140, s71, v200
	ds_read_b128 v[128:131], v140
	ds_read_b128 v[132:135], v140 offset:1024
	ds_read_b128 v[136:139], v140 offset:2048
	ds_read_b128 v[140:143], v140 offset:3072
	s_cmp_eq_u32 s70, 12
	s_cselect_b32 s53, s17, s29
	s_cselect_b32 s52, s66, s28
	s_cselect_b32 s51, s13, s69
	s_cselect_b32 s50, s67, s68
	v_lshl_add_u64 v[174:175], s[6:7], 0, v[162:163]
	s_add_i32 m0, s56, 0xc000
	ds_read_b128 v[144:147], v201
	ds_read_b128 v[148:151], v201 offset:1024
	ds_read_b128 v[152:155], v201 offset:2048
	ds_read_b128 v[166:169], v201 offset:3072
	ds_read_b128 v[170:173], v201 offset:4096
	ds_read_b128 v[188:191], v201 offset:5120
	ds_read_b128 v[192:195], v201 offset:6144
	ds_read_b128 v[202:205], v201 offset:7168
	global_load_lds_dwordx4 v[174:175], off
	v_lshl_add_u64 v[174:175], s[6:7], 0, v[164:165]
	s_add_i32 m0, s56, 0xe000
	s_nop 0
	global_load_lds_dwordx4 v[174:175], off
	s_waitcnt lgkmcnt(8)
	s_barrier
	s_setprio 1
	s_waitcnt lgkmcnt(7)
	v_mfma_f32_16x16x32_bf16 v[124:127], v[128:131], v[144:147], v[124:127]
	v_mfma_f32_16x16x32_bf16 v[116:119], v[136:139], v[144:147], v[116:119]
	s_waitcnt lgkmcnt(5)
	v_mfma_f32_16x16x32_bf16 v[108:111], v[128:131], v[152:155], v[108:111]
	v_mfma_f32_16x16x32_bf16 v[100:103], v[136:139], v[152:155], v[100:103]
	s_waitcnt lgkmcnt(3)
	v_mfma_f32_16x16x32_bf16 v[92:95], v[128:131], v[170:173], v[92:95]
	v_mfma_f32_16x16x32_bf16 v[84:87], v[136:139], v[170:173], v[84:87]
	s_waitcnt lgkmcnt(1)
	v_mfma_f32_16x16x32_bf16 v[76:79], v[128:131], v[192:195], v[76:79]
	v_mfma_f32_16x16x32_bf16 v[68:71], v[136:139], v[192:195], v[68:71]
	v_mfma_f32_16x16x32_bf16 v[124:127], v[132:135], v[148:151], v[124:127]
	v_mfma_f32_16x16x32_bf16 v[116:119], v[140:143], v[148:151], v[116:119]
	v_mfma_f32_16x16x32_bf16 v[108:111], v[132:135], v[166:169], v[108:111]
	v_mfma_f32_16x16x32_bf16 v[100:103], v[140:143], v[166:169], v[100:103]
	v_mfma_f32_16x16x32_bf16 v[92:95], v[132:135], v[188:191], v[92:95]
	v_mfma_f32_16x16x32_bf16 v[84:87], v[140:143], v[188:191], v[84:87]
	s_waitcnt lgkmcnt(0)
	v_mfma_f32_16x16x32_bf16 v[76:79], v[132:135], v[202:205], v[76:79]
	v_mfma_f32_16x16x32_bf16 v[68:71], v[140:143], v[202:205], v[68:71]
	s_setprio 0
	s_barrier
	s_add_i32 s28, 0, 0x14000
	v_add_u32_e32 v174, s28, v200
	s_add_i32 s29, s71, s55
	ds_read_b128 v[206:209], v174
	ds_read_b128 v[210:213], v174 offset:1024
	ds_read_b128 v[214:217], v174 offset:2048
	ds_read_b128 v[232:235], v174 offset:3072
	v_lshl_add_u64 v[174:175], s[50:51], 0, v[176:177]
	s_mov_b32 m0, s29
	v_lshl_add_u64 v[196:197], s[50:51], 0, v[160:161]
	global_load_lds_dwordx4 v[174:175], off
	s_add_i32 m0, s29, 0x2000
	s_nop 0
	global_load_lds_dwordx4 v[196:197], off
	s_barrier
	s_setprio 1
	s_waitcnt lgkmcnt(3)
	v_mfma_f32_16x16x32_bf16 v[120:123], v[206:209], v[144:147], v[120:123]
	s_waitcnt lgkmcnt(1)
	v_mfma_f32_16x16x32_bf16 v[112:115], v[214:217], v[144:147], v[112:115]
	v_mfma_f32_16x16x32_bf16 v[104:107], v[206:209], v[152:155], v[104:107]
	v_mfma_f32_16x16x32_bf16 v[96:99], v[214:217], v[152:155], v[96:99]
	v_mfma_f32_16x16x32_bf16 v[88:91], v[206:209], v[170:173], v[88:91]
	v_mfma_f32_16x16x32_bf16 v[80:83], v[214:217], v[170:173], v[80:83]
	v_mfma_f32_16x16x32_bf16 v[72:75], v[206:209], v[192:195], v[72:75]
	v_mfma_f32_16x16x32_bf16 v[64:67], v[214:217], v[192:195], v[64:67]
	v_mfma_f32_16x16x32_bf16 v[120:123], v[210:213], v[148:151], v[120:123]
	s_waitcnt lgkmcnt(0)
	v_mfma_f32_16x16x32_bf16 v[112:115], v[232:235], v[148:151], v[112:115]
	v_mfma_f32_16x16x32_bf16 v[104:107], v[210:213], v[166:169], v[104:107]
	v_mfma_f32_16x16x32_bf16 v[96:99], v[232:235], v[166:169], v[96:99]
	v_mfma_f32_16x16x32_bf16 v[88:91], v[210:213], v[188:191], v[88:91]
	v_mfma_f32_16x16x32_bf16 v[80:83], v[232:235], v[188:191], v[80:83]
	v_mfma_f32_16x16x32_bf16 v[72:75], v[210:213], v[202:205], v[72:75]
	v_mfma_f32_16x16x32_bf16 v[64:67], v[232:235], v[202:205], v[64:67]
	s_setprio 0
	s_mov_b32 m0, s56
	v_lshl_add_u64 v[236:237], s[52:53], 0, v[156:157]
	s_barrier
	ds_read_b128 v[144:147], v201 offset:16384
	ds_read_b128 v[148:151], v201 offset:17408
	ds_read_b128 v[152:155], v201 offset:18432
	ds_read_b128 v[166:169], v201 offset:19456
	ds_read_b128 v[170:173], v201 offset:20480
	ds_read_b128 v[188:191], v201 offset:21504
	ds_read_b128 v[192:195], v201 offset:22528
	ds_read_b128 v[202:205], v201 offset:23552
	global_load_lds_dwordx4 v[236:237], off
	v_lshl_add_u64 v[238:239], s[52:53], 0, v[158:159]
	s_mov_b32 m0, s57
	s_nop 0
	global_load_lds_dwordx4 v[238:239], off
	s_barrier
	s_setprio 1
	s_waitcnt lgkmcnt(7)
	v_mfma_f32_16x16x32_bf16 v[60:63], v[128:131], v[144:147], v[60:63]
	v_mfma_f32_16x16x32_bf16 v[52:55], v[136:139], v[144:147], v[52:55]
	s_waitcnt lgkmcnt(5)
	v_mfma_f32_16x16x32_bf16 v[44:47], v[128:131], v[152:155], v[44:47]
	v_mfma_f32_16x16x32_bf16 v[36:39], v[136:139], v[152:155], v[36:39]
	s_waitcnt lgkmcnt(3)
	v_mfma_f32_16x16x32_bf16 v[28:31], v[128:131], v[170:173], v[28:31]
	v_mfma_f32_16x16x32_bf16 v[20:23], v[136:139], v[170:173], v[20:23]
	s_waitcnt lgkmcnt(1)
	v_mfma_f32_16x16x32_bf16 v[12:15], v[128:131], v[192:195], v[12:15]
	v_mfma_f32_16x16x32_bf16 v[4:7], v[136:139], v[192:195], v[4:7]
	v_mfma_f32_16x16x32_bf16 v[60:63], v[132:135], v[148:151], v[60:63]
	v_mfma_f32_16x16x32_bf16 v[52:55], v[140:143], v[148:151], v[52:55]
	v_mfma_f32_16x16x32_bf16 v[44:47], v[132:135], v[166:169], v[44:47]
	v_mfma_f32_16x16x32_bf16 v[36:39], v[140:143], v[166:169], v[36:39]
	v_mfma_f32_16x16x32_bf16 v[28:31], v[132:135], v[188:191], v[28:31]
	v_mfma_f32_16x16x32_bf16 v[20:23], v[140:143], v[188:191], v[20:23]
	s_waitcnt lgkmcnt(0)
	v_mfma_f32_16x16x32_bf16 v[12:15], v[132:135], v[202:205], v[12:15]
	v_mfma_f32_16x16x32_bf16 v[4:7], v[140:143], v[202:205], v[4:7]
	s_setprio 0
	s_barrier
	s_add_u32 s72, s50, 0x40000
	s_addc_u32 s73, s51, 0
	s_add_i32 s28, s28, s55
	v_lshl_add_u64 v[128:129], s[72:73], 0, v[176:177]
	s_mov_b32 m0, s28
	s_nop 0
	global_load_lds_dwordx4 v[128:129], off
	v_lshl_add_u64 v[128:129], s[72:73], 0, v[160:161]
	s_add_i32 m0, s28, 0x2000
	s_nop 0
	global_load_lds_dwordx4 v[128:129], off
	s_waitcnt vmcnt(6)
	s_barrier
	s_setprio 1
	v_mfma_f32_16x16x32_bf16 v[56:59], v[206:209], v[144:147], v[56:59]
	v_mfma_f32_16x16x32_bf16 v[48:51], v[214:217], v[144:147], v[48:51]
	v_mfma_f32_16x16x32_bf16 v[40:43], v[206:209], v[152:155], v[40:43]
	v_mfma_f32_16x16x32_bf16 v[32:35], v[214:217], v[152:155], v[32:35]
	v_mfma_f32_16x16x32_bf16 v[24:27], v[206:209], v[170:173], v[24:27]
	v_mfma_f32_16x16x32_bf16 v[16:19], v[214:217], v[170:173], v[16:19]
	v_mfma_f32_16x16x32_bf16 v[8:11], v[206:209], v[192:195], v[8:11]
	v_mfma_f32_16x16x32_bf16 v[0:3], v[214:217], v[192:195], v[0:3]
	v_mfma_f32_16x16x32_bf16 v[56:59], v[210:213], v[148:151], v[56:59]
	v_mfma_f32_16x16x32_bf16 v[48:51], v[232:235], v[148:151], v[48:51]
	v_mfma_f32_16x16x32_bf16 v[40:43], v[210:213], v[166:169], v[40:43]
	v_mfma_f32_16x16x32_bf16 v[32:35], v[232:235], v[166:169], v[32:35]
	v_mfma_f32_16x16x32_bf16 v[24:27], v[210:213], v[188:191], v[24:27]
	v_mfma_f32_16x16x32_bf16 v[16:19], v[232:235], v[188:191], v[16:19]
	v_mfma_f32_16x16x32_bf16 v[8:11], v[210:213], v[202:205], v[8:11]
	v_mfma_f32_16x16x32_bf16 v[0:3], v[232:235], v[202:205], v[0:3]
	s_setprio 0
	s_add_i32 s28, 0, 0x18000
	v_add_u32_e32 v140, s28, v200
	s_barrier
	ds_read_b128 v[128:131], v140
	ds_read_b128 v[132:135], v140 offset:1024
	ds_read_b128 v[136:139], v140 offset:2048
	ds_read_b128 v[140:143], v140 offset:3072
	s_add_u32 s52, s52, 0x40000
	s_addc_u32 s53, s53, 0
	s_mov_b32 m0, s58
	v_lshl_add_u64 v[206:207], s[52:53], 0, v[156:157]
	ds_read_b128 v[144:147], v201 offset:32768
	ds_read_b128 v[148:151], v201 offset:33792
	ds_read_b128 v[152:155], v201 offset:34816
	ds_read_b128 v[166:169], v201 offset:35840
	ds_read_b128 v[170:173], v201 offset:36864
	ds_read_b128 v[188:191], v201 offset:37888
	ds_read_b128 v[192:195], v201 offset:38912
	ds_read_b128 v[202:205], v201 offset:39936
	global_load_lds_dwordx4 v[206:207], off
	v_lshl_add_u64 v[206:207], s[52:53], 0, v[158:159]
	s_mov_b32 m0, s59
	s_nop 0
	global_load_lds_dwordx4 v[206:207], off
	s_waitcnt lgkmcnt(8)
	s_barrier
	s_setprio 1
	s_waitcnt lgkmcnt(7)
	v_mfma_f32_16x16x32_bf16 v[124:127], v[128:131], v[144:147], v[124:127]
	v_mfma_f32_16x16x32_bf16 v[116:119], v[136:139], v[144:147], v[116:119]
	s_waitcnt lgkmcnt(5)
	v_mfma_f32_16x16x32_bf16 v[108:111], v[128:131], v[152:155], v[108:111]
	v_mfma_f32_16x16x32_bf16 v[100:103], v[136:139], v[152:155], v[100:103]
	s_waitcnt lgkmcnt(3)
	v_mfma_f32_16x16x32_bf16 v[92:95], v[128:131], v[170:173], v[92:95]
	v_mfma_f32_16x16x32_bf16 v[84:87], v[136:139], v[170:173], v[84:87]
	s_waitcnt lgkmcnt(1)
	v_mfma_f32_16x16x32_bf16 v[76:79], v[128:131], v[192:195], v[76:79]
	v_mfma_f32_16x16x32_bf16 v[68:71], v[136:139], v[192:195], v[68:71]
	v_mfma_f32_16x16x32_bf16 v[124:127], v[132:135], v[148:151], v[124:127]
	v_mfma_f32_16x16x32_bf16 v[116:119], v[140:143], v[148:151], v[116:119]
	v_mfma_f32_16x16x32_bf16 v[108:111], v[132:135], v[166:169], v[108:111]
	v_mfma_f32_16x16x32_bf16 v[100:103], v[140:143], v[166:169], v[100:103]
	v_mfma_f32_16x16x32_bf16 v[92:95], v[132:135], v[188:191], v[92:95]
	v_mfma_f32_16x16x32_bf16 v[84:87], v[140:143], v[188:191], v[84:87]
	s_waitcnt lgkmcnt(0)
	v_mfma_f32_16x16x32_bf16 v[76:79], v[132:135], v[202:205], v[76:79]
	v_mfma_f32_16x16x32_bf16 v[68:71], v[140:143], v[202:205], v[68:71]
	s_setprio 0
	s_barrier
	s_add_i32 s29, 0, 0x1c000
	s_add_i32 s28, s28, s55
	v_add_u32_e32 v232, s29, v200
	v_lshl_add_u64 v[174:175], v[174:175], 0, s[40:41]
	s_mov_b32 m0, s28
	ds_read_b128 v[206:209], v232
	ds_read_b128 v[210:213], v232 offset:1024
	ds_read_b128 v[214:217], v232 offset:2048
	ds_read_b128 v[232:235], v232 offset:3072
	global_load_lds_dwordx4 v[174:175], off
	v_lshl_add_u64 v[174:175], v[196:197], 0, s[40:41]
	s_add_i32 m0, s28, 0x2000
	s_nop 0
	global_load_lds_dwordx4 v[174:175], off
	s_barrier
	s_setprio 1
	s_waitcnt lgkmcnt(3)
	v_mfma_f32_16x16x32_bf16 v[120:123], v[206:209], v[144:147], v[120:123]
	s_waitcnt lgkmcnt(1)
	v_mfma_f32_16x16x32_bf16 v[112:115], v[214:217], v[144:147], v[112:115]
	v_mfma_f32_16x16x32_bf16 v[104:107], v[206:209], v[152:155], v[104:107]
	v_mfma_f32_16x16x32_bf16 v[96:99], v[214:217], v[152:155], v[96:99]
	v_mfma_f32_16x16x32_bf16 v[88:91], v[206:209], v[170:173], v[88:91]
	v_mfma_f32_16x16x32_bf16 v[80:83], v[214:217], v[170:173], v[80:83]
	v_mfma_f32_16x16x32_bf16 v[72:75], v[206:209], v[192:195], v[72:75]
	v_mfma_f32_16x16x32_bf16 v[64:67], v[214:217], v[192:195], v[64:67]
	v_mfma_f32_16x16x32_bf16 v[120:123], v[210:213], v[148:151], v[120:123]
	s_waitcnt lgkmcnt(0)
	v_mfma_f32_16x16x32_bf16 v[112:115], v[232:235], v[148:151], v[112:115]
	v_mfma_f32_16x16x32_bf16 v[104:107], v[210:213], v[166:169], v[104:107]
	v_mfma_f32_16x16x32_bf16 v[96:99], v[232:235], v[166:169], v[96:99]
	v_mfma_f32_16x16x32_bf16 v[88:91], v[210:213], v[188:191], v[88:91]
	v_mfma_f32_16x16x32_bf16 v[80:83], v[232:235], v[188:191], v[80:83]
	v_mfma_f32_16x16x32_bf16 v[72:75], v[210:213], v[202:205], v[72:75]
	v_mfma_f32_16x16x32_bf16 v[64:67], v[232:235], v[202:205], v[64:67]
	s_setprio 0
	s_mov_b32 m0, s62
	v_lshl_add_u64 v[174:175], v[236:237], 0, s[40:41]
	s_barrier
	ds_read_b128 v[144:147], v201 offset:49152
	ds_read_b128 v[148:151], v201 offset:50176
	ds_read_b128 v[152:155], v201 offset:51200
	ds_read_b128 v[166:169], v201 offset:52224
	ds_read_b128 v[170:173], v201 offset:53248
	ds_read_b128 v[188:191], v201 offset:54272
	ds_read_b128 v[192:195], v201 offset:55296
	ds_read_b128 v[202:205], v201 offset:56320
	global_load_lds_dwordx4 v[174:175], off
	v_lshl_add_u64 v[174:175], v[238:239], 0, s[40:41]
	s_mov_b32 m0, s63
	s_nop 0
	global_load_lds_dwordx4 v[174:175], off
	s_barrier
	s_setprio 1
	s_waitcnt lgkmcnt(7)
	v_mfma_f32_16x16x32_bf16 v[60:63], v[128:131], v[144:147], v[60:63]
	v_mfma_f32_16x16x32_bf16 v[52:55], v[136:139], v[144:147], v[52:55]
	s_waitcnt lgkmcnt(5)
	v_mfma_f32_16x16x32_bf16 v[44:47], v[128:131], v[152:155], v[44:47]
	v_mfma_f32_16x16x32_bf16 v[36:39], v[136:139], v[152:155], v[36:39]
	s_waitcnt lgkmcnt(3)
	v_mfma_f32_16x16x32_bf16 v[28:31], v[128:131], v[170:173], v[28:31]
	v_mfma_f32_16x16x32_bf16 v[20:23], v[136:139], v[170:173], v[20:23]
	s_waitcnt lgkmcnt(1)
	v_mfma_f32_16x16x32_bf16 v[12:15], v[128:131], v[192:195], v[12:15]
	v_mfma_f32_16x16x32_bf16 v[4:7], v[136:139], v[192:195], v[4:7]
	v_mfma_f32_16x16x32_bf16 v[60:63], v[132:135], v[148:151], v[60:63]
	v_mfma_f32_16x16x32_bf16 v[52:55], v[140:143], v[148:151], v[52:55]
	v_mfma_f32_16x16x32_bf16 v[44:47], v[132:135], v[166:169], v[44:47]
	v_mfma_f32_16x16x32_bf16 v[36:39], v[140:143], v[166:169], v[36:39]
	v_mfma_f32_16x16x32_bf16 v[28:31], v[132:135], v[188:191], v[28:31]
	v_mfma_f32_16x16x32_bf16 v[20:23], v[140:143], v[188:191], v[20:23]
	s_waitcnt lgkmcnt(0)
	v_mfma_f32_16x16x32_bf16 v[12:15], v[132:135], v[202:205], v[12:15]
	v_mfma_f32_16x16x32_bf16 v[4:7], v[140:143], v[202:205], v[4:7]
	s_setprio 0
	s_barrier
	s_add_u32 s50, s50, 0x40080
	s_addc_u32 s51, s51, 0
	s_add_i32 s28, s29, s55
	v_lshl_add_u64 v[128:129], s[50:51], 0, v[176:177]
	s_mov_b32 m0, s28
	s_nop 0
	global_load_lds_dwordx4 v[128:129], off
	v_lshl_add_u64 v[128:129], s[50:51], 0, v[160:161]
	s_add_i32 m0, s28, 0x2000
	s_nop 0
	global_load_lds_dwordx4 v[128:129], off
	s_waitcnt vmcnt(6)
	s_barrier
	s_setprio 1
	v_mfma_f32_16x16x32_bf16 v[56:59], v[206:209], v[144:147], v[56:59]
	v_mfma_f32_16x16x32_bf16 v[48:51], v[214:217], v[144:147], v[48:51]
	v_mfma_f32_16x16x32_bf16 v[40:43], v[206:209], v[152:155], v[40:43]
	v_mfma_f32_16x16x32_bf16 v[32:35], v[214:217], v[152:155], v[32:35]
	v_mfma_f32_16x16x32_bf16 v[24:27], v[206:209], v[170:173], v[24:27]
	v_mfma_f32_16x16x32_bf16 v[16:19], v[214:217], v[170:173], v[16:19]
	v_mfma_f32_16x16x32_bf16 v[8:11], v[206:209], v[192:195], v[8:11]
	v_mfma_f32_16x16x32_bf16 v[0:3], v[214:217], v[192:195], v[0:3]
	v_mfma_f32_16x16x32_bf16 v[56:59], v[210:213], v[148:151], v[56:59]
	v_mfma_f32_16x16x32_bf16 v[48:51], v[232:235], v[148:151], v[48:51]
	v_mfma_f32_16x16x32_bf16 v[40:43], v[210:213], v[166:169], v[40:43]
	v_mfma_f32_16x16x32_bf16 v[32:35], v[232:235], v[166:169], v[32:35]
	v_mfma_f32_16x16x32_bf16 v[24:27], v[210:213], v[188:191], v[24:27]
	v_mfma_f32_16x16x32_bf16 v[16:19], v[232:235], v[188:191], v[16:19]
	v_mfma_f32_16x16x32_bf16 v[8:11], v[210:213], v[202:205], v[8:11]
	v_mfma_f32_16x16x32_bf16 v[0:3], v[232:235], v[202:205], v[0:3]
	s_setprio 0
	s_add_i32 s70, s70, 2
	s_add_u32 s6, s6, 0x100
	s_addc_u32 s7, s7, 0
	s_add_u32 s68, s68, 0x100
	s_addc_u32 s69, s69, 0
	s_cmp_lt_u32 s70, 14
	s_barrier
	s_cbranch_scc1 .LBB0_1436
	v_mov_b32_e32 v134, v199
	v_mov_b32_e32 v128, v198
	s_lshl_b32 s4, s4, 8
	s_add_i32 s4, s4, s60
	v_add_u32_e32 v192, s4, v128
	v_lshlrev_b32_e32 v128, 2, v134
	v_ashrrev_i32_e32 v129, 31, v128
	v_ashrrev_i32_e32 v193, 31, v192
	v_add_u32_e32 v190, 16, v192
	v_lshl_add_u64 v[132:133], v[128:129], 2, s[8:9]
	v_lshlrev_b64 v[128:129], 6, v[192:193]
	v_ashrrev_i32_e32 v191, 31, v190
	v_add_u32_e32 v188, 32, v192
	v_lshl_add_u64 v[128:129], v[132:133], 0, v[128:129]
	v_lshlrev_b64 v[130:131], 6, v[190:191]
	v_ashrrev_i32_e32 v189, 31, v188
	v_lshl_add_u64 v[130:131], v[132:133], 0, v[130:131]
	global_load_dwordx4 v[202:205], v[128:129], off
	global_load_dwordx4 v[144:147], v[130:131], off
	v_lshlrev_b64 v[128:129], 6, v[188:189]
	v_add_u32_e32 v174, 48, v192
	v_lshl_add_u64 v[128:129], v[132:133], 0, v[128:129]
	v_ashrrev_i32_e32 v175, 31, v174
	global_load_dwordx4 v[148:151], v[128:129], off
	v_lshlrev_b64 v[128:129], 6, v[174:175]
	v_lshl_add_u64 v[128:129], v[132:133], 0, v[128:129]
	global_load_dwordx4 v[152:155], v[128:129], off
	v_add_u32_e32 v172, 0x80, v192
	v_ashrrev_i32_e32 v173, 31, v172
	v_lshlrev_b64 v[128:129], 6, v[172:173]
	v_lshl_add_u64 v[128:129], v[132:133], 0, v[128:129]
	global_load_dwordx4 v[140:143], v[128:129], off
	v_add_u32_e32 v170, 0x90, v192
	v_ashrrev_i32_e32 v171, 31, v170
	v_lshlrev_b64 v[128:129], 6, v[170:171]
	v_lshl_add_u64 v[128:129], v[132:133], 0, v[128:129]
	global_load_dwordx4 v[128:131], v[128:129], off
	s_lshl_b32 s5, s5, 7
	v_add_u32_e32 v168, 0xa0, v192
	v_add_u32_e32 v166, 0xb0, v192
	s_or_b32 s5, s5, s61
	v_ashrrev_i32_e32 v169, 31, v168
	v_ashrrev_i32_e32 v167, 31, v166
	v_lshl_add_u32 v194, v134, 3, s5
	v_lshlrev_b64 v[134:135], 6, v[168:169]
	v_lshlrev_b64 v[136:137], 6, v[166:167]
	v_lshl_add_u64 v[134:135], v[132:133], 0, v[134:135]
	v_lshl_add_u64 v[132:133], v[132:133], 0, v[136:137]
	global_load_dwordx4 v[136:139], v[134:135], off
	s_nop 0
	global_load_dwordx4 v[132:135], v[132:133], off
	s_mov_b32 s4, 0x358637bd
	v_mov_b64_e32 v[196:197], s[4:5]
	v_ashrrev_i32_e32 v195, 31, v194
	s_mov_b64 s[50:51], s[20:21]
	s_waitcnt vmcnt(0)
	v_mov_b32_e32 v206, v203
	v_mov_b32_e32 v207, v204
	v_mov_b32_e32 v203, v205
	v_mov_b32_e32 v204, v145
	v_mov_b32_e32 v205, v146
	v_mov_b32_e32 v145, v147
	v_pk_add_f32 v[202:203], v[206:207], v[202:203]
	v_mov_b32_e32 v146, v149
	v_mov_b32_e32 v147, v150
	v_mov_b32_e32 v149, v151
	v_mov_b32_e32 v150, v153
	v_mov_b32_e32 v151, v154
	v_mov_b32_e32 v153, v155
	v_pk_add_f32 v[144:145], v[204:205], v[144:145]
	v_mov_b32_e32 v155, v202
	v_pk_add_f32 v[146:147], v[146:147], v[148:149]
	v_pk_add_f32 v[148:149], v[150:151], v[152:153]
	v_mov_b32_e32 v154, v144
	v_mov_b32_e32 v202, v145
	v_mov_b32_e32 v144, v148
	v_mov_b32_e32 v145, v146
	v_mov_b32_e32 v146, v149
	v_pk_add_f32 v[148:149], v[154:155], v[202:203]
	v_pk_add_f32 v[144:145], v[144:145], v[146:147]
	ds_bpermute_b32 v147, v219, v149
	ds_bpermute_b32 v146, v219, v148
	ds_bpermute_b32 v151, v219, v145
	ds_bpermute_b32 v150, v219, v144
	v_mov_b32_e32 v152, v141
	v_mov_b32_e32 v153, v142
	v_mov_b32_e32 v141, v143
	s_waitcnt lgkmcnt(0)
	v_pk_add_f32 v[142:143], v[148:149], v[146:147]
	ds_bpermute_b32 v147, v218, v143
	ds_bpermute_b32 v146, v218, v142
	v_pk_add_f32 v[144:145], v[144:145], v[150:151]
	ds_bpermute_b32 v149, v218, v145
	ds_bpermute_b32 v148, v218, v144
	v_mov_b32_e32 v150, v129
	s_waitcnt lgkmcnt(2)
	v_pk_add_f32 v[142:143], v[142:143], v[146:147]
	v_mov_b32_e32 v151, v130
	v_pk_fma_f32 v[142:143], v[142:143], s[30:31], v[196:197] op_sel_hi:[1,0,0]
	s_waitcnt lgkmcnt(0)
	v_pk_add_f32 v[144:145], v[144:145], v[148:149]
	v_mul_f32_e32 v129, 0x4b800000, v143
	v_cmp_gt_f32_e32 vcc, s86, v143
	v_pk_fma_f32 v[146:147], v[144:145], s[30:31], v[196:197] op_sel_hi:[1,0,0]
	v_mul_f32_e32 v130, 0x4b800000, v142
	v_cndmask_b32_e32 v129, v143, v129, vcc
	v_rsq_f32_e32 v129, v129
	v_cmp_gt_f32_e64 s[4:5], s86, v142
	v_mul_f32_e32 v144, 0x4b800000, v147
	v_cmp_gt_f32_e64 s[6:7], s86, v147
	v_cndmask_b32_e64 v130, v142, v130, s[4:5]
	v_rsq_f32_e32 v142, v130
	v_cndmask_b32_e64 v130, v147, v144, s[6:7]
	v_rsq_f32_e32 v143, v130
	v_mul_f32_e32 v130, 0x45800000, v129
	v_cndmask_b32_e32 v144, v129, v130, vcc
	v_mov_b32_e32 v129, v131
	v_pk_add_f32 v[140:141], v[152:153], v[140:141]
	v_pk_add_f32 v[128:129], v[150:151], v[128:129]
	v_mov_b32_e32 v131, v140
	v_mov_b32_e32 v130, v128
	v_mov_b32_e32 v140, v129
	v_pk_add_f32 v[128:129], v[130:131], v[140:141]
	ds_bpermute_b32 v131, v219, v129
	ds_bpermute_b32 v130, v219, v128
	v_mul_f32_e32 v145, 0x45800000, v142
	v_cndmask_b32_e64 v142, v142, v145, s[4:5]
	v_mul_f32_e32 v140, 0x4b800000, v146
	v_cmp_gt_f32_e32 vcc, s86, v146
	s_waitcnt lgkmcnt(0)
	v_pk_add_f32 v[128:129], v[128:129], v[130:131]
	ds_bpermute_b32 v131, v218, v129
	ds_bpermute_b32 v130, v218, v128
	v_cndmask_b32_e32 v140, v146, v140, vcc
	v_rsq_f32_e32 v141, v140
	v_mul_f32_e32 v140, 0x45800000, v143
	v_cndmask_b32_e64 v140, v143, v140, s[6:7]
	s_waitcnt lgkmcnt(0)
	v_pk_add_f32 v[128:129], v[128:129], v[130:131]
	v_mov_b32_e32 v131, v138
	v_pk_fma_f32 v[128:129], v[128:129], s[30:31], v[196:197] op_sel_hi:[1,0,0]
	v_mul_f32_e32 v143, 0x45800000, v141
	v_mul_f32_e32 v130, 0x4b800000, v129
	v_cmp_gt_f32_e64 s[4:5], s86, v129
	v_cmp_gt_f32_e64 s[6:7], s86, v128
	v_pk_mul_f32 v[110:111], v[110:111], v[142:143] op_sel_hi:[1,0]
	v_cndmask_b32_e64 v129, v129, v130, s[4:5]
	v_mov_b32_e32 v130, v137
	v_mov_b32_e32 v137, v139
	v_pk_add_f32 v[130:131], v[130:131], v[136:137]
	v_mov_b32_e32 v136, v133
	v_mov_b32_e32 v137, v134
	v_mov_b32_e32 v133, v135
	v_pk_add_f32 v[132:133], v[136:137], v[132:133]
	v_mov_b32_e32 v135, v130
	v_mov_b32_e32 v134, v132
	v_mov_b32_e32 v130, v133
	v_pk_add_f32 v[130:131], v[134:135], v[130:131]
	ds_bpermute_b32 v133, v219, v131
	ds_bpermute_b32 v132, v219, v130
	v_rsq_f32_e32 v145, v129
	v_mul_f32_e32 v129, 0x4b800000, v128
	v_cndmask_b32_e64 v128, v128, v129, s[6:7]
	v_rsq_f32_e32 v135, v128
	s_waitcnt lgkmcnt(0)
	v_pk_add_f32 v[128:129], v[130:131], v[132:133]
	ds_bpermute_b32 v131, v218, v129
	ds_bpermute_b32 v130, v218, v128
	v_pk_mul_f32 v[126:127], v[126:127], v[144:145] op_sel_hi:[1,0]
	v_pk_mul_f32 v[122:123], v[122:123], v[144:145] op_sel_hi:[1,0]
	v_pk_mul_f32 v[116:117], v[116:117], v[144:145] op_sel_hi:[1,0]
	v_pk_mul_f32 v[124:125], v[124:125], v[144:145] op_sel_hi:[1,0]
	v_pk_mul_f32 v[138:139], v[126:127], s[44:45] op_sel_hi:[1,0]
	v_pk_mul_f32 v[120:121], v[120:121], v[144:145] op_sel_hi:[1,0]
	v_pk_mul_f32 v[122:123], v[126:127], v[122:123]
	v_pk_mul_f32 v[118:119], v[118:119], v[144:145] op_sel_hi:[1,0]
	v_pk_mul_f32 v[126:127], v[116:117], s[44:45] op_sel_hi:[1,0]
	v_pk_mul_f32 v[146:147], v[124:125], s[44:45] op_sel_hi:[1,0]
	v_pk_mul_f32 v[120:121], v[124:125], v[120:121]
	v_pk_mul_f32 v[124:125], v[118:119], s[44:45] op_sel_hi:[1,0]
	v_exp_f32_e32 v126, v126
	v_exp_f32_e32 v127, v127
	s_waitcnt lgkmcnt(0)
	v_pk_add_f32 v[128:129], v[128:129], v[130:131]
	v_exp_f32_e32 v146, v146
	v_exp_f32_e32 v138, v138
	v_exp_f32_e32 v139, v139
	v_exp_f32_e32 v147, v147
	v_exp_f32_e32 v124, v124
	v_exp_f32_e32 v125, v125
	v_pk_fma_f32 v[128:129], v[128:129], s[30:31], v[196:197] op_sel_hi:[1,0,0]
	v_cndmask_b32_e32 v136, v141, v143, vcc
	v_mul_f32_e32 v132, 0x45800000, v145
	v_mul_f32_e32 v130, 0x4b800000, v129
	v_cmp_gt_f32_e32 vcc, s86, v129
	v_cndmask_b32_e64 v134, v145, v132, s[4:5]
	v_cmp_gt_f32_e64 s[4:5], s86, v128
	v_cndmask_b32_e32 v129, v129, v130, vcc
	v_mul_f32_e32 v130, 0x4b800000, v128
	v_pk_add_f32 v[126:127], v[126:127], 1.0 op_sel_hi:[1,0]
	v_rsq_f32_e32 v129, v129
	v_cndmask_b32_e64 v128, v128, v130, s[4:5]
	v_pk_add_f32 v[138:139], v[138:139], 1.0 op_sel_hi:[1,0]
	v_pk_add_f32 v[146:147], v[146:147], 1.0 op_sel_hi:[1,0]
	v_pk_add_f32 v[124:125], v[124:125], 1.0 op_sel_hi:[1,0]
	v_rcp_f32_e32 v126, v126
	v_rcp_f32_e32 v127, v127
	v_rsq_f32_e32 v128, v128
	v_rcp_f32_e32 v146, v146
	v_rcp_f32_e32 v138, v138
	v_rcp_f32_e32 v139, v139
	v_rcp_f32_e32 v147, v147
	v_rcp_f32_e32 v124, v124
	v_rcp_f32_e32 v125, v125
	v_pk_mul_f32 v[112:113], v[112:113], v[144:145] op_sel_hi:[1,0]
	v_pk_mul_f32 v[114:115], v[114:115], v[144:145] op_sel_hi:[1,0]
	v_pk_mul_f32 v[112:113], v[116:117], v[112:113]
	v_mul_f32_e32 v130, 0x45800000, v129
	v_pk_mul_f32 v[114:115], v[118:119], v[114:115]
	v_pk_mul_f32 v[112:113], v[112:113], v[126:127]
	v_cndmask_b32_e32 v130, v129, v130, vcc
	v_mul_f32_e32 v129, 0x45800000, v128
	v_pk_mul_f32 v[122:123], v[122:123], v[138:139]
	v_pk_mul_f32 v[120:121], v[120:121], v[146:147]
	v_pk_mul_f32 v[114:115], v[114:115], v[124:125]
	v_cvt_pk_bf16_f32 v116, v120, v121
	v_cvt_pk_bf16_f32 v117, v122, v123
	v_cvt_pk_bf16_f32 v118, v112, v113
	v_mov_b64_e32 v[112:113], s[10:11]
	v_cndmask_b32_e64 v128, v128, v129, s[4:5]
	v_cvt_pk_bf16_f32 v119, v114, v115
	v_mad_i64_i32 v[120:121], s[4:5], v192, s35, v[112:113]
	v_lshlrev_b64 v[114:115], 1, v[194:195]
	v_lshl_add_u64 v[120:121], v[120:121], 0, v[114:115]
	v_pk_mul_f32 v[108:109], v[108:109], v[142:143] op_sel_hi:[1,0]
	v_pk_mul_f32 v[106:107], v[106:107], v[142:143] op_sel_hi:[1,0]
	v_pk_mul_f32 v[104:105], v[104:105], v[142:143] op_sel_hi:[1,0]
	v_pk_mul_f32 v[102:103], v[102:103], v[142:143] op_sel_hi:[1,0]
	v_pk_mul_f32 v[100:101], v[100:101], v[142:143] op_sel_hi:[1,0]
	global_store_dwordx4 v[120:121], v[116:119], off
	v_pk_mul_f32 v[104:105], v[108:109], v[104:105]
	v_pk_mul_f32 v[106:107], v[110:111], v[106:107]
	v_pk_mul_f32 v[116:117], v[110:111], s[44:45] op_sel_hi:[1,0]
	v_pk_mul_f32 v[118:119], v[108:109], s[44:45] op_sel_hi:[1,0]
	v_pk_mul_f32 v[108:109], v[102:103], s[44:45] op_sel_hi:[1,0]
	v_pk_mul_f32 v[110:111], v[100:101], s[44:45] op_sel_hi:[1,0]
	v_exp_f32_e32 v108, v108
	v_exp_f32_e32 v110, v110
	v_exp_f32_e32 v109, v109
	v_exp_f32_e32 v111, v111
	v_exp_f32_e32 v118, v118
	v_exp_f32_e32 v116, v116
	v_exp_f32_e32 v117, v117
	v_exp_f32_e32 v119, v119
	v_pk_add_f32 v[108:109], v[108:109], 1.0 op_sel_hi:[1,0]
	v_pk_add_f32 v[110:111], v[110:111], 1.0 op_sel_hi:[1,0]
	v_pk_add_f32 v[116:117], v[116:117], 1.0 op_sel_hi:[1,0]
	v_pk_add_f32 v[118:119], v[118:119], 1.0 op_sel_hi:[1,0]
	v_rcp_f32_e32 v110, v110
	v_rcp_f32_e32 v108, v108
	v_rcp_f32_e32 v109, v109
	v_rcp_f32_e32 v111, v111
	v_rcp_f32_e32 v118, v118
	v_rcp_f32_e32 v116, v116
	v_rcp_f32_e32 v117, v117
	v_rcp_f32_e32 v119, v119
	v_pk_mul_f32 v[98:99], v[98:99], v[142:143] op_sel_hi:[1,0]
	v_pk_mul_f32 v[96:97], v[96:97], v[142:143] op_sel_hi:[1,0]
	v_pk_mul_f32 v[98:99], v[102:103], v[98:99]
	v_pk_mul_f32 v[96:97], v[100:101], v[96:97]
	v_pk_mul_f32 v[100:101], v[98:99], v[108:109]
	v_pk_mul_f32 v[98:99], v[96:97], v[110:111]
	v_pk_mul_f32 v[106:107], v[106:107], v[116:117]
	v_pk_mul_f32 v[104:105], v[104:105], v[118:119]
	v_pk_mul_f32 v[94:95], v[94:95], v[140:141] op_sel_hi:[1,0]
	v_cvt_pk_bf16_f32 v96, v104, v105
	v_cvt_pk_bf16_f32 v97, v106, v107
	v_cvt_pk_bf16_f32 v98, v98, v99
	v_cvt_pk_bf16_f32 v99, v100, v101
	v_mad_i64_i32 v[100:101], s[4:5], v190, s35, v[112:113]
	v_lshl_add_u64 v[100:101], v[100:101], 0, v[114:115]
	v_pk_mul_f32 v[92:93], v[92:93], v[140:141] op_sel_hi:[1,0]
	v_pk_mul_f32 v[90:91], v[90:91], v[140:141] op_sel_hi:[1,0]
	v_pk_mul_f32 v[88:89], v[88:89], v[140:141] op_sel_hi:[1,0]
	v_pk_mul_f32 v[86:87], v[86:87], v[140:141] op_sel_hi:[1,0]
	v_pk_mul_f32 v[84:85], v[84:85], v[140:141] op_sel_hi:[1,0]
	global_store_dwordx4 v[100:101], v[96:99], off
	v_pk_mul_f32 v[88:89], v[92:93], v[88:89]
	v_pk_mul_f32 v[90:91], v[94:95], v[90:91]
	v_pk_mul_f32 v[96:97], v[94:95], s[44:45] op_sel_hi:[1,0]
	v_pk_mul_f32 v[98:99], v[92:93], s[44:45] op_sel_hi:[1,0]
	v_pk_mul_f32 v[92:93], v[86:87], s[44:45] op_sel_hi:[1,0]
	v_pk_mul_f32 v[94:95], v[84:85], s[44:45] op_sel_hi:[1,0]
	v_exp_f32_e32 v92, v92
	v_exp_f32_e32 v94, v94
	v_exp_f32_e32 v93, v93
	v_exp_f32_e32 v95, v95
	v_exp_f32_e32 v98, v98
	v_exp_f32_e32 v96, v96
	v_exp_f32_e32 v97, v97
	v_exp_f32_e32 v99, v99
	v_pk_add_f32 v[92:93], v[92:93], 1.0 op_sel_hi:[1,0]
	v_pk_add_f32 v[94:95], v[94:95], 1.0 op_sel_hi:[1,0]
	v_pk_add_f32 v[96:97], v[96:97], 1.0 op_sel_hi:[1,0]
	v_pk_add_f32 v[98:99], v[98:99], 1.0 op_sel_hi:[1,0]
	v_rcp_f32_e32 v94, v94
	v_rcp_f32_e32 v92, v92
	v_rcp_f32_e32 v93, v93
	v_rcp_f32_e32 v95, v95
	v_rcp_f32_e32 v98, v98
	v_rcp_f32_e32 v96, v96
	v_rcp_f32_e32 v97, v97
	v_rcp_f32_e32 v99, v99
	v_pk_mul_f32 v[82:83], v[82:83], v[140:141] op_sel_hi:[1,0]
	v_pk_mul_f32 v[80:81], v[80:81], v[140:141] op_sel_hi:[1,0]
	v_pk_mul_f32 v[82:83], v[86:87], v[82:83]
	v_pk_mul_f32 v[80:81], v[84:85], v[80:81]
	v_pk_mul_f32 v[84:85], v[82:83], v[92:93]
	v_pk_mul_f32 v[82:83], v[80:81], v[94:95]
	v_pk_mul_f32 v[90:91], v[90:91], v[96:97]
	v_pk_mul_f32 v[88:89], v[88:89], v[98:99]
	v_pk_mul_f32 v[78:79], v[78:79], v[136:137] op_sel_hi:[1,0]
	v_cvt_pk_bf16_f32 v80, v88, v89
	v_cvt_pk_bf16_f32 v81, v90, v91
	v_cvt_pk_bf16_f32 v82, v82, v83
	v_cvt_pk_bf16_f32 v83, v84, v85
	v_mad_i64_i32 v[84:85], s[4:5], v188, s35, v[112:113]
	v_lshl_add_u64 v[84:85], v[84:85], 0, v[114:115]
	v_pk_mul_f32 v[76:77], v[76:77], v[136:137] op_sel_hi:[1,0]
	v_pk_mul_f32 v[74:75], v[74:75], v[136:137] op_sel_hi:[1,0]
	v_pk_mul_f32 v[72:73], v[72:73], v[136:137] op_sel_hi:[1,0]
	v_pk_mul_f32 v[70:71], v[70:71], v[136:137] op_sel_hi:[1,0]
	v_pk_mul_f32 v[68:69], v[68:69], v[136:137] op_sel_hi:[1,0]
	global_store_dwordx4 v[84:85], v[80:83], off
	v_pk_mul_f32 v[72:73], v[76:77], v[72:73]
	v_pk_mul_f32 v[74:75], v[78:79], v[74:75]
	v_pk_mul_f32 v[80:81], v[78:79], s[44:45] op_sel_hi:[1,0]
	v_pk_mul_f32 v[82:83], v[76:77], s[44:45] op_sel_hi:[1,0]
	v_pk_mul_f32 v[76:77], v[70:71], s[44:45] op_sel_hi:[1,0]
	v_pk_mul_f32 v[78:79], v[68:69], s[44:45] op_sel_hi:[1,0]
	v_exp_f32_e32 v76, v76
	v_exp_f32_e32 v78, v78
	v_exp_f32_e32 v77, v77
	v_exp_f32_e32 v79, v79
	v_exp_f32_e32 v82, v82
	v_exp_f32_e32 v80, v80
	v_exp_f32_e32 v81, v81
	v_exp_f32_e32 v83, v83
	v_pk_add_f32 v[76:77], v[76:77], 1.0 op_sel_hi:[1,0]
	v_pk_add_f32 v[78:79], v[78:79], 1.0 op_sel_hi:[1,0]
	v_pk_add_f32 v[80:81], v[80:81], 1.0 op_sel_hi:[1,0]
	v_pk_add_f32 v[82:83], v[82:83], 1.0 op_sel_hi:[1,0]
	v_rcp_f32_e32 v78, v78
	v_rcp_f32_e32 v76, v76
	v_rcp_f32_e32 v77, v77
	v_rcp_f32_e32 v79, v79
	v_rcp_f32_e32 v82, v82
	v_rcp_f32_e32 v80, v80
	v_rcp_f32_e32 v81, v81
	v_rcp_f32_e32 v83, v83
	v_pk_mul_f32 v[66:67], v[66:67], v[136:137] op_sel_hi:[1,0]
	v_pk_mul_f32 v[64:65], v[64:65], v[136:137] op_sel_hi:[1,0]
	v_pk_mul_f32 v[66:67], v[70:71], v[66:67]
	v_pk_mul_f32 v[64:65], v[68:69], v[64:65]
	v_pk_mul_f32 v[68:69], v[66:67], v[76:77]
	v_pk_mul_f32 v[66:67], v[64:65], v[78:79]
	v_pk_mul_f32 v[74:75], v[74:75], v[80:81]
	v_pk_mul_f32 v[72:73], v[72:73], v[82:83]
	v_pk_mul_f32 v[62:63], v[62:63], v[134:135] op_sel_hi:[1,0]
	v_cvt_pk_bf16_f32 v64, v72, v73
	v_cvt_pk_bf16_f32 v65, v74, v75
	v_cvt_pk_bf16_f32 v66, v66, v67
	v_cvt_pk_bf16_f32 v67, v68, v69
	v_mad_i64_i32 v[68:69], s[4:5], v174, s35, v[112:113]
	v_lshl_add_u64 v[68:69], v[68:69], 0, v[114:115]
	v_pk_mul_f32 v[60:61], v[60:61], v[134:135] op_sel_hi:[1,0]
	v_pk_mul_f32 v[58:59], v[58:59], v[134:135] op_sel_hi:[1,0]
	v_pk_mul_f32 v[56:57], v[56:57], v[134:135] op_sel_hi:[1,0]
	v_pk_mul_f32 v[54:55], v[54:55], v[134:135] op_sel_hi:[1,0]
	v_pk_mul_f32 v[52:53], v[52:53], v[134:135] op_sel_hi:[1,0]
	global_store_dwordx4 v[68:69], v[64:67], off
	v_pk_mul_f32 v[56:57], v[60:61], v[56:57]
	v_pk_mul_f32 v[58:59], v[62:63], v[58:59]
	v_pk_mul_f32 v[64:65], v[62:63], s[44:45] op_sel_hi:[1,0]
	v_pk_mul_f32 v[66:67], v[60:61], s[44:45] op_sel_hi:[1,0]
	v_pk_mul_f32 v[60:61], v[54:55], s[44:45] op_sel_hi:[1,0]
	v_pk_mul_f32 v[62:63], v[52:53], s[44:45] op_sel_hi:[1,0]
	v_exp_f32_e32 v60, v60
	v_exp_f32_e32 v62, v62
	v_exp_f32_e32 v61, v61
	v_exp_f32_e32 v63, v63
	v_exp_f32_e32 v66, v66
	v_exp_f32_e32 v64, v64
	v_exp_f32_e32 v65, v65
	v_exp_f32_e32 v67, v67
	v_pk_add_f32 v[60:61], v[60:61], 1.0 op_sel_hi:[1,0]
	v_pk_add_f32 v[62:63], v[62:63], 1.0 op_sel_hi:[1,0]
	v_pk_add_f32 v[64:65], v[64:65], 1.0 op_sel_hi:[1,0]
	v_pk_add_f32 v[66:67], v[66:67], 1.0 op_sel_hi:[1,0]
	v_rcp_f32_e32 v62, v62
	v_rcp_f32_e32 v60, v60
	v_rcp_f32_e32 v61, v61
	v_rcp_f32_e32 v63, v63
	v_rcp_f32_e32 v66, v66
	v_rcp_f32_e32 v64, v64
	v_rcp_f32_e32 v65, v65
	v_rcp_f32_e32 v67, v67
	v_pk_mul_f32 v[50:51], v[50:51], v[134:135] op_sel_hi:[1,0]
	v_pk_mul_f32 v[48:49], v[48:49], v[134:135] op_sel_hi:[1,0]
	v_pk_mul_f32 v[50:51], v[54:55], v[50:51]
	v_pk_mul_f32 v[48:49], v[52:53], v[48:49]
	v_mul_f32_e32 v132, 0x45800000, v135
	v_pk_mul_f32 v[52:53], v[50:51], v[60:61]
	v_pk_mul_f32 v[50:51], v[48:49], v[62:63]
	v_cndmask_b32_e64 v132, v135, v132, s[6:7]
	v_pk_mul_f32 v[58:59], v[58:59], v[64:65]
	v_pk_mul_f32 v[56:57], v[56:57], v[66:67]
	v_pk_mul_f32 v[46:47], v[46:47], v[132:133] op_sel_hi:[1,0]
	v_cvt_pk_bf16_f32 v48, v56, v57
	v_cvt_pk_bf16_f32 v49, v58, v59
	v_cvt_pk_bf16_f32 v50, v50, v51
	v_cvt_pk_bf16_f32 v51, v52, v53
	v_mad_i64_i32 v[52:53], s[4:5], v172, s35, v[112:113]
	v_lshl_add_u64 v[52:53], v[52:53], 0, v[114:115]
	v_pk_mul_f32 v[44:45], v[44:45], v[132:133] op_sel_hi:[1,0]
	v_pk_mul_f32 v[42:43], v[42:43], v[132:133] op_sel_hi:[1,0]
	v_pk_mul_f32 v[40:41], v[40:41], v[132:133] op_sel_hi:[1,0]
	v_pk_mul_f32 v[38:39], v[38:39], v[132:133] op_sel_hi:[1,0]
	v_pk_mul_f32 v[36:37], v[36:37], v[132:133] op_sel_hi:[1,0]
	global_store_dwordx4 v[52:53], v[48:51], off
	v_pk_mul_f32 v[40:41], v[44:45], v[40:41]
	v_pk_mul_f32 v[42:43], v[46:47], v[42:43]
	v_pk_mul_f32 v[48:49], v[46:47], s[44:45] op_sel_hi:[1,0]
	v_pk_mul_f32 v[50:51], v[44:45], s[44:45] op_sel_hi:[1,0]
	v_pk_mul_f32 v[44:45], v[38:39], s[44:45] op_sel_hi:[1,0]
	v_pk_mul_f32 v[46:47], v[36:37], s[44:45] op_sel_hi:[1,0]
	v_exp_f32_e32 v44, v44
	v_exp_f32_e32 v46, v46
	v_exp_f32_e32 v45, v45
	v_exp_f32_e32 v47, v47
	v_exp_f32_e32 v50, v50
	v_exp_f32_e32 v48, v48
	v_exp_f32_e32 v49, v49
	v_exp_f32_e32 v51, v51
	v_pk_add_f32 v[44:45], v[44:45], 1.0 op_sel_hi:[1,0]
	v_pk_add_f32 v[46:47], v[46:47], 1.0 op_sel_hi:[1,0]
	v_pk_add_f32 v[48:49], v[48:49], 1.0 op_sel_hi:[1,0]
	v_pk_add_f32 v[50:51], v[50:51], 1.0 op_sel_hi:[1,0]
	v_rcp_f32_e32 v46, v46
	v_rcp_f32_e32 v44, v44
	v_rcp_f32_e32 v45, v45
	v_rcp_f32_e32 v47, v47
	v_rcp_f32_e32 v50, v50
	v_rcp_f32_e32 v48, v48
	v_rcp_f32_e32 v49, v49
	v_rcp_f32_e32 v51, v51
	v_pk_mul_f32 v[34:35], v[34:35], v[132:133] op_sel_hi:[1,0]
	v_pk_mul_f32 v[32:33], v[32:33], v[132:133] op_sel_hi:[1,0]
	v_pk_mul_f32 v[34:35], v[38:39], v[34:35]
	v_pk_mul_f32 v[32:33], v[36:37], v[32:33]
	v_pk_mul_f32 v[36:37], v[34:35], v[44:45]
	v_pk_mul_f32 v[34:35], v[32:33], v[46:47]
	v_pk_mul_f32 v[42:43], v[42:43], v[48:49]
	v_pk_mul_f32 v[40:41], v[40:41], v[50:51]
	v_pk_mul_f32 v[30:31], v[30:31], v[130:131] op_sel_hi:[1,0]
	v_cvt_pk_bf16_f32 v32, v40, v41
	v_cvt_pk_bf16_f32 v33, v42, v43
	v_cvt_pk_bf16_f32 v34, v34, v35
	v_cvt_pk_bf16_f32 v35, v36, v37
	v_mad_i64_i32 v[36:37], s[4:5], v170, s35, v[112:113]
	v_lshl_add_u64 v[36:37], v[36:37], 0, v[114:115]
	v_pk_mul_f32 v[28:29], v[28:29], v[130:131] op_sel_hi:[1,0]
	v_pk_mul_f32 v[26:27], v[26:27], v[130:131] op_sel_hi:[1,0]
	v_pk_mul_f32 v[24:25], v[24:25], v[130:131] op_sel_hi:[1,0]
	v_pk_mul_f32 v[22:23], v[22:23], v[130:131] op_sel_hi:[1,0]
	v_pk_mul_f32 v[20:21], v[20:21], v[130:131] op_sel_hi:[1,0]
	global_store_dwordx4 v[36:37], v[32:35], off
	v_pk_mul_f32 v[24:25], v[28:29], v[24:25]
	v_pk_mul_f32 v[26:27], v[30:31], v[26:27]
	v_pk_mul_f32 v[32:33], v[30:31], s[44:45] op_sel_hi:[1,0]
	v_pk_mul_f32 v[34:35], v[28:29], s[44:45] op_sel_hi:[1,0]
	v_pk_mul_f32 v[28:29], v[22:23], s[44:45] op_sel_hi:[1,0]
	v_pk_mul_f32 v[30:31], v[20:21], s[44:45] op_sel_hi:[1,0]
	v_exp_f32_e32 v28, v28
	v_exp_f32_e32 v30, v30
	v_exp_f32_e32 v29, v29
	v_exp_f32_e32 v31, v31
	v_exp_f32_e32 v34, v34
	v_exp_f32_e32 v32, v32
	v_exp_f32_e32 v33, v33
	v_exp_f32_e32 v35, v35
	v_pk_add_f32 v[28:29], v[28:29], 1.0 op_sel_hi:[1,0]
	v_pk_add_f32 v[30:31], v[30:31], 1.0 op_sel_hi:[1,0]
	v_pk_add_f32 v[32:33], v[32:33], 1.0 op_sel_hi:[1,0]
	v_pk_add_f32 v[34:35], v[34:35], 1.0 op_sel_hi:[1,0]
	v_rcp_f32_e32 v30, v30
	v_rcp_f32_e32 v28, v28
	v_rcp_f32_e32 v29, v29
	v_rcp_f32_e32 v31, v31
	v_rcp_f32_e32 v34, v34
	v_rcp_f32_e32 v32, v32
	v_rcp_f32_e32 v33, v33
	v_rcp_f32_e32 v35, v35
	v_pk_mul_f32 v[18:19], v[18:19], v[130:131] op_sel_hi:[1,0]
	v_pk_mul_f32 v[16:17], v[16:17], v[130:131] op_sel_hi:[1,0]
	v_pk_mul_f32 v[18:19], v[22:23], v[18:19]
	v_pk_mul_f32 v[16:17], v[20:21], v[16:17]
	v_pk_mul_f32 v[20:21], v[18:19], v[28:29]
	v_pk_mul_f32 v[18:19], v[16:17], v[30:31]
	v_pk_mul_f32 v[26:27], v[26:27], v[32:33]
	v_pk_mul_f32 v[24:25], v[24:25], v[34:35]
	v_pk_mul_f32 v[14:15], v[14:15], v[128:129] op_sel_hi:[1,0]
	v_cvt_pk_bf16_f32 v16, v24, v25
	v_cvt_pk_bf16_f32 v17, v26, v27
	v_cvt_pk_bf16_f32 v18, v18, v19
	v_cvt_pk_bf16_f32 v19, v20, v21
	v_mad_i64_i32 v[20:21], s[4:5], v168, s35, v[112:113]
	v_lshl_add_u64 v[20:21], v[20:21], 0, v[114:115]
	v_pk_mul_f32 v[12:13], v[12:13], v[128:129] op_sel_hi:[1,0]
	v_pk_mul_f32 v[10:11], v[10:11], v[128:129] op_sel_hi:[1,0]
	v_pk_mul_f32 v[8:9], v[8:9], v[128:129] op_sel_hi:[1,0]
	v_pk_mul_f32 v[6:7], v[6:7], v[128:129] op_sel_hi:[1,0]
	v_pk_mul_f32 v[4:5], v[4:5], v[128:129] op_sel_hi:[1,0]
	global_store_dwordx4 v[20:21], v[16:19], off
	v_pk_mul_f32 v[8:9], v[12:13], v[8:9]
	v_pk_mul_f32 v[10:11], v[14:15], v[10:11]
	v_pk_mul_f32 v[16:17], v[14:15], s[44:45] op_sel_hi:[1,0]
	v_pk_mul_f32 v[18:19], v[12:13], s[44:45] op_sel_hi:[1,0]
	v_pk_mul_f32 v[12:13], v[6:7], s[44:45] op_sel_hi:[1,0]
	v_pk_mul_f32 v[14:15], v[4:5], s[44:45] op_sel_hi:[1,0]
	v_exp_f32_e32 v12, v12
	v_exp_f32_e32 v14, v14
	v_exp_f32_e32 v13, v13
	v_exp_f32_e32 v15, v15
	v_exp_f32_e32 v18, v18
	v_exp_f32_e32 v16, v16
	v_exp_f32_e32 v17, v17
	v_exp_f32_e32 v19, v19
	v_pk_add_f32 v[12:13], v[12:13], 1.0 op_sel_hi:[1,0]
	v_pk_add_f32 v[14:15], v[14:15], 1.0 op_sel_hi:[1,0]
	v_pk_add_f32 v[16:17], v[16:17], 1.0 op_sel_hi:[1,0]
	v_pk_add_f32 v[18:19], v[18:19], 1.0 op_sel_hi:[1,0]
	v_rcp_f32_e32 v14, v14
	v_rcp_f32_e32 v12, v12
	v_rcp_f32_e32 v13, v13
	v_rcp_f32_e32 v15, v15
	v_rcp_f32_e32 v18, v18
	v_rcp_f32_e32 v16, v16
	v_rcp_f32_e32 v17, v17
	v_rcp_f32_e32 v19, v19
	v_pk_mul_f32 v[2:3], v[2:3], v[128:129] op_sel_hi:[1,0]
	v_pk_mul_f32 v[0:1], v[0:1], v[128:129] op_sel_hi:[1,0]
	v_pk_mul_f32 v[2:3], v[6:7], v[2:3]
	v_pk_mul_f32 v[0:1], v[4:5], v[0:1]
	v_pk_mul_f32 v[4:5], v[2:3], v[12:13]
	v_pk_mul_f32 v[2:3], v[0:1], v[14:15]
	v_pk_mul_f32 v[10:11], v[10:11], v[16:17]
	v_pk_mul_f32 v[8:9], v[8:9], v[18:19]
	s_andn2_b64 vcc, exec, s[2:3]
	v_cvt_pk_bf16_f32 v0, v8, v9
	v_cvt_pk_bf16_f32 v1, v10, v11
	v_cvt_pk_bf16_f32 v2, v2, v3
	v_cvt_pk_bf16_f32 v3, v4, v5
	v_mad_i64_i32 v[4:5], s[4:5], v166, s35, v[112:113]
	v_lshl_add_u64 v[4:5], v[4:5], 0, v[114:115]
	s_mov_b32 s4, s16
	s_mov_b32 s5, s12
	s_mov_b64 s[6:7], s[18:19]
	global_store_dwordx4 v[4:5], v[0:3], off
	s_cbranch_vccnz .LBB0_1429
	s_waitcnt vmcnt(0)
	s_cmpk_gt_u32 s24, 0xff
	s_cbranch_scc1 .LBB0_1440
	s_barrier
